# bh2 + in-proj dt tile epilogue: loop-invariant dt-bias loads hoisted (2 dwordx4 per row half instead of 64 serialized dword loads with vmcnt(0))
# baseline (speedup 1.0000x reference)
; __device__ __forceinline__ float softplusf_(float x) { const float e = __expf(x); const float sm = e * (1.f - e * (0.5f - e * 0.33333334f)); return x > 20.f ? x : (e < 0.01f ? sm : __logf(1.f + e)); }
;     __device__ __forceinline__ void operator()(AccT acc, const Unit& u, int wr, int wc, int fr, int fq) const {
;     ...
;             const float rs = rs8[ai * 4 + m];
;             const int sq = seq_of_row(row); const bool isS = row >= NPROMPT; const int t = isS ? ((row - NPROMPT) & 7) : (row & (SEQ - 1));
;             if (!uni) { const float* sw = SHW + (size_t)sq * NZT + col0;
; #pragma unroll
;                 for (int bj = 0; bj < 2; ++bj) { sh[bj][0] = *(const f32x4*)(sw + bj * HALF); sh[bj][1] = *(const f32x4*)(sw + bj * HALF + 4); }
;                 asm volatile("" :: "v"(sh[0][0]), "v"(sh[0][1]), "v"(sh[1][0]), "v"(sh[1][1])); }
; #pragma unroll
;             for (int bj = 0; bj < 2; ++bj) { const int c = col0 + bj * HALF;
;                 const f32x4 v0 = acc[ai][bj][m][0] * rs + sh[bj][0], v1 = acc[ai][bj][m][1] * rs + sh[bj][1];
;                 if (u.pn < 48) {
;     ...
;                 } else if (bj == 0 && wc == 0 && fq < 2) {
;                     float* d = DT + (size_t)row * 16 + 8 * fq; const float* bb = dtb + 8 * fq;
;                     *(f32x4*)d = (f32x4){softplusf_(v0[0] + bb[0]), softplusf_(v0[1] + bb[1]), softplusf_(v0[2] + bb[2]), softplusf_(v0[3] + bb[3])};
.LBB0_664:
	s_waitcnt lgkmcnt(7)
	v_add_f32_e32 v146, v146, v147
	s_add_i32 s8, s18, -6
	s_sub_i32 s9, s18, 22
	v_fmamk_f32 v146, v146, 0x3a800000, v193
	s_cmp_lt_u32 s9, 10
	v_rsq_f32_e32 v180, v146
	s_cselect_b32 s9, 2, 0
	s_cmp_gt_u32 s8, 11
	s_cselect_b32 s47, s9, 1
	s_cmp_lt_i32 s18, 48
	s_cselect_b64 s[54:55], -1, 0
	s_cmp_gt_i32 s18, 47
	s_cselect_b64 s[20:21], -1, 0
	v_cmp_gt_i32_e64 s[10:11], s81, v176
	v_cmp_lt_i32_e64 s[12:13], s91, v176
	v_ashrrev_i32_e32 v177, 31, v176
	s_mov_b64 s[8:9], -1
	v_pk_fma_f32 v[144:145], v[144:145], v[180:181], v[40:41] op_sel_hi:[1,0,1]
	v_pk_fma_f32 v[142:143], v[142:143], v[180:181], v[38:39] op_sel_hi:[1,0,1]
	v_pk_fma_f32 v[140:141], v[140:141], v[180:181], v[36:37] op_sel_hi:[1,0,1]
	v_pk_fma_f32 v[138:139], v[138:139], v[180:181], v[34:35] op_sel_hi:[1,0,1]
	s_and_b64 vcc, exec, s[20:21]
	s_cbranch_vccz .LBB0_700
	s_and_saveexec_b64 s[14:15], s[38:39]
	s_cbranch_execz .LBB0_699
	global_load_dwordx4 v[244:247], v[166:167], off
	global_load_dwordx4 v[248:251], v[166:167], off offset:16
	s_waitcnt vmcnt(0)
	v_mov_b32_e32 v146, v244
	v_add_f32_e32 v146, v142, v146
	v_cmp_nlt_f32_e32 vcc, s92, v146
	s_and_saveexec_b64 s[16:17], vcc
	s_cbranch_execz .LBB0_670
	v_mul_f32_e32 v146, 0x3fb8aa3b, v146
	v_exp_f32_e32 v147, v146
	s_nop 0
	v_fma_f32 v146, v147, s93, 0.5
	v_fma_f32 v146, -v147, v146, 1.0
	v_mul_f32_e32 v146, v147, v146
	v_cmp_ngt_f32_e32 vcc, s94, v147
	s_and_saveexec_b64 s[58:59], vcc
	s_cbranch_execz .LBB0_669
	v_add_f32_e32 v146, 1.0, v147
	v_cmp_gt_f32_e32 vcc, s95, v146
	s_nop 1
	v_cndmask_b32_e64 v147, 0, 32, vcc
	v_ldexp_f32 v146, v146, v147
	v_log_f32_e32 v146, v146
	s_nop 0
	v_mul_f32_e32 v147, 0x3f317217, v146
	v_fma_f32 v147, v146, s96, -v147
	v_fmac_f32_e32 v147, 0x3377d1cf, v146
	v_fmac_f32_e32 v147, 0x3f317217, v146
	v_cmp_lt_f32_e64 s[8:9], |v146|, s97
	s_nop 1
	v_cndmask_b32_e64 v146, v146, v147, s[8:9]
	v_cndmask_b32_e32 v147, 0, v194, vcc
	v_sub_f32_e32 v146, v146, v147

; __device__ __forceinline__ float softplusf_(float x) { const float e = __expf(x); const float sm = e * (1.f - e * (0.5f - e * 0.33333334f)); return x > 20.f ? x : (e < 0.01f ? sm : __logf(1.f + e)); }
;     __device__ __forceinline__ void operator()(AccT acc, const Unit& u, int wr, int wc, int fr, int fq) const {
;     ...
;                     *(f32x4*)d = (f32x4){softplusf_(v0[0] + bb[0]), softplusf_(v0[1] + bb[1]), softplusf_(v0[2] + bb[2]), softplusf_(v0[3] + bb[3])};
.LBB0_670:
	s_or_b64 exec, exec, s[16:17]
	s_nop 1
	v_mov_b32_e32 v147, v245
	v_add_f32_e32 v147, v143, v147
	v_cmp_nlt_f32_e32 vcc, s92, v147
	s_and_saveexec_b64 s[16:17], vcc
	s_cbranch_execz .LBB0_674
	v_mul_f32_e32 v147, 0x3fb8aa3b, v147
	v_exp_f32_e32 v148, v147
	s_nop 0
	v_fma_f32 v147, v148, s93, 0.5
	v_fma_f32 v147, -v148, v147, 1.0
	v_mul_f32_e32 v147, v148, v147
	v_cmp_ngt_f32_e32 vcc, s94, v148
	s_and_saveexec_b64 s[58:59], vcc
	s_cbranch_execz .LBB0_673
	v_add_f32_e32 v147, 1.0, v148
	v_cmp_gt_f32_e32 vcc, s95, v147
	s_nop 1
	v_cndmask_b32_e64 v148, 0, 32, vcc
	v_ldexp_f32 v147, v147, v148
	v_log_f32_e32 v147, v147
	s_nop 0
	v_mul_f32_e32 v148, 0x3f317217, v147
	v_fma_f32 v148, v147, s96, -v148
	v_fmac_f32_e32 v148, 0x3377d1cf, v147
	v_fmac_f32_e32 v148, 0x3f317217, v147
	v_cmp_lt_f32_e64 s[8:9], |v147|, s97
	s_nop 1
	v_cndmask_b32_e64 v147, v147, v148, s[8:9]
	v_cndmask_b32_e32 v148, 0, v194, vcc
	v_sub_f32_e32 v147, v147, v148

; __device__ __forceinline__ float softplusf_(float x) { const float e = __expf(x); const float sm = e * (1.f - e * (0.5f - e * 0.33333334f)); return x > 20.f ? x : (e < 0.01f ? sm : __logf(1.f + e)); }
;     __device__ __forceinline__ void operator()(AccT acc, const Unit& u, int wr, int wc, int fr, int fq) const {
;     ...
;                     *(f32x4*)d = (f32x4){softplusf_(v0[0] + bb[0]), softplusf_(v0[1] + bb[1]), softplusf_(v0[2] + bb[2]), softplusf_(v0[3] + bb[3])};
.LBB0_674:
	s_or_b64 exec, exec, s[16:17]
	s_nop 1
	v_mov_b32_e32 v148, v246
	v_add_f32_e32 v148, v144, v148
	v_cmp_nlt_f32_e32 vcc, s92, v148
	s_and_saveexec_b64 s[16:17], vcc
	s_cbranch_execz .LBB0_678
	v_mul_f32_e32 v148, 0x3fb8aa3b, v148
	v_exp_f32_e32 v149, v148
	s_nop 0
	v_fma_f32 v148, v149, s93, 0.5
	v_fma_f32 v148, -v149, v148, 1.0
	v_mul_f32_e32 v148, v149, v148
	v_cmp_ngt_f32_e32 vcc, s94, v149
	s_and_saveexec_b64 s[58:59], vcc
	s_cbranch_execz .LBB0_677
	v_add_f32_e32 v148, 1.0, v149
	v_cmp_gt_f32_e32 vcc, s95, v148
	s_nop 1
	v_cndmask_b32_e64 v149, 0, 32, vcc
	v_ldexp_f32 v148, v148, v149
	v_log_f32_e32 v148, v148
	s_nop 0
	v_mul_f32_e32 v149, 0x3f317217, v148
	v_fma_f32 v149, v148, s96, -v149
	v_fmac_f32_e32 v149, 0x3377d1cf, v148
	v_fmac_f32_e32 v149, 0x3f317217, v148
	v_cmp_lt_f32_e64 s[8:9], |v148|, s97
	s_nop 1
	v_cndmask_b32_e64 v148, v148, v149, s[8:9]
	v_cndmask_b32_e32 v149, 0, v194, vcc
	v_sub_f32_e32 v148, v148, v149

; __device__ __forceinline__ float softplusf_(float x) { const float e = __expf(x); const float sm = e * (1.f - e * (0.5f - e * 0.33333334f)); return x > 20.f ? x : (e < 0.01f ? sm : __logf(1.f + e)); }
;     __device__ __forceinline__ void operator()(AccT acc, const Unit& u, int wr, int wc, int fr, int fq) const {
;     ...
;                     *(f32x4*)d = (f32x4){softplusf_(v0[0] + bb[0]), softplusf_(v0[1] + bb[1]), softplusf_(v0[2] + bb[2]), softplusf_(v0[3] + bb[3])};
.LBB0_678:
	s_or_b64 exec, exec, s[16:17]
	s_nop 1
	v_mov_b32_e32 v149, v247
	v_add_f32_e32 v149, v145, v149
	v_cmp_nlt_f32_e32 vcc, s92, v149
	s_and_saveexec_b64 s[16:17], vcc
	s_cbranch_execz .LBB0_682
	v_mul_f32_e32 v149, 0x3fb8aa3b, v149
	v_exp_f32_e32 v158, v149
	s_nop 0
	v_fma_f32 v149, v158, s93, 0.5
	v_fma_f32 v149, -v158, v149, 1.0
	v_mul_f32_e32 v149, v158, v149
	v_cmp_ngt_f32_e32 vcc, s94, v158
	s_and_saveexec_b64 s[58:59], vcc
	s_cbranch_execz .LBB0_681
	v_add_f32_e32 v149, 1.0, v158
	v_cmp_gt_f32_e32 vcc, s95, v149
	s_nop 1
	v_cndmask_b32_e64 v158, 0, 32, vcc
	v_ldexp_f32 v149, v149, v158
	v_log_f32_e32 v149, v149
	s_nop 0
	v_mul_f32_e32 v158, 0x3f317217, v149
	v_fma_f32 v158, v149, s96, -v158
	v_fmac_f32_e32 v158, 0x3377d1cf, v149
	v_fmac_f32_e32 v158, 0x3f317217, v149
	v_cmp_lt_f32_e64 s[8:9], |v149|, s97
	s_nop 1
	v_cndmask_b32_e64 v149, v149, v158, s[8:9]
	v_cndmask_b32_e32 v158, 0, v194, vcc
	v_sub_f32_e32 v149, v149, v158

; __device__ __forceinline__ float softplusf_(float x) { const float e = __expf(x); const float sm = e * (1.f - e * (0.5f - e * 0.33333334f)); return x > 20.f ? x : (e < 0.01f ? sm : __logf(1.f + e)); }
;     __device__ __forceinline__ void operator()(AccT acc, const Unit& u, int wr, int wc, int fr, int fq) const {
;     ...
;                     *(f32x4*)d = (f32x4){softplusf_(v0[0] + bb[0]), softplusf_(v0[1] + bb[1]), softplusf_(v0[2] + bb[2]), softplusf_(v0[3] + bb[3])};
;                     *(f32x4*)(d + 4) = (f32x4){softplusf_(v1[0] + bb[4]), softplusf_(v1[1] + bb[5]), softplusf_(v1[2] + bb[6]), softplusf_(v1[3] + bb[7])};
.LBB0_682:
	s_or_b64 exec, exec, s[16:17]
	v_lshlrev_b64 v[182:183], 6, v[176:177]
	v_lshl_add_u64 v[182:183], v[162:163], 0, v[182:183]
	global_store_dwordx4 v[182:183], v[146:149], off
	s_nop 1
	v_mov_b32_e32 v146, v248
	v_add_f32_e32 v146, v138, v146
	v_cmp_nlt_f32_e32 vcc, s92, v146
	s_and_saveexec_b64 s[16:17], vcc
	s_cbranch_execz .LBB0_686
	v_mul_f32_e32 v146, 0x3fb8aa3b, v146
	v_exp_f32_e32 v147, v146
	s_nop 0
	v_fma_f32 v146, v147, s93, 0.5
	v_fma_f32 v146, -v147, v146, 1.0
	v_mul_f32_e32 v146, v147, v146
	v_cmp_ngt_f32_e32 vcc, s94, v147
	s_and_saveexec_b64 s[58:59], vcc
	s_cbranch_execz .LBB0_685
	v_add_f32_e32 v146, 1.0, v147
	v_cmp_gt_f32_e32 vcc, s95, v146
	s_nop 1
	v_cndmask_b32_e64 v147, 0, 32, vcc
	v_ldexp_f32 v146, v146, v147
	v_log_f32_e32 v146, v146
	s_nop 0
	v_mul_f32_e32 v147, 0x3f317217, v146
	v_fma_f32 v147, v146, s96, -v147
	v_fmac_f32_e32 v147, 0x3377d1cf, v146
	v_fmac_f32_e32 v147, 0x3f317217, v146
	v_cmp_lt_f32_e64 s[8:9], |v146|, s97
	s_nop 1
	v_cndmask_b32_e64 v146, v146, v147, s[8:9]
	v_cndmask_b32_e32 v147, 0, v194, vcc
	v_sub_f32_e32 v146, v146, v147

; __device__ __forceinline__ float softplusf_(float x) { const float e = __expf(x); const float sm = e * (1.f - e * (0.5f - e * 0.33333334f)); return x > 20.f ? x : (e < 0.01f ? sm : __logf(1.f + e)); }
;     __device__ __forceinline__ void operator()(AccT acc, const Unit& u, int wr, int wc, int fr, int fq) const {
;     ...
;                     *(f32x4*)(d + 4) = (f32x4){softplusf_(v1[0] + bb[4]), softplusf_(v1[1] + bb[5]), softplusf_(v1[2] + bb[6]), softplusf_(v1[3] + bb[7])};
.LBB0_686:
	s_or_b64 exec, exec, s[16:17]
	s_nop 1
	v_mov_b32_e32 v147, v249
	v_add_f32_e32 v147, v139, v147
	v_cmp_nlt_f32_e32 vcc, s92, v147
	s_and_saveexec_b64 s[16:17], vcc
	s_cbranch_execz .LBB0_690
	v_mul_f32_e32 v147, 0x3fb8aa3b, v147
	v_exp_f32_e32 v148, v147
	s_nop 0
	v_fma_f32 v147, v148, s93, 0.5
	v_fma_f32 v147, -v148, v147, 1.0
	v_mul_f32_e32 v147, v148, v147
	v_cmp_ngt_f32_e32 vcc, s94, v148
	s_and_saveexec_b64 s[58:59], vcc
	s_cbranch_execz .LBB0_689
	v_add_f32_e32 v147, 1.0, v148
	v_cmp_gt_f32_e32 vcc, s95, v147
	s_nop 1
	v_cndmask_b32_e64 v148, 0, 32, vcc
	v_ldexp_f32 v147, v147, v148
	v_log_f32_e32 v147, v147
	s_nop 0
	v_mul_f32_e32 v148, 0x3f317217, v147
	v_fma_f32 v148, v147, s96, -v148
	v_fmac_f32_e32 v148, 0x3377d1cf, v147
	v_fmac_f32_e32 v148, 0x3f317217, v147
	v_cmp_lt_f32_e64 s[8:9], |v147|, s97
	s_nop 1
	v_cndmask_b32_e64 v147, v147, v148, s[8:9]
	v_cndmask_b32_e32 v148, 0, v194, vcc
	v_sub_f32_e32 v147, v147, v148

; __device__ __forceinline__ float softplusf_(float x) { const float e = __expf(x); const float sm = e * (1.f - e * (0.5f - e * 0.33333334f)); return x > 20.f ? x : (e < 0.01f ? sm : __logf(1.f + e)); }
;     __device__ __forceinline__ void operator()(AccT acc, const Unit& u, int wr, int wc, int fr, int fq) const {
;     ...
;                     *(f32x4*)(d + 4) = (f32x4){softplusf_(v1[0] + bb[4]), softplusf_(v1[1] + bb[5]), softplusf_(v1[2] + bb[6]), softplusf_(v1[3] + bb[7])};
.LBB0_690:
	s_or_b64 exec, exec, s[16:17]
	s_nop 1
	v_mov_b32_e32 v148, v250
	v_add_f32_e32 v148, v140, v148
	v_cmp_nlt_f32_e32 vcc, s92, v148
	s_and_saveexec_b64 s[16:17], vcc
	s_cbranch_execz .LBB0_694
	v_mul_f32_e32 v148, 0x3fb8aa3b, v148
	v_exp_f32_e32 v149, v148
	s_nop 0
	v_fma_f32 v148, v149, s93, 0.5
	v_fma_f32 v148, -v149, v148, 1.0
	v_mul_f32_e32 v148, v149, v148
	v_cmp_ngt_f32_e32 vcc, s94, v149
	s_and_saveexec_b64 s[58:59], vcc
	s_cbranch_execz .LBB0_693
	v_add_f32_e32 v148, 1.0, v149
	v_cmp_gt_f32_e32 vcc, s95, v148
	s_nop 1
	v_cndmask_b32_e64 v149, 0, 32, vcc
	v_ldexp_f32 v148, v148, v149
	v_log_f32_e32 v148, v148
	s_nop 0
	v_mul_f32_e32 v149, 0x3f317217, v148
	v_fma_f32 v149, v148, s96, -v149
	v_fmac_f32_e32 v149, 0x3377d1cf, v148
	v_fmac_f32_e32 v149, 0x3f317217, v148
	v_cmp_lt_f32_e64 s[8:9], |v148|, s97
	s_nop 1
	v_cndmask_b32_e64 v148, v148, v149, s[8:9]
	v_cndmask_b32_e32 v149, 0, v194, vcc
	v_sub_f32_e32 v148, v148, v149

; __device__ __forceinline__ float softplusf_(float x) { const float e = __expf(x); const float sm = e * (1.f - e * (0.5f - e * 0.33333334f)); return x > 20.f ? x : (e < 0.01f ? sm : __logf(1.f + e)); }
;     __device__ __forceinline__ void operator()(AccT acc, const Unit& u, int wr, int wc, int fr, int fq) const {
;     ...
;                     *(f32x4*)(d + 4) = (f32x4){softplusf_(v1[0] + bb[4]), softplusf_(v1[1] + bb[5]), softplusf_(v1[2] + bb[6]), softplusf_(v1[3] + bb[7])};
.LBB0_694:
	s_or_b64 exec, exec, s[16:17]
	s_nop 1
	v_mov_b32_e32 v149, v251
	v_add_f32_e32 v149, v141, v149
	v_cmp_nlt_f32_e32 vcc, s92, v149
	s_and_saveexec_b64 s[16:17], vcc
	s_cbranch_execz .LBB0_698
	v_mul_f32_e32 v149, 0x3fb8aa3b, v149
	v_exp_f32_e32 v158, v149
	s_nop 0
	v_fma_f32 v149, v158, s93, 0.5
	v_fma_f32 v149, -v158, v149, 1.0
	v_mul_f32_e32 v149, v158, v149
	v_cmp_ngt_f32_e32 vcc, s94, v158
	s_and_saveexec_b64 s[58:59], vcc
	s_cbranch_execz .LBB0_697
	v_add_f32_e32 v149, 1.0, v158
	v_cmp_gt_f32_e32 vcc, s95, v149
	s_nop 1
	v_cndmask_b32_e64 v158, 0, 32, vcc
	v_ldexp_f32 v149, v149, v158
	v_log_f32_e32 v149, v149
	s_nop 0
	v_mul_f32_e32 v158, 0x3f317217, v149
	v_fma_f32 v158, v149, s96, -v158
	v_fmac_f32_e32 v158, 0x3377d1cf, v149
	v_fmac_f32_e32 v158, 0x3f317217, v149
	v_cmp_lt_f32_e64 s[8:9], |v149|, s97
	s_nop 1
	v_cndmask_b32_e64 v149, v149, v158, s[8:9]
	v_cndmask_b32_e32 v158, 0, v194, vcc
	v_sub_f32_e32 v149, v149, v158

; __device__ __forceinline__ float softplusf_(float x) { const float e = __expf(x); const float sm = e * (1.f - e * (0.5f - e * 0.33333334f)); return x > 20.f ? x : (e < 0.01f ? sm : __logf(1.f + e)); }
;     __device__ __forceinline__ void operator()(AccT acc, const Unit& u, int wr, int wc, int fr, int fq) const {
;     ...
;             const float rs = rs8[ai * 4 + m];
;             const int sq = seq_of_row(row); const bool isS = row >= NPROMPT; const int t = isS ? ((row - NPROMPT) & 7) : (row & (SEQ - 1));
;             if (!uni) { const float* sw = SHW + (size_t)sq * NZT + col0;
; #pragma unroll
;                 for (int bj = 0; bj < 2; ++bj) { sh[bj][0] = *(const f32x4*)(sw + bj * HALF); sh[bj][1] = *(const f32x4*)(sw + bj * HALF + 4); }
;                 asm volatile("" :: "v"(sh[0][0]), "v"(sh[0][1]), "v"(sh[1][0]), "v"(sh[1][1])); }
; #pragma unroll
;             for (int bj = 0; bj < 2; ++bj) { const int c = col0 + bj * HALF;
;                 const f32x4 v0 = acc[ai][bj][m][0] * rs + sh[bj][0], v1 = acc[ai][bj][m][1] * rs + sh[bj][1];
;                 if (u.pn < 48) {
;     ...
;                 } else if (bj == 0 && wc == 0 && fq < 2) {
;                     float* d = DT + (size_t)row * 16 + 8 * fq; const float* bb = dtb + 8 * fq;
;                     *(f32x4*)d = (f32x4){softplusf_(v0[0] + bb[0]), softplusf_(v0[1] + bb[1]), softplusf_(v0[2] + bb[2]), softplusf_(v0[3] + bb[3])};
.LBB0_728:
	s_waitcnt lgkmcnt(6)
	v_add_f32_e32 v130, v224, v225
	v_fmamk_f32 v130, v130, 0x3a800000, v193
	v_rsq_f32_e32 v136, v130
	v_cndmask_b32_e64 v130, 0, 1, s[20:21]
	v_cmp_gt_i32_e64 s[12:13], s81, v140
	v_cmp_lt_i32_e64 s[14:15], s91, v140
	v_ashrrev_i32_e32 v141, 31, v140
	s_mov_b64 s[16:17], -1
	v_pk_fma_f32 v[128:129], v[128:129], v[136:137], v[40:41] op_sel_hi:[1,0,1]
	v_pk_fma_f32 v[126:127], v[126:127], v[136:137], v[38:39] op_sel_hi:[1,0,1]
	v_pk_fma_f32 v[124:125], v[124:125], v[136:137], v[36:37] op_sel_hi:[1,0,1]
	v_cmp_ne_u32_e64 s[10:11], 1, v130
	s_andn2_b64 vcc, exec, s[20:21]
	v_pk_fma_f32 v[122:123], v[122:123], v[136:137], v[34:35] op_sel_hi:[1,0,1]
	s_cbranch_vccnz .LBB0_764
	s_and_saveexec_b64 s[20:21], s[38:39]
	s_cbranch_execz .LBB0_763
	s_nop 1
	v_mov_b32_e32 v130, v244
	v_add_f32_e32 v130, v126, v130
	v_cmp_nlt_f32_e32 vcc, s92, v130
	s_and_saveexec_b64 s[54:55], vcc
	s_cbranch_execz .LBB0_734
	v_mul_f32_e32 v130, 0x3fb8aa3b, v130
	v_exp_f32_e32 v131, v130
	s_nop 0
	v_fma_f32 v130, v131, s93, 0.5
	v_fma_f32 v130, -v131, v130, 1.0
	v_mul_f32_e32 v130, v131, v130
	v_cmp_ngt_f32_e32 vcc, s94, v131
	s_and_saveexec_b64 s[58:59], vcc
	s_cbranch_execz .LBB0_733
	v_add_f32_e32 v130, 1.0, v131
	v_cmp_gt_f32_e32 vcc, s95, v130
	s_nop 1
	v_cndmask_b32_e64 v131, 0, 32, vcc
	v_ldexp_f32 v130, v130, v131
	v_log_f32_e32 v130, v130
	s_nop 0
	v_mul_f32_e32 v131, 0x3f317217, v130
	v_fma_f32 v131, v130, s96, -v131
	v_fmac_f32_e32 v131, 0x3377d1cf, v130
	v_fmac_f32_e32 v131, 0x3f317217, v130
	v_cmp_lt_f32_e64 s[16:17], |v130|, s97
	s_nop 1
	v_cndmask_b32_e64 v130, v130, v131, s[16:17]
	v_cndmask_b32_e32 v131, 0, v194, vcc
	v_sub_f32_e32 v130, v130, v131

; __device__ __forceinline__ float softplusf_(float x) { const float e = __expf(x); const float sm = e * (1.f - e * (0.5f - e * 0.33333334f)); return x > 20.f ? x : (e < 0.01f ? sm : __logf(1.f + e)); }
;     __device__ __forceinline__ void operator()(AccT acc, const Unit& u, int wr, int wc, int fr, int fq) const {
;     ...
;                     *(f32x4*)d = (f32x4){softplusf_(v0[0] + bb[0]), softplusf_(v0[1] + bb[1]), softplusf_(v0[2] + bb[2]), softplusf_(v0[3] + bb[3])};
.LBB0_734:
	s_or_b64 exec, exec, s[54:55]
	s_nop 1
	v_mov_b32_e32 v131, v245
	v_add_f32_e32 v131, v127, v131
	v_cmp_nlt_f32_e32 vcc, s92, v131
	s_and_saveexec_b64 s[54:55], vcc
	s_cbranch_execz .LBB0_738
	v_mul_f32_e32 v131, 0x3fb8aa3b, v131
	v_exp_f32_e32 v132, v131
	s_nop 0
	v_fma_f32 v131, v132, s93, 0.5
	v_fma_f32 v131, -v132, v131, 1.0
	v_mul_f32_e32 v131, v132, v131
	v_cmp_ngt_f32_e32 vcc, s94, v132
	s_and_saveexec_b64 s[58:59], vcc
	s_cbranch_execz .LBB0_737
	v_add_f32_e32 v131, 1.0, v132
	v_cmp_gt_f32_e32 vcc, s95, v131
	s_nop 1
	v_cndmask_b32_e64 v132, 0, 32, vcc
	v_ldexp_f32 v131, v131, v132
	v_log_f32_e32 v131, v131
	s_nop 0
	v_mul_f32_e32 v132, 0x3f317217, v131
	v_fma_f32 v132, v131, s96, -v132
	v_fmac_f32_e32 v132, 0x3377d1cf, v131
	v_fmac_f32_e32 v132, 0x3f317217, v131
	v_cmp_lt_f32_e64 s[16:17], |v131|, s97
	s_nop 1
	v_cndmask_b32_e64 v131, v131, v132, s[16:17]
	v_cndmask_b32_e32 v132, 0, v194, vcc
	v_sub_f32_e32 v131, v131, v132

; __device__ __forceinline__ float softplusf_(float x) { const float e = __expf(x); const float sm = e * (1.f - e * (0.5f - e * 0.33333334f)); return x > 20.f ? x : (e < 0.01f ? sm : __logf(1.f + e)); }
;     __device__ __forceinline__ void operator()(AccT acc, const Unit& u, int wr, int wc, int fr, int fq) const {
;     ...
;                     *(f32x4*)d = (f32x4){softplusf_(v0[0] + bb[0]), softplusf_(v0[1] + bb[1]), softplusf_(v0[2] + bb[2]), softplusf_(v0[3] + bb[3])};
.LBB0_738:
	s_or_b64 exec, exec, s[54:55]
	s_nop 1
	v_mov_b32_e32 v132, v246
	v_add_f32_e32 v132, v128, v132
	v_cmp_nlt_f32_e32 vcc, s92, v132
	s_and_saveexec_b64 s[54:55], vcc
	s_cbranch_execz .LBB0_742
	v_mul_f32_e32 v132, 0x3fb8aa3b, v132
	v_exp_f32_e32 v133, v132
	s_nop 0
	v_fma_f32 v132, v133, s93, 0.5
	v_fma_f32 v132, -v133, v132, 1.0
	v_mul_f32_e32 v132, v133, v132
	v_cmp_ngt_f32_e32 vcc, s94, v133
	s_and_saveexec_b64 s[58:59], vcc
	s_cbranch_execz .LBB0_741
	v_add_f32_e32 v132, 1.0, v133
	v_cmp_gt_f32_e32 vcc, s95, v132
	s_nop 1
	v_cndmask_b32_e64 v133, 0, 32, vcc
	v_ldexp_f32 v132, v132, v133
	v_log_f32_e32 v132, v132
	s_nop 0
	v_mul_f32_e32 v133, 0x3f317217, v132
	v_fma_f32 v133, v132, s96, -v133
	v_fmac_f32_e32 v133, 0x3377d1cf, v132
	v_fmac_f32_e32 v133, 0x3f317217, v132
	v_cmp_lt_f32_e64 s[16:17], |v132|, s97
	s_nop 1
	v_cndmask_b32_e64 v132, v132, v133, s[16:17]
	v_cndmask_b32_e32 v133, 0, v194, vcc
	v_sub_f32_e32 v132, v132, v133

; __device__ __forceinline__ float softplusf_(float x) { const float e = __expf(x); const float sm = e * (1.f - e * (0.5f - e * 0.33333334f)); return x > 20.f ? x : (e < 0.01f ? sm : __logf(1.f + e)); }
;     __device__ __forceinline__ void operator()(AccT acc, const Unit& u, int wr, int wc, int fr, int fq) const {
;     ...
;                     *(f32x4*)d = (f32x4){softplusf_(v0[0] + bb[0]), softplusf_(v0[1] + bb[1]), softplusf_(v0[2] + bb[2]), softplusf_(v0[3] + bb[3])};
.LBB0_742:
	s_or_b64 exec, exec, s[54:55]
	s_nop 1
	v_mov_b32_e32 v133, v247
	v_add_f32_e32 v133, v129, v133
	v_cmp_nlt_f32_e32 vcc, s92, v133
	s_and_saveexec_b64 s[54:55], vcc
	s_cbranch_execz .LBB0_746
	v_mul_f32_e32 v133, 0x3fb8aa3b, v133
	v_exp_f32_e32 v135, v133
	s_nop 0
	v_fma_f32 v133, v135, s93, 0.5
	v_fma_f32 v133, -v135, v133, 1.0
	v_mul_f32_e32 v133, v135, v133
	v_cmp_ngt_f32_e32 vcc, s94, v135
	s_and_saveexec_b64 s[58:59], vcc
	s_cbranch_execz .LBB0_745
	v_add_f32_e32 v133, 1.0, v135
	v_cmp_gt_f32_e32 vcc, s95, v133
	s_nop 1
	v_cndmask_b32_e64 v135, 0, 32, vcc
	v_ldexp_f32 v133, v133, v135
	v_log_f32_e32 v133, v133
	s_nop 0
	v_mul_f32_e32 v135, 0x3f317217, v133
	v_fma_f32 v135, v133, s96, -v135
	v_fmac_f32_e32 v135, 0x3377d1cf, v133
	v_fmac_f32_e32 v135, 0x3f317217, v133
	v_cmp_lt_f32_e64 s[16:17], |v133|, s97
	s_nop 1
	v_cndmask_b32_e64 v133, v133, v135, s[16:17]
	v_cndmask_b32_e32 v135, 0, v194, vcc
	v_sub_f32_e32 v133, v133, v135

; __device__ __forceinline__ float softplusf_(float x) { const float e = __expf(x); const float sm = e * (1.f - e * (0.5f - e * 0.33333334f)); return x > 20.f ? x : (e < 0.01f ? sm : __logf(1.f + e)); }
;     __device__ __forceinline__ void operator()(AccT acc, const Unit& u, int wr, int wc, int fr, int fq) const {
;     ...
;                     *(f32x4*)d = (f32x4){softplusf_(v0[0] + bb[0]), softplusf_(v0[1] + bb[1]), softplusf_(v0[2] + bb[2]), softplusf_(v0[3] + bb[3])};
;                     *(f32x4*)(d + 4) = (f32x4){softplusf_(v1[0] + bb[4]), softplusf_(v1[1] + bb[5]), softplusf_(v1[2] + bb[6]), softplusf_(v1[3] + bb[7])};
.LBB0_746:
	s_or_b64 exec, exec, s[54:55]
	v_lshlrev_b64 v[142:143], 6, v[140:141]
	v_lshl_add_u64 v[142:143], v[162:163], 0, v[142:143]
	global_store_dwordx4 v[142:143], v[130:133], off
	s_nop 1
	v_mov_b32_e32 v130, v248
	v_add_f32_e32 v130, v122, v130
	v_cmp_nlt_f32_e32 vcc, s92, v130
	s_and_saveexec_b64 s[54:55], vcc
	s_cbranch_execz .LBB0_750
	v_mul_f32_e32 v130, 0x3fb8aa3b, v130
	v_exp_f32_e32 v131, v130
	s_nop 0
	v_fma_f32 v130, v131, s93, 0.5
	v_fma_f32 v130, -v131, v130, 1.0
	v_mul_f32_e32 v130, v131, v130
	v_cmp_ngt_f32_e32 vcc, s94, v131
	s_and_saveexec_b64 s[58:59], vcc
	s_cbranch_execz .LBB0_749
	v_add_f32_e32 v130, 1.0, v131
	v_cmp_gt_f32_e32 vcc, s95, v130
	s_nop 1
	v_cndmask_b32_e64 v131, 0, 32, vcc
	v_ldexp_f32 v130, v130, v131
	v_log_f32_e32 v130, v130
	s_nop 0
	v_mul_f32_e32 v131, 0x3f317217, v130
	v_fma_f32 v131, v130, s96, -v131
	v_fmac_f32_e32 v131, 0x3377d1cf, v130
	v_fmac_f32_e32 v131, 0x3f317217, v130
	v_cmp_lt_f32_e64 s[16:17], |v130|, s97
	s_nop 1
	v_cndmask_b32_e64 v130, v130, v131, s[16:17]
	v_cndmask_b32_e32 v131, 0, v194, vcc
	v_sub_f32_e32 v130, v130, v131

; __device__ __forceinline__ float softplusf_(float x) { const float e = __expf(x); const float sm = e * (1.f - e * (0.5f - e * 0.33333334f)); return x > 20.f ? x : (e < 0.01f ? sm : __logf(1.f + e)); }
;     __device__ __forceinline__ void operator()(AccT acc, const Unit& u, int wr, int wc, int fr, int fq) const {
;     ...
;                     *(f32x4*)(d + 4) = (f32x4){softplusf_(v1[0] + bb[4]), softplusf_(v1[1] + bb[5]), softplusf_(v1[2] + bb[6]), softplusf_(v1[3] + bb[7])};
.LBB0_750:
	s_or_b64 exec, exec, s[54:55]
	s_nop 1
	v_mov_b32_e32 v131, v249
	v_add_f32_e32 v131, v123, v131
	v_cmp_nlt_f32_e32 vcc, s92, v131
	s_and_saveexec_b64 s[54:55], vcc
	s_cbranch_execz .LBB0_754
	v_mul_f32_e32 v131, 0x3fb8aa3b, v131
	v_exp_f32_e32 v132, v131
	s_nop 0
	v_fma_f32 v131, v132, s93, 0.5
	v_fma_f32 v131, -v132, v131, 1.0
	v_mul_f32_e32 v131, v132, v131
	v_cmp_ngt_f32_e32 vcc, s94, v132
	s_and_saveexec_b64 s[58:59], vcc
	s_cbranch_execz .LBB0_753
	v_add_f32_e32 v131, 1.0, v132
	v_cmp_gt_f32_e32 vcc, s95, v131
	s_nop 1
	v_cndmask_b32_e64 v132, 0, 32, vcc
	v_ldexp_f32 v131, v131, v132
	v_log_f32_e32 v131, v131
	s_nop 0
	v_mul_f32_e32 v132, 0x3f317217, v131
	v_fma_f32 v132, v131, s96, -v132
	v_fmac_f32_e32 v132, 0x3377d1cf, v131
	v_fmac_f32_e32 v132, 0x3f317217, v131
	v_cmp_lt_f32_e64 s[16:17], |v131|, s97
	s_nop 1
	v_cndmask_b32_e64 v131, v131, v132, s[16:17]
	v_cndmask_b32_e32 v132, 0, v194, vcc
	v_sub_f32_e32 v131, v131, v132

; __device__ __forceinline__ float softplusf_(float x) { const float e = __expf(x); const float sm = e * (1.f - e * (0.5f - e * 0.33333334f)); return x > 20.f ? x : (e < 0.01f ? sm : __logf(1.f + e)); }
;     __device__ __forceinline__ void operator()(AccT acc, const Unit& u, int wr, int wc, int fr, int fq) const {
;     ...
;                     *(f32x4*)(d + 4) = (f32x4){softplusf_(v1[0] + bb[4]), softplusf_(v1[1] + bb[5]), softplusf_(v1[2] + bb[6]), softplusf_(v1[3] + bb[7])};
.LBB0_754:
	s_or_b64 exec, exec, s[54:55]
	s_nop 1
	v_mov_b32_e32 v132, v250
	v_add_f32_e32 v132, v124, v132
	v_cmp_nlt_f32_e32 vcc, s92, v132
	s_and_saveexec_b64 s[54:55], vcc
	s_cbranch_execz .LBB0_758
	v_mul_f32_e32 v132, 0x3fb8aa3b, v132
	v_exp_f32_e32 v133, v132
	s_nop 0
	v_fma_f32 v132, v133, s93, 0.5
	v_fma_f32 v132, -v133, v132, 1.0
	v_mul_f32_e32 v132, v133, v132
	v_cmp_ngt_f32_e32 vcc, s94, v133
	s_and_saveexec_b64 s[58:59], vcc
	s_cbranch_execz .LBB0_757
	v_add_f32_e32 v132, 1.0, v133
	v_cmp_gt_f32_e32 vcc, s95, v132
	s_nop 1
	v_cndmask_b32_e64 v133, 0, 32, vcc
	v_ldexp_f32 v132, v132, v133
	v_log_f32_e32 v132, v132
	s_nop 0
	v_mul_f32_e32 v133, 0x3f317217, v132
	v_fma_f32 v133, v132, s96, -v133
	v_fmac_f32_e32 v133, 0x3377d1cf, v132
	v_fmac_f32_e32 v133, 0x3f317217, v132
	v_cmp_lt_f32_e64 s[16:17], |v132|, s97
	s_nop 1
	v_cndmask_b32_e64 v132, v132, v133, s[16:17]
	v_cndmask_b32_e32 v133, 0, v194, vcc
	v_sub_f32_e32 v132, v132, v133

; __device__ __forceinline__ float softplusf_(float x) { const float e = __expf(x); const float sm = e * (1.f - e * (0.5f - e * 0.33333334f)); return x > 20.f ? x : (e < 0.01f ? sm : __logf(1.f + e)); }
;     __device__ __forceinline__ void operator()(AccT acc, const Unit& u, int wr, int wc, int fr, int fq) const {
;     ...
;                     *(f32x4*)(d + 4) = (f32x4){softplusf_(v1[0] + bb[4]), softplusf_(v1[1] + bb[5]), softplusf_(v1[2] + bb[6]), softplusf_(v1[3] + bb[7])};
.LBB0_758:
	s_or_b64 exec, exec, s[54:55]
	s_nop 1
	v_mov_b32_e32 v133, v251
	v_add_f32_e32 v133, v125, v133
	v_cmp_nlt_f32_e32 vcc, s92, v133
	s_and_saveexec_b64 s[54:55], vcc
	s_cbranch_execz .LBB0_762
	v_mul_f32_e32 v133, 0x3fb8aa3b, v133
	v_exp_f32_e32 v135, v133
	s_nop 0
	v_fma_f32 v133, v135, s93, 0.5
	v_fma_f32 v133, -v135, v133, 1.0
	v_mul_f32_e32 v133, v135, v133
	v_cmp_ngt_f32_e32 vcc, s94, v135
	s_and_saveexec_b64 s[58:59], vcc
	s_cbranch_execz .LBB0_761
	v_add_f32_e32 v133, 1.0, v135
	v_cmp_gt_f32_e32 vcc, s95, v133
	s_nop 1
	v_cndmask_b32_e64 v135, 0, 32, vcc
	v_ldexp_f32 v133, v133, v135
	v_log_f32_e32 v133, v133
	s_nop 0
	v_mul_f32_e32 v135, 0x3f317217, v133
	v_fma_f32 v135, v133, s96, -v135
	v_fmac_f32_e32 v135, 0x3377d1cf, v133
	v_fmac_f32_e32 v135, 0x3f317217, v133
	v_cmp_lt_f32_e64 s[16:17], |v133|, s97
	s_nop 1
	v_cndmask_b32_e64 v133, v133, v135, s[16:17]
	v_cndmask_b32_e32 v135, 0, v194, vcc
	v_sub_f32_e32 v133, v133, v135

; __device__ __forceinline__ float softplusf_(float x) { const float e = __expf(x); const float sm = e * (1.f - e * (0.5f - e * 0.33333334f)); return x > 20.f ? x : (e < 0.01f ? sm : __logf(1.f + e)); }
;     __device__ __forceinline__ void operator()(AccT acc, const Unit& u, int wr, int wc, int fr, int fq) const {
;     ...
;             const float rs = rs8[ai * 4 + m];
;             const int sq = seq_of_row(row); const bool isS = row >= NPROMPT; const int t = isS ? ((row - NPROMPT) & 7) : (row & (SEQ - 1));
;             if (!uni) { const float* sw = SHW + (size_t)sq * NZT + col0;
; #pragma unroll
;                 for (int bj = 0; bj < 2; ++bj) { sh[bj][0] = *(const f32x4*)(sw + bj * HALF); sh[bj][1] = *(const f32x4*)(sw + bj * HALF + 4); }
;                 asm volatile("" :: "v"(sh[0][0]), "v"(sh[0][1]), "v"(sh[1][0]), "v"(sh[1][1])); }
; #pragma unroll
;             for (int bj = 0; bj < 2; ++bj) { const int c = col0 + bj * HALF;
;                 const f32x4 v0 = acc[ai][bj][m][0] * rs + sh[bj][0], v1 = acc[ai][bj][m][1] * rs + sh[bj][1];
;                 if (u.pn < 48) {
;     ...
;                 } else if (bj == 0 && wc == 0 && fq < 2) {
;                     float* d = DT + (size_t)row * 16 + 8 * fq; const float* bb = dtb + 8 * fq;
;                     *(f32x4*)d = (f32x4){softplusf_(v0[0] + bb[0]), softplusf_(v0[1] + bb[1]), softplusf_(v0[2] + bb[2]), softplusf_(v0[3] + bb[3])};
.LBB0_792:
	s_waitcnt lgkmcnt(5)
	v_add_f32_e32 v114, v222, v223
	v_fmamk_f32 v114, v114, 0x3a800000, v193
	v_rsq_f32_e32 v120, v114
	v_cmp_gt_i32_e64 s[12:13], s81, v122
	v_cmp_lt_i32_e64 s[14:15], s91, v122
	v_ashrrev_i32_e32 v123, 31, v122
	s_mov_b64 s[16:17], -1
	v_pk_fma_f32 v[112:113], v[112:113], v[120:121], v[40:41] op_sel_hi:[1,0,1]
	v_pk_fma_f32 v[110:111], v[110:111], v[120:121], v[38:39] op_sel_hi:[1,0,1]
	v_pk_fma_f32 v[108:109], v[108:109], v[120:121], v[36:37] op_sel_hi:[1,0,1]
	s_and_b64 vcc, exec, s[10:11]
	v_pk_fma_f32 v[106:107], v[106:107], v[120:121], v[34:35] op_sel_hi:[1,0,1]
	s_cbranch_vccnz .LBB0_828
	s_and_saveexec_b64 s[18:19], s[38:39]
	s_cbranch_execz .LBB0_827
	s_nop 1
	v_mov_b32_e32 v114, v244
	v_add_f32_e32 v114, v110, v114
	v_cmp_nlt_f32_e32 vcc, s92, v114
	s_and_saveexec_b64 s[20:21], vcc
	s_cbranch_execz .LBB0_798
	v_mul_f32_e32 v114, 0x3fb8aa3b, v114
	v_exp_f32_e32 v115, v114
	s_nop 0
	v_fma_f32 v114, v115, s93, 0.5
	v_fma_f32 v114, -v115, v114, 1.0
	v_mul_f32_e32 v114, v115, v114
	v_cmp_ngt_f32_e32 vcc, s94, v115
	s_and_saveexec_b64 s[58:59], vcc
	s_cbranch_execz .LBB0_797
	v_add_f32_e32 v114, 1.0, v115
	v_cmp_gt_f32_e32 vcc, s95, v114
	s_nop 1
	v_cndmask_b32_e64 v115, 0, 32, vcc
	v_ldexp_f32 v114, v114, v115
	v_log_f32_e32 v114, v114
	s_nop 0
	v_mul_f32_e32 v115, 0x3f317217, v114
	v_fma_f32 v115, v114, s96, -v115
	v_fmac_f32_e32 v115, 0x3377d1cf, v114
	v_fmac_f32_e32 v115, 0x3f317217, v114
	v_cmp_lt_f32_e64 s[16:17], |v114|, s97
	s_nop 1
	v_cndmask_b32_e64 v114, v114, v115, s[16:17]
	v_cndmask_b32_e32 v115, 0, v194, vcc
	v_sub_f32_e32 v114, v114, v115

; __device__ __forceinline__ float softplusf_(float x) { const float e = __expf(x); const float sm = e * (1.f - e * (0.5f - e * 0.33333334f)); return x > 20.f ? x : (e < 0.01f ? sm : __logf(1.f + e)); }
;     __device__ __forceinline__ void operator()(AccT acc, const Unit& u, int wr, int wc, int fr, int fq) const {
;     ...
;                     *(f32x4*)d = (f32x4){softplusf_(v0[0] + bb[0]), softplusf_(v0[1] + bb[1]), softplusf_(v0[2] + bb[2]), softplusf_(v0[3] + bb[3])};
.LBB0_798:
	s_or_b64 exec, exec, s[20:21]
	s_nop 1
	v_mov_b32_e32 v115, v245
	v_add_f32_e32 v115, v111, v115
	v_cmp_nlt_f32_e32 vcc, s92, v115
	s_and_saveexec_b64 s[20:21], vcc
	s_cbranch_execz .LBB0_802
	v_mul_f32_e32 v115, 0x3fb8aa3b, v115
	v_exp_f32_e32 v116, v115
	s_nop 0
	v_fma_f32 v115, v116, s93, 0.5
	v_fma_f32 v115, -v116, v115, 1.0
	v_mul_f32_e32 v115, v116, v115
	v_cmp_ngt_f32_e32 vcc, s94, v116
	s_and_saveexec_b64 s[58:59], vcc
	s_cbranch_execz .LBB0_801
	v_add_f32_e32 v115, 1.0, v116
	v_cmp_gt_f32_e32 vcc, s95, v115
	s_nop 1
	v_cndmask_b32_e64 v116, 0, 32, vcc
	v_ldexp_f32 v115, v115, v116
	v_log_f32_e32 v115, v115
	s_nop 0
	v_mul_f32_e32 v116, 0x3f317217, v115
	v_fma_f32 v116, v115, s96, -v116
	v_fmac_f32_e32 v116, 0x3377d1cf, v115
	v_fmac_f32_e32 v116, 0x3f317217, v115
	v_cmp_lt_f32_e64 s[16:17], |v115|, s97
	s_nop 1
	v_cndmask_b32_e64 v115, v115, v116, s[16:17]
	v_cndmask_b32_e32 v116, 0, v194, vcc
	v_sub_f32_e32 v115, v115, v116

; __device__ __forceinline__ float softplusf_(float x) { const float e = __expf(x); const float sm = e * (1.f - e * (0.5f - e * 0.33333334f)); return x > 20.f ? x : (e < 0.01f ? sm : __logf(1.f + e)); }
;     __device__ __forceinline__ void operator()(AccT acc, const Unit& u, int wr, int wc, int fr, int fq) const {
;     ...
;                     *(f32x4*)d = (f32x4){softplusf_(v0[0] + bb[0]), softplusf_(v0[1] + bb[1]), softplusf_(v0[2] + bb[2]), softplusf_(v0[3] + bb[3])};
.LBB0_802:
	s_or_b64 exec, exec, s[20:21]
	s_nop 1
	v_mov_b32_e32 v116, v246
	v_add_f32_e32 v116, v112, v116
	v_cmp_nlt_f32_e32 vcc, s92, v116
	s_and_saveexec_b64 s[20:21], vcc
	s_cbranch_execz .LBB0_806
	v_mul_f32_e32 v116, 0x3fb8aa3b, v116
	v_exp_f32_e32 v117, v116
	s_nop 0
	v_fma_f32 v116, v117, s93, 0.5
	v_fma_f32 v116, -v117, v116, 1.0
	v_mul_f32_e32 v116, v117, v116
	v_cmp_ngt_f32_e32 vcc, s94, v117
	s_and_saveexec_b64 s[58:59], vcc
	s_cbranch_execz .LBB0_805
	v_add_f32_e32 v116, 1.0, v117
	v_cmp_gt_f32_e32 vcc, s95, v116
	s_nop 1
	v_cndmask_b32_e64 v117, 0, 32, vcc
	v_ldexp_f32 v116, v116, v117
	v_log_f32_e32 v116, v116
	s_nop 0
	v_mul_f32_e32 v117, 0x3f317217, v116
	v_fma_f32 v117, v116, s96, -v117
	v_fmac_f32_e32 v117, 0x3377d1cf, v116
	v_fmac_f32_e32 v117, 0x3f317217, v116
	v_cmp_lt_f32_e64 s[16:17], |v116|, s97
	s_nop 1
	v_cndmask_b32_e64 v116, v116, v117, s[16:17]
	v_cndmask_b32_e32 v117, 0, v194, vcc
	v_sub_f32_e32 v116, v116, v117

; __device__ __forceinline__ float softplusf_(float x) { const float e = __expf(x); const float sm = e * (1.f - e * (0.5f - e * 0.33333334f)); return x > 20.f ? x : (e < 0.01f ? sm : __logf(1.f + e)); }
;     __device__ __forceinline__ void operator()(AccT acc, const Unit& u, int wr, int wc, int fr, int fq) const {
;     ...
;                     *(f32x4*)d = (f32x4){softplusf_(v0[0] + bb[0]), softplusf_(v0[1] + bb[1]), softplusf_(v0[2] + bb[2]), softplusf_(v0[3] + bb[3])};
.LBB0_806:
	s_or_b64 exec, exec, s[20:21]
	s_nop 1
	v_mov_b32_e32 v117, v247
	v_add_f32_e32 v117, v113, v117
	v_cmp_nlt_f32_e32 vcc, s92, v117
	s_and_saveexec_b64 s[20:21], vcc
	s_cbranch_execz .LBB0_810
	v_mul_f32_e32 v117, 0x3fb8aa3b, v117
	v_exp_f32_e32 v119, v117
	s_nop 0
	v_fma_f32 v117, v119, s93, 0.5
	v_fma_f32 v117, -v119, v117, 1.0
	v_mul_f32_e32 v117, v119, v117
	v_cmp_ngt_f32_e32 vcc, s94, v119
	s_and_saveexec_b64 s[58:59], vcc
	s_cbranch_execz .LBB0_809
	v_add_f32_e32 v117, 1.0, v119
	v_cmp_gt_f32_e32 vcc, s95, v117
	s_nop 1
	v_cndmask_b32_e64 v119, 0, 32, vcc
	v_ldexp_f32 v117, v117, v119
	v_log_f32_e32 v117, v117
	s_nop 0
	v_mul_f32_e32 v119, 0x3f317217, v117
	v_fma_f32 v119, v117, s96, -v119
	v_fmac_f32_e32 v119, 0x3377d1cf, v117
	v_fmac_f32_e32 v119, 0x3f317217, v117
	v_cmp_lt_f32_e64 s[16:17], |v117|, s97
	s_nop 1
	v_cndmask_b32_e64 v117, v117, v119, s[16:17]
	v_cndmask_b32_e32 v119, 0, v194, vcc
	v_sub_f32_e32 v117, v117, v119

; __device__ __forceinline__ float softplusf_(float x) { const float e = __expf(x); const float sm = e * (1.f - e * (0.5f - e * 0.33333334f)); return x > 20.f ? x : (e < 0.01f ? sm : __logf(1.f + e)); }
;     __device__ __forceinline__ void operator()(AccT acc, const Unit& u, int wr, int wc, int fr, int fq) const {
;     ...
;                     *(f32x4*)d = (f32x4){softplusf_(v0[0] + bb[0]), softplusf_(v0[1] + bb[1]), softplusf_(v0[2] + bb[2]), softplusf_(v0[3] + bb[3])};
;                     *(f32x4*)(d + 4) = (f32x4){softplusf_(v1[0] + bb[4]), softplusf_(v1[1] + bb[5]), softplusf_(v1[2] + bb[6]), softplusf_(v1[3] + bb[7])};
.LBB0_810:
	s_or_b64 exec, exec, s[20:21]
	v_lshlrev_b64 v[124:125], 6, v[122:123]
	v_lshl_add_u64 v[124:125], v[162:163], 0, v[124:125]
	global_store_dwordx4 v[124:125], v[114:117], off
	s_nop 1
	v_mov_b32_e32 v114, v248
	v_add_f32_e32 v114, v106, v114
	v_cmp_nlt_f32_e32 vcc, s92, v114
	s_and_saveexec_b64 s[20:21], vcc
	s_cbranch_execz .LBB0_814
	v_mul_f32_e32 v114, 0x3fb8aa3b, v114
	v_exp_f32_e32 v115, v114
	s_nop 0
	v_fma_f32 v114, v115, s93, 0.5
	v_fma_f32 v114, -v115, v114, 1.0
	v_mul_f32_e32 v114, v115, v114
	v_cmp_ngt_f32_e32 vcc, s94, v115
	s_and_saveexec_b64 s[58:59], vcc
	s_cbranch_execz .LBB0_813
	v_add_f32_e32 v114, 1.0, v115
	v_cmp_gt_f32_e32 vcc, s95, v114
	s_nop 1
	v_cndmask_b32_e64 v115, 0, 32, vcc
	v_ldexp_f32 v114, v114, v115
	v_log_f32_e32 v114, v114
	s_nop 0
	v_mul_f32_e32 v115, 0x3f317217, v114
	v_fma_f32 v115, v114, s96, -v115
	v_fmac_f32_e32 v115, 0x3377d1cf, v114
	v_fmac_f32_e32 v115, 0x3f317217, v114
	v_cmp_lt_f32_e64 s[16:17], |v114|, s97
	s_nop 1
	v_cndmask_b32_e64 v114, v114, v115, s[16:17]
	v_cndmask_b32_e32 v115, 0, v194, vcc
	v_sub_f32_e32 v114, v114, v115

; __device__ __forceinline__ float softplusf_(float x) { const float e = __expf(x); const float sm = e * (1.f - e * (0.5f - e * 0.33333334f)); return x > 20.f ? x : (e < 0.01f ? sm : __logf(1.f + e)); }
;     __device__ __forceinline__ void operator()(AccT acc, const Unit& u, int wr, int wc, int fr, int fq) const {
;     ...
;                     *(f32x4*)(d + 4) = (f32x4){softplusf_(v1[0] + bb[4]), softplusf_(v1[1] + bb[5]), softplusf_(v1[2] + bb[6]), softplusf_(v1[3] + bb[7])};
.LBB0_814:
	s_or_b64 exec, exec, s[20:21]
	s_nop 1
	v_mov_b32_e32 v115, v249
	v_add_f32_e32 v115, v107, v115
	v_cmp_nlt_f32_e32 vcc, s92, v115
	s_and_saveexec_b64 s[20:21], vcc
	s_cbranch_execz .LBB0_818
	v_mul_f32_e32 v115, 0x3fb8aa3b, v115
	v_exp_f32_e32 v116, v115
	s_nop 0
	v_fma_f32 v115, v116, s93, 0.5
	v_fma_f32 v115, -v116, v115, 1.0
	v_mul_f32_e32 v115, v116, v115
	v_cmp_ngt_f32_e32 vcc, s94, v116
	s_and_saveexec_b64 s[58:59], vcc
	s_cbranch_execz .LBB0_817
	v_add_f32_e32 v115, 1.0, v116
	v_cmp_gt_f32_e32 vcc, s95, v115
	s_nop 1
	v_cndmask_b32_e64 v116, 0, 32, vcc
	v_ldexp_f32 v115, v115, v116
	v_log_f32_e32 v115, v115
	s_nop 0
	v_mul_f32_e32 v116, 0x3f317217, v115
	v_fma_f32 v116, v115, s96, -v116
	v_fmac_f32_e32 v116, 0x3377d1cf, v115
	v_fmac_f32_e32 v116, 0x3f317217, v115
	v_cmp_lt_f32_e64 s[16:17], |v115|, s97
	s_nop 1
	v_cndmask_b32_e64 v115, v115, v116, s[16:17]
	v_cndmask_b32_e32 v116, 0, v194, vcc
	v_sub_f32_e32 v115, v115, v116

; __device__ __forceinline__ float softplusf_(float x) { const float e = __expf(x); const float sm = e * (1.f - e * (0.5f - e * 0.33333334f)); return x > 20.f ? x : (e < 0.01f ? sm : __logf(1.f + e)); }
;     __device__ __forceinline__ void operator()(AccT acc, const Unit& u, int wr, int wc, int fr, int fq) const {
;     ...
;                     *(f32x4*)(d + 4) = (f32x4){softplusf_(v1[0] + bb[4]), softplusf_(v1[1] + bb[5]), softplusf_(v1[2] + bb[6]), softplusf_(v1[3] + bb[7])};
.LBB0_818:
	s_or_b64 exec, exec, s[20:21]
	s_nop 1
	v_mov_b32_e32 v116, v250
	v_add_f32_e32 v116, v108, v116
	v_cmp_nlt_f32_e32 vcc, s92, v116
	s_and_saveexec_b64 s[20:21], vcc
	s_cbranch_execz .LBB0_822
	v_mul_f32_e32 v116, 0x3fb8aa3b, v116
	v_exp_f32_e32 v117, v116
	s_nop 0
	v_fma_f32 v116, v117, s93, 0.5
	v_fma_f32 v116, -v117, v116, 1.0
	v_mul_f32_e32 v116, v117, v116
	v_cmp_ngt_f32_e32 vcc, s94, v117
	s_and_saveexec_b64 s[58:59], vcc
	s_cbranch_execz .LBB0_821
	v_add_f32_e32 v116, 1.0, v117
	v_cmp_gt_f32_e32 vcc, s95, v116
	s_nop 1
	v_cndmask_b32_e64 v117, 0, 32, vcc
	v_ldexp_f32 v116, v116, v117
	v_log_f32_e32 v116, v116
	s_nop 0
	v_mul_f32_e32 v117, 0x3f317217, v116
	v_fma_f32 v117, v116, s96, -v117
	v_fmac_f32_e32 v117, 0x3377d1cf, v116
	v_fmac_f32_e32 v117, 0x3f317217, v116
	v_cmp_lt_f32_e64 s[16:17], |v116|, s97
	s_nop 1
	v_cndmask_b32_e64 v116, v116, v117, s[16:17]
	v_cndmask_b32_e32 v117, 0, v194, vcc
	v_sub_f32_e32 v116, v116, v117

; __device__ __forceinline__ float softplusf_(float x) { const float e = __expf(x); const float sm = e * (1.f - e * (0.5f - e * 0.33333334f)); return x > 20.f ? x : (e < 0.01f ? sm : __logf(1.f + e)); }
;     __device__ __forceinline__ void operator()(AccT acc, const Unit& u, int wr, int wc, int fr, int fq) const {
;     ...
;                     *(f32x4*)(d + 4) = (f32x4){softplusf_(v1[0] + bb[4]), softplusf_(v1[1] + bb[5]), softplusf_(v1[2] + bb[6]), softplusf_(v1[3] + bb[7])};
.LBB0_822:
	s_or_b64 exec, exec, s[20:21]
	s_nop 1
	v_mov_b32_e32 v117, v251
	v_add_f32_e32 v117, v109, v117
	v_cmp_nlt_f32_e32 vcc, s92, v117
	s_and_saveexec_b64 s[20:21], vcc
	s_cbranch_execz .LBB0_826
	v_mul_f32_e32 v117, 0x3fb8aa3b, v117
	v_exp_f32_e32 v119, v117
	s_nop 0
	v_fma_f32 v117, v119, s93, 0.5
	v_fma_f32 v117, -v119, v117, 1.0
	v_mul_f32_e32 v117, v119, v117
	v_cmp_ngt_f32_e32 vcc, s94, v119
	s_and_saveexec_b64 s[58:59], vcc
	s_cbranch_execz .LBB0_825
	v_add_f32_e32 v117, 1.0, v119
	v_cmp_gt_f32_e32 vcc, s95, v117
	s_nop 1
	v_cndmask_b32_e64 v119, 0, 32, vcc
	v_ldexp_f32 v117, v117, v119
	v_log_f32_e32 v117, v117
	s_nop 0
	v_mul_f32_e32 v119, 0x3f317217, v117
	v_fma_f32 v119, v117, s96, -v119
	v_fmac_f32_e32 v119, 0x3377d1cf, v117
	v_fmac_f32_e32 v119, 0x3f317217, v117
	v_cmp_lt_f32_e64 s[16:17], |v117|, s97
	s_nop 1
	v_cndmask_b32_e64 v117, v117, v119, s[16:17]
	v_cndmask_b32_e32 v119, 0, v194, vcc
	v_sub_f32_e32 v117, v117, v119

; __device__ __forceinline__ float softplusf_(float x) { const float e = __expf(x); const float sm = e * (1.f - e * (0.5f - e * 0.33333334f)); return x > 20.f ? x : (e < 0.01f ? sm : __logf(1.f + e)); }
;     __device__ __forceinline__ void operator()(AccT acc, const Unit& u, int wr, int wc, int fr, int fq) const {
;     ...
;             const float rs = rs8[ai * 4 + m];
;             const int sq = seq_of_row(row); const bool isS = row >= NPROMPT; const int t = isS ? ((row - NPROMPT) & 7) : (row & (SEQ - 1));
;             if (!uni) { const float* sw = SHW + (size_t)sq * NZT + col0;
; #pragma unroll
;                 for (int bj = 0; bj < 2; ++bj) { sh[bj][0] = *(const f32x4*)(sw + bj * HALF); sh[bj][1] = *(const f32x4*)(sw + bj * HALF + 4); }
;                 asm volatile("" :: "v"(sh[0][0]), "v"(sh[0][1]), "v"(sh[1][0]), "v"(sh[1][1])); }
; #pragma unroll
;             for (int bj = 0; bj < 2; ++bj) { const int c = col0 + bj * HALF;
;                 const f32x4 v0 = acc[ai][bj][m][0] * rs + sh[bj][0], v1 = acc[ai][bj][m][1] * rs + sh[bj][1];
;                 if (u.pn < 48) {
;     ...
;                 } else if (bj == 0 && wc == 0 && fq < 2) {
;                     float* d = DT + (size_t)row * 16 + 8 * fq; const float* bb = dtb + 8 * fq;
;                     *(f32x4*)d = (f32x4){softplusf_(v0[0] + bb[0]), softplusf_(v0[1] + bb[1]), softplusf_(v0[2] + bb[2]), softplusf_(v0[3] + bb[3])};
.LBB0_856:
	s_waitcnt lgkmcnt(4)
	v_add_f32_e32 v98, v220, v221
	v_fmamk_f32 v98, v98, 0x3a800000, v193
	v_rsq_f32_e32 v104, v98
	v_cmp_gt_i32_e64 s[12:13], s81, v106
	v_cmp_lt_i32_e64 s[14:15], s91, v106
	v_ashrrev_i32_e32 v107, 31, v106
	s_mov_b64 s[16:17], -1
	v_pk_fma_f32 v[96:97], v[96:97], v[104:105], v[40:41] op_sel_hi:[1,0,1]
	v_pk_fma_f32 v[94:95], v[94:95], v[104:105], v[38:39] op_sel_hi:[1,0,1]
	v_pk_fma_f32 v[92:93], v[92:93], v[104:105], v[36:37] op_sel_hi:[1,0,1]
	s_and_b64 vcc, exec, s[10:11]
	v_pk_fma_f32 v[90:91], v[90:91], v[104:105], v[34:35] op_sel_hi:[1,0,1]
	s_cbranch_vccnz .LBB0_892
	s_and_saveexec_b64 s[18:19], s[38:39]
	s_cbranch_execz .LBB0_891
	s_nop 1
	v_mov_b32_e32 v98, v244
	v_add_f32_e32 v98, v94, v98
	v_cmp_nlt_f32_e32 vcc, s92, v98
	s_and_saveexec_b64 s[20:21], vcc
	s_cbranch_execz .LBB0_862
	v_mul_f32_e32 v98, 0x3fb8aa3b, v98
	v_exp_f32_e32 v99, v98
	s_nop 0
	v_fma_f32 v98, v99, s93, 0.5
	v_fma_f32 v98, -v99, v98, 1.0
	v_mul_f32_e32 v98, v99, v98
	v_cmp_ngt_f32_e32 vcc, s94, v99
	s_and_saveexec_b64 s[58:59], vcc
	s_cbranch_execz .LBB0_861
	v_add_f32_e32 v98, 1.0, v99
	v_cmp_gt_f32_e32 vcc, s95, v98
	s_nop 1
	v_cndmask_b32_e64 v99, 0, 32, vcc
	v_ldexp_f32 v98, v98, v99
	v_log_f32_e32 v98, v98
	s_nop 0
	v_mul_f32_e32 v99, 0x3f317217, v98
	v_fma_f32 v99, v98, s96, -v99
	v_fmac_f32_e32 v99, 0x3377d1cf, v98
	v_fmac_f32_e32 v99, 0x3f317217, v98
	v_cmp_lt_f32_e64 s[16:17], |v98|, s97
	s_nop 1
	v_cndmask_b32_e64 v98, v98, v99, s[16:17]
	v_cndmask_b32_e32 v99, 0, v194, vcc
	v_sub_f32_e32 v98, v98, v99

; __device__ __forceinline__ float softplusf_(float x) { const float e = __expf(x); const float sm = e * (1.f - e * (0.5f - e * 0.33333334f)); return x > 20.f ? x : (e < 0.01f ? sm : __logf(1.f + e)); }
;     __device__ __forceinline__ void operator()(AccT acc, const Unit& u, int wr, int wc, int fr, int fq) const {
;     ...
;                     *(f32x4*)d = (f32x4){softplusf_(v0[0] + bb[0]), softplusf_(v0[1] + bb[1]), softplusf_(v0[2] + bb[2]), softplusf_(v0[3] + bb[3])};
.LBB0_862:
	s_or_b64 exec, exec, s[20:21]
	s_nop 1
	v_mov_b32_e32 v99, v245
	v_add_f32_e32 v99, v95, v99
	v_cmp_nlt_f32_e32 vcc, s92, v99
	s_and_saveexec_b64 s[20:21], vcc
	s_cbranch_execz .LBB0_866
	v_mul_f32_e32 v99, 0x3fb8aa3b, v99
	v_exp_f32_e32 v100, v99
	s_nop 0
	v_fma_f32 v99, v100, s93, 0.5
	v_fma_f32 v99, -v100, v99, 1.0
	v_mul_f32_e32 v99, v100, v99
	v_cmp_ngt_f32_e32 vcc, s94, v100
	s_and_saveexec_b64 s[58:59], vcc
	s_cbranch_execz .LBB0_865
	v_add_f32_e32 v99, 1.0, v100
	v_cmp_gt_f32_e32 vcc, s95, v99
	s_nop 1
	v_cndmask_b32_e64 v100, 0, 32, vcc
	v_ldexp_f32 v99, v99, v100
	v_log_f32_e32 v99, v99
	s_nop 0
	v_mul_f32_e32 v100, 0x3f317217, v99
	v_fma_f32 v100, v99, s96, -v100
	v_fmac_f32_e32 v100, 0x3377d1cf, v99
	v_fmac_f32_e32 v100, 0x3f317217, v99
	v_cmp_lt_f32_e64 s[16:17], |v99|, s97
	s_nop 1
	v_cndmask_b32_e64 v99, v99, v100, s[16:17]
	v_cndmask_b32_e32 v100, 0, v194, vcc
	v_sub_f32_e32 v99, v99, v100

; __device__ __forceinline__ float softplusf_(float x) { const float e = __expf(x); const float sm = e * (1.f - e * (0.5f - e * 0.33333334f)); return x > 20.f ? x : (e < 0.01f ? sm : __logf(1.f + e)); }
;     __device__ __forceinline__ void operator()(AccT acc, const Unit& u, int wr, int wc, int fr, int fq) const {
;     ...
;                     *(f32x4*)d = (f32x4){softplusf_(v0[0] + bb[0]), softplusf_(v0[1] + bb[1]), softplusf_(v0[2] + bb[2]), softplusf_(v0[3] + bb[3])};
.LBB0_866:
	s_or_b64 exec, exec, s[20:21]
	s_nop 1
	v_mov_b32_e32 v100, v246
	v_add_f32_e32 v100, v96, v100
	v_cmp_nlt_f32_e32 vcc, s92, v100
	s_and_saveexec_b64 s[20:21], vcc
	s_cbranch_execz .LBB0_870
	v_mul_f32_e32 v100, 0x3fb8aa3b, v100
	v_exp_f32_e32 v101, v100
	s_nop 0
	v_fma_f32 v100, v101, s93, 0.5
	v_fma_f32 v100, -v101, v100, 1.0
	v_mul_f32_e32 v100, v101, v100
	v_cmp_ngt_f32_e32 vcc, s94, v101
	s_and_saveexec_b64 s[58:59], vcc
	s_cbranch_execz .LBB0_869
	v_add_f32_e32 v100, 1.0, v101
	v_cmp_gt_f32_e32 vcc, s95, v100
	s_nop 1
	v_cndmask_b32_e64 v101, 0, 32, vcc
	v_ldexp_f32 v100, v100, v101
	v_log_f32_e32 v100, v100
	s_nop 0
	v_mul_f32_e32 v101, 0x3f317217, v100
	v_fma_f32 v101, v100, s96, -v101
	v_fmac_f32_e32 v101, 0x3377d1cf, v100
	v_fmac_f32_e32 v101, 0x3f317217, v100
	v_cmp_lt_f32_e64 s[16:17], |v100|, s97
	s_nop 1
	v_cndmask_b32_e64 v100, v100, v101, s[16:17]
	v_cndmask_b32_e32 v101, 0, v194, vcc
	v_sub_f32_e32 v100, v100, v101

; __device__ __forceinline__ float softplusf_(float x) { const float e = __expf(x); const float sm = e * (1.f - e * (0.5f - e * 0.33333334f)); return x > 20.f ? x : (e < 0.01f ? sm : __logf(1.f + e)); }
;     __device__ __forceinline__ void operator()(AccT acc, const Unit& u, int wr, int wc, int fr, int fq) const {
;     ...
;                     *(f32x4*)d = (f32x4){softplusf_(v0[0] + bb[0]), softplusf_(v0[1] + bb[1]), softplusf_(v0[2] + bb[2]), softplusf_(v0[3] + bb[3])};
.LBB0_870:
	s_or_b64 exec, exec, s[20:21]
	s_nop 1
	v_mov_b32_e32 v101, v247
	v_add_f32_e32 v101, v97, v101
	v_cmp_nlt_f32_e32 vcc, s92, v101
	s_and_saveexec_b64 s[20:21], vcc
	s_cbranch_execz .LBB0_874
	v_mul_f32_e32 v101, 0x3fb8aa3b, v101
	v_exp_f32_e32 v103, v101
	s_nop 0
	v_fma_f32 v101, v103, s93, 0.5
	v_fma_f32 v101, -v103, v101, 1.0
	v_mul_f32_e32 v101, v103, v101
	v_cmp_ngt_f32_e32 vcc, s94, v103
	s_and_saveexec_b64 s[58:59], vcc
	s_cbranch_execz .LBB0_873
	v_add_f32_e32 v101, 1.0, v103
	v_cmp_gt_f32_e32 vcc, s95, v101
	s_nop 1
	v_cndmask_b32_e64 v103, 0, 32, vcc
	v_ldexp_f32 v101, v101, v103
	v_log_f32_e32 v101, v101
	s_nop 0
	v_mul_f32_e32 v103, 0x3f317217, v101
	v_fma_f32 v103, v101, s96, -v103
	v_fmac_f32_e32 v103, 0x3377d1cf, v101
	v_fmac_f32_e32 v103, 0x3f317217, v101
	v_cmp_lt_f32_e64 s[16:17], |v101|, s97
	s_nop 1
	v_cndmask_b32_e64 v101, v101, v103, s[16:17]
	v_cndmask_b32_e32 v103, 0, v194, vcc
	v_sub_f32_e32 v101, v101, v103

; __device__ __forceinline__ float softplusf_(float x) { const float e = __expf(x); const float sm = e * (1.f - e * (0.5f - e * 0.33333334f)); return x > 20.f ? x : (e < 0.01f ? sm : __logf(1.f + e)); }
;     __device__ __forceinline__ void operator()(AccT acc, const Unit& u, int wr, int wc, int fr, int fq) const {
;     ...
;                     *(f32x4*)d = (f32x4){softplusf_(v0[0] + bb[0]), softplusf_(v0[1] + bb[1]), softplusf_(v0[2] + bb[2]), softplusf_(v0[3] + bb[3])};
;                     *(f32x4*)(d + 4) = (f32x4){softplusf_(v1[0] + bb[4]), softplusf_(v1[1] + bb[5]), softplusf_(v1[2] + bb[6]), softplusf_(v1[3] + bb[7])};
.LBB0_874:
	s_or_b64 exec, exec, s[20:21]
	v_lshlrev_b64 v[108:109], 6, v[106:107]
	v_lshl_add_u64 v[108:109], v[162:163], 0, v[108:109]
	global_store_dwordx4 v[108:109], v[98:101], off
	s_nop 1
	v_mov_b32_e32 v98, v248
	v_add_f32_e32 v98, v90, v98
	v_cmp_nlt_f32_e32 vcc, s92, v98
	s_and_saveexec_b64 s[20:21], vcc
	s_cbranch_execz .LBB0_878
	v_mul_f32_e32 v98, 0x3fb8aa3b, v98
	v_exp_f32_e32 v99, v98
	s_nop 0
	v_fma_f32 v98, v99, s93, 0.5
	v_fma_f32 v98, -v99, v98, 1.0
	v_mul_f32_e32 v98, v99, v98
	v_cmp_ngt_f32_e32 vcc, s94, v99
	s_and_saveexec_b64 s[58:59], vcc
	s_cbranch_execz .LBB0_877
	v_add_f32_e32 v98, 1.0, v99
	v_cmp_gt_f32_e32 vcc, s95, v98
	s_nop 1
	v_cndmask_b32_e64 v99, 0, 32, vcc
	v_ldexp_f32 v98, v98, v99
	v_log_f32_e32 v98, v98
	s_nop 0
	v_mul_f32_e32 v99, 0x3f317217, v98
	v_fma_f32 v99, v98, s96, -v99
	v_fmac_f32_e32 v99, 0x3377d1cf, v98
	v_fmac_f32_e32 v99, 0x3f317217, v98
	v_cmp_lt_f32_e64 s[16:17], |v98|, s97
	s_nop 1
	v_cndmask_b32_e64 v98, v98, v99, s[16:17]
	v_cndmask_b32_e32 v99, 0, v194, vcc
	v_sub_f32_e32 v98, v98, v99

; __device__ __forceinline__ float softplusf_(float x) { const float e = __expf(x); const float sm = e * (1.f - e * (0.5f - e * 0.33333334f)); return x > 20.f ? x : (e < 0.01f ? sm : __logf(1.f + e)); }
;     __device__ __forceinline__ void operator()(AccT acc, const Unit& u, int wr, int wc, int fr, int fq) const {
;     ...
;                     *(f32x4*)(d + 4) = (f32x4){softplusf_(v1[0] + bb[4]), softplusf_(v1[1] + bb[5]), softplusf_(v1[2] + bb[6]), softplusf_(v1[3] + bb[7])};
.LBB0_878:
	s_or_b64 exec, exec, s[20:21]
	s_nop 1
	v_mov_b32_e32 v99, v249
	v_add_f32_e32 v99, v91, v99
	v_cmp_nlt_f32_e32 vcc, s92, v99
	s_and_saveexec_b64 s[20:21], vcc
	s_cbranch_execz .LBB0_882
	v_mul_f32_e32 v99, 0x3fb8aa3b, v99
	v_exp_f32_e32 v100, v99
	s_nop 0
	v_fma_f32 v99, v100, s93, 0.5
	v_fma_f32 v99, -v100, v99, 1.0
	v_mul_f32_e32 v99, v100, v99
	v_cmp_ngt_f32_e32 vcc, s94, v100
	s_and_saveexec_b64 s[58:59], vcc
	s_cbranch_execz .LBB0_881
	v_add_f32_e32 v99, 1.0, v100
	v_cmp_gt_f32_e32 vcc, s95, v99
	s_nop 1
	v_cndmask_b32_e64 v100, 0, 32, vcc
	v_ldexp_f32 v99, v99, v100
	v_log_f32_e32 v99, v99
	s_nop 0
	v_mul_f32_e32 v100, 0x3f317217, v99
	v_fma_f32 v100, v99, s96, -v100
	v_fmac_f32_e32 v100, 0x3377d1cf, v99
	v_fmac_f32_e32 v100, 0x3f317217, v99
	v_cmp_lt_f32_e64 s[16:17], |v99|, s97
	s_nop 1
	v_cndmask_b32_e64 v99, v99, v100, s[16:17]
	v_cndmask_b32_e32 v100, 0, v194, vcc
	v_sub_f32_e32 v99, v99, v100

; __device__ __forceinline__ float softplusf_(float x) { const float e = __expf(x); const float sm = e * (1.f - e * (0.5f - e * 0.33333334f)); return x > 20.f ? x : (e < 0.01f ? sm : __logf(1.f + e)); }
;     __device__ __forceinline__ void operator()(AccT acc, const Unit& u, int wr, int wc, int fr, int fq) const {
;     ...
;                     *(f32x4*)(d + 4) = (f32x4){softplusf_(v1[0] + bb[4]), softplusf_(v1[1] + bb[5]), softplusf_(v1[2] + bb[6]), softplusf_(v1[3] + bb[7])};
.LBB0_882:
	s_or_b64 exec, exec, s[20:21]
	s_nop 1
	v_mov_b32_e32 v100, v250
	v_add_f32_e32 v100, v92, v100
	v_cmp_nlt_f32_e32 vcc, s92, v100
	s_and_saveexec_b64 s[20:21], vcc
	s_cbranch_execz .LBB0_886
	v_mul_f32_e32 v100, 0x3fb8aa3b, v100
	v_exp_f32_e32 v101, v100
	s_nop 0
	v_fma_f32 v100, v101, s93, 0.5
	v_fma_f32 v100, -v101, v100, 1.0
	v_mul_f32_e32 v100, v101, v100
	v_cmp_ngt_f32_e32 vcc, s94, v101
	s_and_saveexec_b64 s[58:59], vcc
	s_cbranch_execz .LBB0_885
	v_add_f32_e32 v100, 1.0, v101
	v_cmp_gt_f32_e32 vcc, s95, v100
	s_nop 1
	v_cndmask_b32_e64 v101, 0, 32, vcc
	v_ldexp_f32 v100, v100, v101
	v_log_f32_e32 v100, v100
	s_nop 0
	v_mul_f32_e32 v101, 0x3f317217, v100
	v_fma_f32 v101, v100, s96, -v101
	v_fmac_f32_e32 v101, 0x3377d1cf, v100
	v_fmac_f32_e32 v101, 0x3f317217, v100
	v_cmp_lt_f32_e64 s[16:17], |v100|, s97
	s_nop 1
	v_cndmask_b32_e64 v100, v100, v101, s[16:17]
	v_cndmask_b32_e32 v101, 0, v194, vcc
	v_sub_f32_e32 v100, v100, v101

; __device__ __forceinline__ float softplusf_(float x) { const float e = __expf(x); const float sm = e * (1.f - e * (0.5f - e * 0.33333334f)); return x > 20.f ? x : (e < 0.01f ? sm : __logf(1.f + e)); }
;     __device__ __forceinline__ void operator()(AccT acc, const Unit& u, int wr, int wc, int fr, int fq) const {
;     ...
;                     *(f32x4*)(d + 4) = (f32x4){softplusf_(v1[0] + bb[4]), softplusf_(v1[1] + bb[5]), softplusf_(v1[2] + bb[6]), softplusf_(v1[3] + bb[7])};
.LBB0_886:
	s_or_b64 exec, exec, s[20:21]
	s_nop 1
	v_mov_b32_e32 v101, v251
	v_add_f32_e32 v101, v93, v101
	v_cmp_nlt_f32_e32 vcc, s92, v101
	s_and_saveexec_b64 s[20:21], vcc
	s_cbranch_execz .LBB0_890
	v_mul_f32_e32 v101, 0x3fb8aa3b, v101
	v_exp_f32_e32 v103, v101
	s_nop 0
	v_fma_f32 v101, v103, s93, 0.5
	v_fma_f32 v101, -v103, v101, 1.0
	v_mul_f32_e32 v101, v103, v101
	v_cmp_ngt_f32_e32 vcc, s94, v103
	s_and_saveexec_b64 s[58:59], vcc
	s_cbranch_execz .LBB0_889
	v_add_f32_e32 v101, 1.0, v103
	v_cmp_gt_f32_e32 vcc, s95, v101
	s_nop 1
	v_cndmask_b32_e64 v103, 0, 32, vcc
	v_ldexp_f32 v101, v101, v103
	v_log_f32_e32 v101, v101
	s_nop 0
	v_mul_f32_e32 v103, 0x3f317217, v101
	v_fma_f32 v103, v101, s96, -v103
	v_fmac_f32_e32 v103, 0x3377d1cf, v101
	v_fmac_f32_e32 v103, 0x3f317217, v101
	v_cmp_lt_f32_e64 s[16:17], |v101|, s97
	s_nop 1
	v_cndmask_b32_e64 v101, v101, v103, s[16:17]
	v_cndmask_b32_e32 v103, 0, v194, vcc
	v_sub_f32_e32 v101, v101, v103

; __device__ __forceinline__ float softplusf_(float x) { const float e = __expf(x); const float sm = e * (1.f - e * (0.5f - e * 0.33333334f)); return x > 20.f ? x : (e < 0.01f ? sm : __logf(1.f + e)); }
;     __device__ __forceinline__ void operator()(AccT acc, const Unit& u, int wr, int wc, int fr, int fq) const {
;     ...
;             const float rs = rs8[ai * 4 + m];
;             const int sq = seq_of_row(row); const bool isS = row >= NPROMPT; const int t = isS ? ((row - NPROMPT) & 7) : (row & (SEQ - 1));
;             if (!uni) { const float* sw = SHW + (size_t)sq * NZT + col0;
; #pragma unroll
;                 for (int bj = 0; bj < 2; ++bj) { sh[bj][0] = *(const f32x4*)(sw + bj * HALF); sh[bj][1] = *(const f32x4*)(sw + bj * HALF + 4); }
;                 asm volatile("" :: "v"(sh[0][0]), "v"(sh[0][1]), "v"(sh[1][0]), "v"(sh[1][1])); }
; #pragma unroll
;             for (int bj = 0; bj < 2; ++bj) { const int c = col0 + bj * HALF;
;                 const f32x4 v0 = acc[ai][bj][m][0] * rs + sh[bj][0], v1 = acc[ai][bj][m][1] * rs + sh[bj][1];
;                 if (u.pn < 48) {
;     ...
;                 } else if (bj == 0 && wc == 0 && fq < 2) {
;                     float* d = DT + (size_t)row * 16 + 8 * fq; const float* bb = dtb + 8 * fq;
;                     *(f32x4*)d = (f32x4){softplusf_(v0[0] + bb[0]), softplusf_(v0[1] + bb[1]), softplusf_(v0[2] + bb[2]), softplusf_(v0[3] + bb[3])};
.LBB0_920:
	s_waitcnt lgkmcnt(3)
	v_add_f32_e32 v82, v218, v219
	v_fmamk_f32 v82, v82, 0x3a800000, v193
	v_rsq_f32_e32 v90, v82
	v_cmp_gt_i32_e64 s[12:13], s81, v86
	v_cmp_lt_i32_e64 s[14:15], s91, v86
	v_ashrrev_i32_e32 v87, 31, v86
	s_mov_b64 s[16:17], -1
	v_pk_fma_f32 v[80:81], v[80:81], v[90:91], v[40:41] op_sel_hi:[1,0,1]
	v_pk_fma_f32 v[78:79], v[78:79], v[90:91], v[38:39] op_sel_hi:[1,0,1]
	v_pk_fma_f32 v[76:77], v[76:77], v[90:91], v[36:37] op_sel_hi:[1,0,1]
	s_and_b64 vcc, exec, s[10:11]
	v_pk_fma_f32 v[74:75], v[74:75], v[90:91], v[34:35] op_sel_hi:[1,0,1]
	s_cbranch_vccnz .LBB0_956
	s_and_saveexec_b64 s[18:19], s[38:39]
	s_cbranch_execz .LBB0_955
	global_load_dwordx4 v[244:247], v[166:167], off
	global_load_dwordx4 v[248:251], v[166:167], off offset:16
	s_waitcnt vmcnt(0)
	v_mov_b32_e32 v82, v244
	v_add_f32_e32 v82, v78, v82
	v_cmp_nlt_f32_e32 vcc, s92, v82
	s_and_saveexec_b64 s[20:21], vcc
	s_cbranch_execz .LBB0_926
	v_mul_f32_e32 v82, 0x3fb8aa3b, v82
	v_exp_f32_e32 v83, v82
	s_nop 0
	v_fma_f32 v82, v83, s93, 0.5
	v_fma_f32 v82, -v83, v82, 1.0
	v_mul_f32_e32 v82, v83, v82
	v_cmp_ngt_f32_e32 vcc, s94, v83
	s_and_saveexec_b64 s[58:59], vcc
	s_cbranch_execz .LBB0_925
	v_add_f32_e32 v82, 1.0, v83
	v_cmp_gt_f32_e32 vcc, s95, v82
	s_nop 1
	v_cndmask_b32_e64 v83, 0, 32, vcc
	v_ldexp_f32 v82, v82, v83
	v_log_f32_e32 v82, v82
	s_nop 0
	v_mul_f32_e32 v83, 0x3f317217, v82
	v_fma_f32 v83, v82, s96, -v83
	v_fmac_f32_e32 v83, 0x3377d1cf, v82
	v_fmac_f32_e32 v83, 0x3f317217, v82
	v_cmp_lt_f32_e64 s[16:17], |v82|, s97
	s_nop 1
	v_cndmask_b32_e64 v82, v82, v83, s[16:17]
	v_cndmask_b32_e32 v83, 0, v194, vcc
	v_sub_f32_e32 v82, v82, v83

; __device__ __forceinline__ float softplusf_(float x) { const float e = __expf(x); const float sm = e * (1.f - e * (0.5f - e * 0.33333334f)); return x > 20.f ? x : (e < 0.01f ? sm : __logf(1.f + e)); }
;     __device__ __forceinline__ void operator()(AccT acc, const Unit& u, int wr, int wc, int fr, int fq) const {
;     ...
;                     *(f32x4*)d = (f32x4){softplusf_(v0[0] + bb[0]), softplusf_(v0[1] + bb[1]), softplusf_(v0[2] + bb[2]), softplusf_(v0[3] + bb[3])};
.LBB0_926:
	s_or_b64 exec, exec, s[20:21]
	s_nop 1
	v_mov_b32_e32 v83, v245
	v_add_f32_e32 v83, v79, v83
	v_cmp_nlt_f32_e32 vcc, s92, v83
	s_and_saveexec_b64 s[20:21], vcc
	s_cbranch_execz .LBB0_930
	v_mul_f32_e32 v83, 0x3fb8aa3b, v83
	v_exp_f32_e32 v84, v83
	s_nop 0
	v_fma_f32 v83, v84, s93, 0.5
	v_fma_f32 v83, -v84, v83, 1.0
	v_mul_f32_e32 v83, v84, v83
	v_cmp_ngt_f32_e32 vcc, s94, v84
	s_and_saveexec_b64 s[58:59], vcc
	s_cbranch_execz .LBB0_929
	v_add_f32_e32 v83, 1.0, v84
	v_cmp_gt_f32_e32 vcc, s95, v83
	s_nop 1
	v_cndmask_b32_e64 v84, 0, 32, vcc
	v_ldexp_f32 v83, v83, v84
	v_log_f32_e32 v83, v83
	s_nop 0
	v_mul_f32_e32 v84, 0x3f317217, v83
	v_fma_f32 v84, v83, s96, -v84
	v_fmac_f32_e32 v84, 0x3377d1cf, v83
	v_fmac_f32_e32 v84, 0x3f317217, v83
	v_cmp_lt_f32_e64 s[16:17], |v83|, s97
	s_nop 1
	v_cndmask_b32_e64 v83, v83, v84, s[16:17]
	v_cndmask_b32_e32 v84, 0, v194, vcc
	v_sub_f32_e32 v83, v83, v84

; __device__ __forceinline__ float softplusf_(float x) { const float e = __expf(x); const float sm = e * (1.f - e * (0.5f - e * 0.33333334f)); return x > 20.f ? x : (e < 0.01f ? sm : __logf(1.f + e)); }
;     __device__ __forceinline__ void operator()(AccT acc, const Unit& u, int wr, int wc, int fr, int fq) const {
;     ...
;                     *(f32x4*)d = (f32x4){softplusf_(v0[0] + bb[0]), softplusf_(v0[1] + bb[1]), softplusf_(v0[2] + bb[2]), softplusf_(v0[3] + bb[3])};
.LBB0_930:
	s_or_b64 exec, exec, s[20:21]
	s_nop 1
	v_mov_b32_e32 v84, v246
	v_add_f32_e32 v84, v80, v84
	v_cmp_nlt_f32_e32 vcc, s92, v84
	s_and_saveexec_b64 s[20:21], vcc
	s_cbranch_execz .LBB0_934
	v_mul_f32_e32 v84, 0x3fb8aa3b, v84
	v_exp_f32_e32 v85, v84
	s_nop 0
	v_fma_f32 v84, v85, s93, 0.5
	v_fma_f32 v84, -v85, v84, 1.0
	v_mul_f32_e32 v84, v85, v84
	v_cmp_ngt_f32_e32 vcc, s94, v85
	s_and_saveexec_b64 s[58:59], vcc
	s_cbranch_execz .LBB0_933
	v_add_f32_e32 v84, 1.0, v85
	v_cmp_gt_f32_e32 vcc, s95, v84
	s_nop 1
	v_cndmask_b32_e64 v85, 0, 32, vcc
	v_ldexp_f32 v84, v84, v85
	v_log_f32_e32 v84, v84
	s_nop 0
	v_mul_f32_e32 v85, 0x3f317217, v84
	v_fma_f32 v85, v84, s96, -v85
	v_fmac_f32_e32 v85, 0x3377d1cf, v84
	v_fmac_f32_e32 v85, 0x3f317217, v84
	v_cmp_lt_f32_e64 s[16:17], |v84|, s97
	s_nop 1
	v_cndmask_b32_e64 v84, v84, v85, s[16:17]
	v_cndmask_b32_e32 v85, 0, v194, vcc
	v_sub_f32_e32 v84, v84, v85

; __device__ __forceinline__ float softplusf_(float x) { const float e = __expf(x); const float sm = e * (1.f - e * (0.5f - e * 0.33333334f)); return x > 20.f ? x : (e < 0.01f ? sm : __logf(1.f + e)); }
;     __device__ __forceinline__ void operator()(AccT acc, const Unit& u, int wr, int wc, int fr, int fq) const {
;     ...
;                     *(f32x4*)d = (f32x4){softplusf_(v0[0] + bb[0]), softplusf_(v0[1] + bb[1]), softplusf_(v0[2] + bb[2]), softplusf_(v0[3] + bb[3])};
.LBB0_934:
	s_or_b64 exec, exec, s[20:21]
	s_nop 1
	v_mov_b32_e32 v85, v247
	v_add_f32_e32 v85, v81, v85
	v_cmp_nlt_f32_e32 vcc, s92, v85
	s_and_saveexec_b64 s[20:21], vcc
	s_cbranch_execz .LBB0_938
	v_mul_f32_e32 v85, 0x3fb8aa3b, v85
	v_exp_f32_e32 v89, v85
	s_nop 0
	v_fma_f32 v85, v89, s93, 0.5
	v_fma_f32 v85, -v89, v85, 1.0
	v_mul_f32_e32 v85, v89, v85
	v_cmp_ngt_f32_e32 vcc, s94, v89
	s_and_saveexec_b64 s[58:59], vcc
	s_cbranch_execz .LBB0_937
	v_add_f32_e32 v85, 1.0, v89
	v_cmp_gt_f32_e32 vcc, s95, v85
	s_nop 1
	v_cndmask_b32_e64 v89, 0, 32, vcc
	v_ldexp_f32 v85, v85, v89
	v_log_f32_e32 v85, v85
	s_nop 0
	v_mul_f32_e32 v89, 0x3f317217, v85
	v_fma_f32 v89, v85, s96, -v89
	v_fmac_f32_e32 v89, 0x3377d1cf, v85
	v_fmac_f32_e32 v89, 0x3f317217, v85
	v_cmp_lt_f32_e64 s[16:17], |v85|, s97
	s_nop 1
	v_cndmask_b32_e64 v85, v85, v89, s[16:17]
	v_cndmask_b32_e32 v89, 0, v194, vcc
	v_sub_f32_e32 v85, v85, v89

; __device__ __forceinline__ float softplusf_(float x) { const float e = __expf(x); const float sm = e * (1.f - e * (0.5f - e * 0.33333334f)); return x > 20.f ? x : (e < 0.01f ? sm : __logf(1.f + e)); }
;     __device__ __forceinline__ void operator()(AccT acc, const Unit& u, int wr, int wc, int fr, int fq) const {
;     ...
;                     *(f32x4*)d = (f32x4){softplusf_(v0[0] + bb[0]), softplusf_(v0[1] + bb[1]), softplusf_(v0[2] + bb[2]), softplusf_(v0[3] + bb[3])};
;                     *(f32x4*)(d + 4) = (f32x4){softplusf_(v1[0] + bb[4]), softplusf_(v1[1] + bb[5]), softplusf_(v1[2] + bb[6]), softplusf_(v1[3] + bb[7])};
.LBB0_938:
	s_or_b64 exec, exec, s[20:21]
	v_lshlrev_b64 v[92:93], 6, v[86:87]
	v_lshl_add_u64 v[92:93], v[162:163], 0, v[92:93]
	global_store_dwordx4 v[92:93], v[82:85], off
	s_nop 1
	v_mov_b32_e32 v82, v248
	v_add_f32_e32 v82, v74, v82
	v_cmp_nlt_f32_e32 vcc, s92, v82
	s_and_saveexec_b64 s[20:21], vcc
	s_cbranch_execz .LBB0_942
	v_mul_f32_e32 v82, 0x3fb8aa3b, v82
	v_exp_f32_e32 v83, v82
	s_nop 0
	v_fma_f32 v82, v83, s93, 0.5
	v_fma_f32 v82, -v83, v82, 1.0
	v_mul_f32_e32 v82, v83, v82
	v_cmp_ngt_f32_e32 vcc, s94, v83
	s_and_saveexec_b64 s[58:59], vcc
	s_cbranch_execz .LBB0_941
	v_add_f32_e32 v82, 1.0, v83
	v_cmp_gt_f32_e32 vcc, s95, v82
	s_nop 1
	v_cndmask_b32_e64 v83, 0, 32, vcc
	v_ldexp_f32 v82, v82, v83
	v_log_f32_e32 v82, v82
	s_nop 0
	v_mul_f32_e32 v83, 0x3f317217, v82
	v_fma_f32 v83, v82, s96, -v83
	v_fmac_f32_e32 v83, 0x3377d1cf, v82
	v_fmac_f32_e32 v83, 0x3f317217, v82
	v_cmp_lt_f32_e64 s[16:17], |v82|, s97
	s_nop 1
	v_cndmask_b32_e64 v82, v82, v83, s[16:17]
	v_cndmask_b32_e32 v83, 0, v194, vcc
	v_sub_f32_e32 v82, v82, v83

; __device__ __forceinline__ float softplusf_(float x) { const float e = __expf(x); const float sm = e * (1.f - e * (0.5f - e * 0.33333334f)); return x > 20.f ? x : (e < 0.01f ? sm : __logf(1.f + e)); }
;     __device__ __forceinline__ void operator()(AccT acc, const Unit& u, int wr, int wc, int fr, int fq) const {
;     ...
;                     *(f32x4*)(d + 4) = (f32x4){softplusf_(v1[0] + bb[4]), softplusf_(v1[1] + bb[5]), softplusf_(v1[2] + bb[6]), softplusf_(v1[3] + bb[7])};
.LBB0_942:
	s_or_b64 exec, exec, s[20:21]
	s_nop 1
	v_mov_b32_e32 v83, v249
	v_add_f32_e32 v83, v75, v83
	v_cmp_nlt_f32_e32 vcc, s92, v83
	s_and_saveexec_b64 s[20:21], vcc
	s_cbranch_execz .LBB0_946
	v_mul_f32_e32 v83, 0x3fb8aa3b, v83
	v_exp_f32_e32 v84, v83
	s_nop 0
	v_fma_f32 v83, v84, s93, 0.5
	v_fma_f32 v83, -v84, v83, 1.0
	v_mul_f32_e32 v83, v84, v83
	v_cmp_ngt_f32_e32 vcc, s94, v84
	s_and_saveexec_b64 s[58:59], vcc
	s_cbranch_execz .LBB0_945
	v_add_f32_e32 v83, 1.0, v84
	v_cmp_gt_f32_e32 vcc, s95, v83
	s_nop 1
	v_cndmask_b32_e64 v84, 0, 32, vcc
	v_ldexp_f32 v83, v83, v84
	v_log_f32_e32 v83, v83
	s_nop 0
	v_mul_f32_e32 v84, 0x3f317217, v83
	v_fma_f32 v84, v83, s96, -v84
	v_fmac_f32_e32 v84, 0x3377d1cf, v83
	v_fmac_f32_e32 v84, 0x3f317217, v83
	v_cmp_lt_f32_e64 s[16:17], |v83|, s97
	s_nop 1
	v_cndmask_b32_e64 v83, v83, v84, s[16:17]
	v_cndmask_b32_e32 v84, 0, v194, vcc
	v_sub_f32_e32 v83, v83, v84

; __device__ __forceinline__ float softplusf_(float x) { const float e = __expf(x); const float sm = e * (1.f - e * (0.5f - e * 0.33333334f)); return x > 20.f ? x : (e < 0.01f ? sm : __logf(1.f + e)); }
;     __device__ __forceinline__ void operator()(AccT acc, const Unit& u, int wr, int wc, int fr, int fq) const {
;     ...
;                     *(f32x4*)(d + 4) = (f32x4){softplusf_(v1[0] + bb[4]), softplusf_(v1[1] + bb[5]), softplusf_(v1[2] + bb[6]), softplusf_(v1[3] + bb[7])};
.LBB0_946:
	s_or_b64 exec, exec, s[20:21]
	s_nop 1
	v_mov_b32_e32 v84, v250
	v_add_f32_e32 v84, v76, v84
	v_cmp_nlt_f32_e32 vcc, s92, v84
	s_and_saveexec_b64 s[20:21], vcc
	s_cbranch_execz .LBB0_950
	v_mul_f32_e32 v84, 0x3fb8aa3b, v84
	v_exp_f32_e32 v85, v84
	s_nop 0
	v_fma_f32 v84, v85, s93, 0.5
	v_fma_f32 v84, -v85, v84, 1.0
	v_mul_f32_e32 v84, v85, v84
	v_cmp_ngt_f32_e32 vcc, s94, v85
	s_and_saveexec_b64 s[58:59], vcc
	s_cbranch_execz .LBB0_949
	v_add_f32_e32 v84, 1.0, v85
	v_cmp_gt_f32_e32 vcc, s95, v84
	s_nop 1
	v_cndmask_b32_e64 v85, 0, 32, vcc
	v_ldexp_f32 v84, v84, v85
	v_log_f32_e32 v84, v84
	s_nop 0
	v_mul_f32_e32 v85, 0x3f317217, v84
	v_fma_f32 v85, v84, s96, -v85
	v_fmac_f32_e32 v85, 0x3377d1cf, v84
	v_fmac_f32_e32 v85, 0x3f317217, v84
	v_cmp_lt_f32_e64 s[16:17], |v84|, s97
	s_nop 1
	v_cndmask_b32_e64 v84, v84, v85, s[16:17]
	v_cndmask_b32_e32 v85, 0, v194, vcc
	v_sub_f32_e32 v84, v84, v85

; __device__ __forceinline__ float softplusf_(float x) { const float e = __expf(x); const float sm = e * (1.f - e * (0.5f - e * 0.33333334f)); return x > 20.f ? x : (e < 0.01f ? sm : __logf(1.f + e)); }
;     __device__ __forceinline__ void operator()(AccT acc, const Unit& u, int wr, int wc, int fr, int fq) const {
;     ...
;                     *(f32x4*)(d + 4) = (f32x4){softplusf_(v1[0] + bb[4]), softplusf_(v1[1] + bb[5]), softplusf_(v1[2] + bb[6]), softplusf_(v1[3] + bb[7])};
.LBB0_950:
	s_or_b64 exec, exec, s[20:21]
	s_nop 1
	v_mov_b32_e32 v85, v251
	v_add_f32_e32 v85, v77, v85
	v_cmp_nlt_f32_e32 vcc, s92, v85
	s_and_saveexec_b64 s[20:21], vcc
	s_cbranch_execz .LBB0_954
	v_mul_f32_e32 v85, 0x3fb8aa3b, v85
	v_exp_f32_e32 v89, v85
	s_nop 0
	v_fma_f32 v85, v89, s93, 0.5
	v_fma_f32 v85, -v89, v85, 1.0
	v_mul_f32_e32 v85, v89, v85
	v_cmp_ngt_f32_e32 vcc, s94, v89
	s_and_saveexec_b64 s[58:59], vcc
	s_cbranch_execz .LBB0_953
	v_add_f32_e32 v85, 1.0, v89
	v_cmp_gt_f32_e32 vcc, s95, v85
	s_nop 1
	v_cndmask_b32_e64 v89, 0, 32, vcc
	v_ldexp_f32 v85, v85, v89
	v_log_f32_e32 v85, v85
	s_nop 0
	v_mul_f32_e32 v89, 0x3f317217, v85
	v_fma_f32 v89, v85, s96, -v89
	v_fmac_f32_e32 v89, 0x3377d1cf, v85
	v_fmac_f32_e32 v89, 0x3f317217, v85
	v_cmp_lt_f32_e64 s[16:17], |v85|, s97
	s_nop 1
	v_cndmask_b32_e64 v85, v85, v89, s[16:17]
	v_cndmask_b32_e32 v89, 0, v194, vcc
	v_sub_f32_e32 v85, v85, v89

; __device__ __forceinline__ float softplusf_(float x) { const float e = __expf(x); const float sm = e * (1.f - e * (0.5f - e * 0.33333334f)); return x > 20.f ? x : (e < 0.01f ? sm : __logf(1.f + e)); }
;     __device__ __forceinline__ void operator()(AccT acc, const Unit& u, int wr, int wc, int fr, int fq) const {
;     ...
;             const float rs = rs8[ai * 4 + m];
;             const int sq = seq_of_row(row); const bool isS = row >= NPROMPT; const int t = isS ? ((row - NPROMPT) & 7) : (row & (SEQ - 1));
;             if (!uni) { const float* sw = SHW + (size_t)sq * NZT + col0;
; #pragma unroll
;                 for (int bj = 0; bj < 2; ++bj) { sh[bj][0] = *(const f32x4*)(sw + bj * HALF); sh[bj][1] = *(const f32x4*)(sw + bj * HALF + 4); }
;                 asm volatile("" :: "v"(sh[0][0]), "v"(sh[0][1]), "v"(sh[1][0]), "v"(sh[1][1])); }
; #pragma unroll
;             for (int bj = 0; bj < 2; ++bj) { const int c = col0 + bj * HALF;
;                 const f32x4 v0 = acc[ai][bj][m][0] * rs + sh[bj][0], v1 = acc[ai][bj][m][1] * rs + sh[bj][1];
;                 if (u.pn < 48) {
;     ...
;                 } else if (bj == 0 && wc == 0 && fq < 2) {
;                     float* d = DT + (size_t)row * 16 + 8 * fq; const float* bb = dtb + 8 * fq;
;                     *(f32x4*)d = (f32x4){softplusf_(v0[0] + bb[0]), softplusf_(v0[1] + bb[1]), softplusf_(v0[2] + bb[2]), softplusf_(v0[3] + bb[3])};
.LBB0_984:
	s_waitcnt lgkmcnt(2)
	v_add_f32_e32 v66, v216, v217
	v_fmamk_f32 v66, v66, 0x3a800000, v193
	v_rsq_f32_e32 v72, v66
	v_cmp_gt_i32_e64 s[12:13], s81, v74
	v_cmp_lt_i32_e64 s[14:15], s91, v74
	v_ashrrev_i32_e32 v75, 31, v74
	s_mov_b64 s[16:17], -1
	v_pk_fma_f32 v[64:65], v[64:65], v[72:73], v[40:41] op_sel_hi:[1,0,1]
	v_pk_fma_f32 v[62:63], v[62:63], v[72:73], v[38:39] op_sel_hi:[1,0,1]
	v_pk_fma_f32 v[60:61], v[60:61], v[72:73], v[36:37] op_sel_hi:[1,0,1]
	s_and_b64 vcc, exec, s[10:11]
	v_pk_fma_f32 v[58:59], v[58:59], v[72:73], v[34:35] op_sel_hi:[1,0,1]
	s_cbranch_vccnz .LBB0_1020
	s_and_saveexec_b64 s[18:19], s[38:39]
	s_cbranch_execz .LBB0_1019
	s_nop 1
	v_mov_b32_e32 v66, v244
	v_add_f32_e32 v66, v62, v66
	v_cmp_nlt_f32_e32 vcc, s92, v66
	s_and_saveexec_b64 s[20:21], vcc
	s_cbranch_execz .LBB0_990
	v_mul_f32_e32 v66, 0x3fb8aa3b, v66
	v_exp_f32_e32 v67, v66
	s_nop 0
	v_fma_f32 v66, v67, s93, 0.5
	v_fma_f32 v66, -v67, v66, 1.0
	v_mul_f32_e32 v66, v67, v66
	v_cmp_ngt_f32_e32 vcc, s94, v67
	s_and_saveexec_b64 s[58:59], vcc
	s_cbranch_execz .LBB0_989
	v_add_f32_e32 v66, 1.0, v67
	v_cmp_gt_f32_e32 vcc, s95, v66
	s_nop 1
	v_cndmask_b32_e64 v67, 0, 32, vcc
	v_ldexp_f32 v66, v66, v67
	v_log_f32_e32 v66, v66
	s_nop 0
	v_mul_f32_e32 v67, 0x3f317217, v66
	v_fma_f32 v67, v66, s96, -v67
	v_fmac_f32_e32 v67, 0x3377d1cf, v66
	v_fmac_f32_e32 v67, 0x3f317217, v66
	v_cmp_lt_f32_e64 s[16:17], |v66|, s97
	s_nop 1
	v_cndmask_b32_e64 v66, v66, v67, s[16:17]
	v_cndmask_b32_e32 v67, 0, v194, vcc
	v_sub_f32_e32 v66, v66, v67

; __device__ __forceinline__ float softplusf_(float x) { const float e = __expf(x); const float sm = e * (1.f - e * (0.5f - e * 0.33333334f)); return x > 20.f ? x : (e < 0.01f ? sm : __logf(1.f + e)); }
;     __device__ __forceinline__ void operator()(AccT acc, const Unit& u, int wr, int wc, int fr, int fq) const {
;     ...
;                     *(f32x4*)d = (f32x4){softplusf_(v0[0] + bb[0]), softplusf_(v0[1] + bb[1]), softplusf_(v0[2] + bb[2]), softplusf_(v0[3] + bb[3])};
.LBB0_990:
	s_or_b64 exec, exec, s[20:21]
	s_nop 1
	v_mov_b32_e32 v67, v245
	v_add_f32_e32 v67, v63, v67
	v_cmp_nlt_f32_e32 vcc, s92, v67
	s_and_saveexec_b64 s[20:21], vcc
	s_cbranch_execz .LBB0_994
	v_mul_f32_e32 v67, 0x3fb8aa3b, v67
	v_exp_f32_e32 v68, v67
	s_nop 0
	v_fma_f32 v67, v68, s93, 0.5
	v_fma_f32 v67, -v68, v67, 1.0
	v_mul_f32_e32 v67, v68, v67
	v_cmp_ngt_f32_e32 vcc, s94, v68
	s_and_saveexec_b64 s[58:59], vcc
	s_cbranch_execz .LBB0_993
	v_add_f32_e32 v67, 1.0, v68
	v_cmp_gt_f32_e32 vcc, s95, v67
	s_nop 1
	v_cndmask_b32_e64 v68, 0, 32, vcc
	v_ldexp_f32 v67, v67, v68
	v_log_f32_e32 v67, v67
	s_nop 0
	v_mul_f32_e32 v68, 0x3f317217, v67
	v_fma_f32 v68, v67, s96, -v68
	v_fmac_f32_e32 v68, 0x3377d1cf, v67
	v_fmac_f32_e32 v68, 0x3f317217, v67
	v_cmp_lt_f32_e64 s[16:17], |v67|, s97
	s_nop 1
	v_cndmask_b32_e64 v67, v67, v68, s[16:17]
	v_cndmask_b32_e32 v68, 0, v194, vcc
	v_sub_f32_e32 v67, v67, v68

; __device__ __forceinline__ float softplusf_(float x) { const float e = __expf(x); const float sm = e * (1.f - e * (0.5f - e * 0.33333334f)); return x > 20.f ? x : (e < 0.01f ? sm : __logf(1.f + e)); }
;     __device__ __forceinline__ void operator()(AccT acc, const Unit& u, int wr, int wc, int fr, int fq) const {
;     ...
;                     *(f32x4*)d = (f32x4){softplusf_(v0[0] + bb[0]), softplusf_(v0[1] + bb[1]), softplusf_(v0[2] + bb[2]), softplusf_(v0[3] + bb[3])};
.LBB0_994:
	s_or_b64 exec, exec, s[20:21]
	s_nop 1
	v_mov_b32_e32 v68, v246
	v_add_f32_e32 v68, v64, v68
	v_cmp_nlt_f32_e32 vcc, s92, v68
	s_and_saveexec_b64 s[20:21], vcc
	s_cbranch_execz .LBB0_998
	v_mul_f32_e32 v68, 0x3fb8aa3b, v68
	v_exp_f32_e32 v69, v68
	s_nop 0
	v_fma_f32 v68, v69, s93, 0.5
	v_fma_f32 v68, -v69, v68, 1.0
	v_mul_f32_e32 v68, v69, v68
	v_cmp_ngt_f32_e32 vcc, s94, v69
	s_and_saveexec_b64 s[58:59], vcc
	s_cbranch_execz .LBB0_997
	v_add_f32_e32 v68, 1.0, v69
	v_cmp_gt_f32_e32 vcc, s95, v68
	s_nop 1
	v_cndmask_b32_e64 v69, 0, 32, vcc
	v_ldexp_f32 v68, v68, v69
	v_log_f32_e32 v68, v68
	s_nop 0
	v_mul_f32_e32 v69, 0x3f317217, v68
	v_fma_f32 v69, v68, s96, -v69
	v_fmac_f32_e32 v69, 0x3377d1cf, v68
	v_fmac_f32_e32 v69, 0x3f317217, v68
	v_cmp_lt_f32_e64 s[16:17], |v68|, s97
	s_nop 1
	v_cndmask_b32_e64 v68, v68, v69, s[16:17]
	v_cndmask_b32_e32 v69, 0, v194, vcc
	v_sub_f32_e32 v68, v68, v69

; __device__ __forceinline__ float softplusf_(float x) { const float e = __expf(x); const float sm = e * (1.f - e * (0.5f - e * 0.33333334f)); return x > 20.f ? x : (e < 0.01f ? sm : __logf(1.f + e)); }
;     __device__ __forceinline__ void operator()(AccT acc, const Unit& u, int wr, int wc, int fr, int fq) const {
;     ...
;                     *(f32x4*)d = (f32x4){softplusf_(v0[0] + bb[0]), softplusf_(v0[1] + bb[1]), softplusf_(v0[2] + bb[2]), softplusf_(v0[3] + bb[3])};
.LBB0_998:
	s_or_b64 exec, exec, s[20:21]
	s_nop 1
	v_mov_b32_e32 v69, v247
	v_add_f32_e32 v69, v65, v69
	v_cmp_nlt_f32_e32 vcc, s92, v69
	s_and_saveexec_b64 s[20:21], vcc
	s_cbranch_execz .LBB0_1002
	v_mul_f32_e32 v69, 0x3fb8aa3b, v69
	v_exp_f32_e32 v71, v69
	s_nop 0
	v_fma_f32 v69, v71, s93, 0.5
	v_fma_f32 v69, -v71, v69, 1.0
	v_mul_f32_e32 v69, v71, v69
	v_cmp_ngt_f32_e32 vcc, s94, v71
	s_and_saveexec_b64 s[58:59], vcc
	s_cbranch_execz .LBB0_1001
	v_add_f32_e32 v69, 1.0, v71
	v_cmp_gt_f32_e32 vcc, s95, v69
	s_nop 1
	v_cndmask_b32_e64 v71, 0, 32, vcc
	v_ldexp_f32 v69, v69, v71
	v_log_f32_e32 v69, v69
	s_nop 0
	v_mul_f32_e32 v71, 0x3f317217, v69
	v_fma_f32 v71, v69, s96, -v71
	v_fmac_f32_e32 v71, 0x3377d1cf, v69
	v_fmac_f32_e32 v71, 0x3f317217, v69
	v_cmp_lt_f32_e64 s[16:17], |v69|, s97
	s_nop 1
	v_cndmask_b32_e64 v69, v69, v71, s[16:17]
	v_cndmask_b32_e32 v71, 0, v194, vcc
	v_sub_f32_e32 v69, v69, v71

; __device__ __forceinline__ float softplusf_(float x) { const float e = __expf(x); const float sm = e * (1.f - e * (0.5f - e * 0.33333334f)); return x > 20.f ? x : (e < 0.01f ? sm : __logf(1.f + e)); }
;     __device__ __forceinline__ void operator()(AccT acc, const Unit& u, int wr, int wc, int fr, int fq) const {
;     ...
;                     *(f32x4*)d = (f32x4){softplusf_(v0[0] + bb[0]), softplusf_(v0[1] + bb[1]), softplusf_(v0[2] + bb[2]), softplusf_(v0[3] + bb[3])};
;                     *(f32x4*)(d + 4) = (f32x4){softplusf_(v1[0] + bb[4]), softplusf_(v1[1] + bb[5]), softplusf_(v1[2] + bb[6]), softplusf_(v1[3] + bb[7])};
.LBB0_1002:
	s_or_b64 exec, exec, s[20:21]
	v_lshlrev_b64 v[76:77], 6, v[74:75]
	v_lshl_add_u64 v[76:77], v[162:163], 0, v[76:77]
	global_store_dwordx4 v[76:77], v[66:69], off
	s_nop 1
	v_mov_b32_e32 v66, v248
	v_add_f32_e32 v66, v58, v66
	v_cmp_nlt_f32_e32 vcc, s92, v66
	s_and_saveexec_b64 s[20:21], vcc
	s_cbranch_execz .LBB0_1006
	v_mul_f32_e32 v66, 0x3fb8aa3b, v66
	v_exp_f32_e32 v67, v66
	s_nop 0
	v_fma_f32 v66, v67, s93, 0.5
	v_fma_f32 v66, -v67, v66, 1.0
	v_mul_f32_e32 v66, v67, v66
	v_cmp_ngt_f32_e32 vcc, s94, v67
	s_and_saveexec_b64 s[58:59], vcc
	s_cbranch_execz .LBB0_1005
	v_add_f32_e32 v66, 1.0, v67
	v_cmp_gt_f32_e32 vcc, s95, v66
	s_nop 1
	v_cndmask_b32_e64 v67, 0, 32, vcc
	v_ldexp_f32 v66, v66, v67
	v_log_f32_e32 v66, v66
	s_nop 0
	v_mul_f32_e32 v67, 0x3f317217, v66
	v_fma_f32 v67, v66, s96, -v67
	v_fmac_f32_e32 v67, 0x3377d1cf, v66
	v_fmac_f32_e32 v67, 0x3f317217, v66
	v_cmp_lt_f32_e64 s[16:17], |v66|, s97
	s_nop 1
	v_cndmask_b32_e64 v66, v66, v67, s[16:17]
	v_cndmask_b32_e32 v67, 0, v194, vcc
	v_sub_f32_e32 v66, v66, v67

; __device__ __forceinline__ float softplusf_(float x) { const float e = __expf(x); const float sm = e * (1.f - e * (0.5f - e * 0.33333334f)); return x > 20.f ? x : (e < 0.01f ? sm : __logf(1.f + e)); }
;     __device__ __forceinline__ void operator()(AccT acc, const Unit& u, int wr, int wc, int fr, int fq) const {
;     ...
;                     *(f32x4*)(d + 4) = (f32x4){softplusf_(v1[0] + bb[4]), softplusf_(v1[1] + bb[5]), softplusf_(v1[2] + bb[6]), softplusf_(v1[3] + bb[7])};
.LBB0_1006:
	s_or_b64 exec, exec, s[20:21]
	s_nop 1
	v_mov_b32_e32 v67, v249
	v_add_f32_e32 v67, v59, v67
	v_cmp_nlt_f32_e32 vcc, s92, v67
	s_and_saveexec_b64 s[20:21], vcc
	s_cbranch_execz .LBB0_1010
	v_mul_f32_e32 v67, 0x3fb8aa3b, v67
	v_exp_f32_e32 v68, v67
	s_nop 0
	v_fma_f32 v67, v68, s93, 0.5
	v_fma_f32 v67, -v68, v67, 1.0
	v_mul_f32_e32 v67, v68, v67
	v_cmp_ngt_f32_e32 vcc, s94, v68
	s_and_saveexec_b64 s[58:59], vcc
	s_cbranch_execz .LBB0_1009
	v_add_f32_e32 v67, 1.0, v68
	v_cmp_gt_f32_e32 vcc, s95, v67
	s_nop 1
	v_cndmask_b32_e64 v68, 0, 32, vcc
	v_ldexp_f32 v67, v67, v68
	v_log_f32_e32 v67, v67
	s_nop 0
	v_mul_f32_e32 v68, 0x3f317217, v67
	v_fma_f32 v68, v67, s96, -v68
	v_fmac_f32_e32 v68, 0x3377d1cf, v67
	v_fmac_f32_e32 v68, 0x3f317217, v67
	v_cmp_lt_f32_e64 s[16:17], |v67|, s97
	s_nop 1
	v_cndmask_b32_e64 v67, v67, v68, s[16:17]
	v_cndmask_b32_e32 v68, 0, v194, vcc
	v_sub_f32_e32 v67, v67, v68

; __device__ __forceinline__ float softplusf_(float x) { const float e = __expf(x); const float sm = e * (1.f - e * (0.5f - e * 0.33333334f)); return x > 20.f ? x : (e < 0.01f ? sm : __logf(1.f + e)); }
;     __device__ __forceinline__ void operator()(AccT acc, const Unit& u, int wr, int wc, int fr, int fq) const {
;     ...
;                     *(f32x4*)(d + 4) = (f32x4){softplusf_(v1[0] + bb[4]), softplusf_(v1[1] + bb[5]), softplusf_(v1[2] + bb[6]), softplusf_(v1[3] + bb[7])};
.LBB0_1010:
	s_or_b64 exec, exec, s[20:21]
	s_nop 1
	v_mov_b32_e32 v68, v250
	v_add_f32_e32 v68, v60, v68
	v_cmp_nlt_f32_e32 vcc, s92, v68
	s_and_saveexec_b64 s[20:21], vcc
	s_cbranch_execz .LBB0_1014
	v_mul_f32_e32 v68, 0x3fb8aa3b, v68
	v_exp_f32_e32 v69, v68
	s_nop 0
	v_fma_f32 v68, v69, s93, 0.5
	v_fma_f32 v68, -v69, v68, 1.0
	v_mul_f32_e32 v68, v69, v68
	v_cmp_ngt_f32_e32 vcc, s94, v69
	s_and_saveexec_b64 s[58:59], vcc
	s_cbranch_execz .LBB0_1013
	v_add_f32_e32 v68, 1.0, v69
	v_cmp_gt_f32_e32 vcc, s95, v68
	s_nop 1
	v_cndmask_b32_e64 v69, 0, 32, vcc
	v_ldexp_f32 v68, v68, v69
	v_log_f32_e32 v68, v68
	s_nop 0
	v_mul_f32_e32 v69, 0x3f317217, v68
	v_fma_f32 v69, v68, s96, -v69
	v_fmac_f32_e32 v69, 0x3377d1cf, v68
	v_fmac_f32_e32 v69, 0x3f317217, v68
	v_cmp_lt_f32_e64 s[16:17], |v68|, s97
	s_nop 1
	v_cndmask_b32_e64 v68, v68, v69, s[16:17]
	v_cndmask_b32_e32 v69, 0, v194, vcc
	v_sub_f32_e32 v68, v68, v69

; __device__ __forceinline__ float softplusf_(float x) { const float e = __expf(x); const float sm = e * (1.f - e * (0.5f - e * 0.33333334f)); return x > 20.f ? x : (e < 0.01f ? sm : __logf(1.f + e)); }
;     __device__ __forceinline__ void operator()(AccT acc, const Unit& u, int wr, int wc, int fr, int fq) const {
;     ...
;                     *(f32x4*)(d + 4) = (f32x4){softplusf_(v1[0] + bb[4]), softplusf_(v1[1] + bb[5]), softplusf_(v1[2] + bb[6]), softplusf_(v1[3] + bb[7])};
.LBB0_1014:
	s_or_b64 exec, exec, s[20:21]
	s_nop 1
	v_mov_b32_e32 v69, v251
	v_add_f32_e32 v69, v61, v69
	v_cmp_nlt_f32_e32 vcc, s92, v69
	s_and_saveexec_b64 s[20:21], vcc
	s_cbranch_execz .LBB0_1018
	v_mul_f32_e32 v69, 0x3fb8aa3b, v69
	v_exp_f32_e32 v71, v69
	s_nop 0
	v_fma_f32 v69, v71, s93, 0.5
	v_fma_f32 v69, -v71, v69, 1.0
	v_mul_f32_e32 v69, v71, v69
	v_cmp_ngt_f32_e32 vcc, s94, v71
	s_and_saveexec_b64 s[58:59], vcc
	s_cbranch_execz .LBB0_1017
	v_add_f32_e32 v69, 1.0, v71
	v_cmp_gt_f32_e32 vcc, s95, v69
	s_nop 1
	v_cndmask_b32_e64 v71, 0, 32, vcc
	v_ldexp_f32 v69, v69, v71
	v_log_f32_e32 v69, v69
	s_nop 0
	v_mul_f32_e32 v71, 0x3f317217, v69
	v_fma_f32 v71, v69, s96, -v71
	v_fmac_f32_e32 v71, 0x3377d1cf, v69
	v_fmac_f32_e32 v71, 0x3f317217, v69
	v_cmp_lt_f32_e64 s[16:17], |v69|, s97
	s_nop 1
	v_cndmask_b32_e64 v69, v69, v71, s[16:17]
	v_cndmask_b32_e32 v71, 0, v194, vcc
	v_sub_f32_e32 v69, v69, v71

; __device__ __forceinline__ float softplusf_(float x) { const float e = __expf(x); const float sm = e * (1.f - e * (0.5f - e * 0.33333334f)); return x > 20.f ? x : (e < 0.01f ? sm : __logf(1.f + e)); }
;     __device__ __forceinline__ void operator()(AccT acc, const Unit& u, int wr, int wc, int fr, int fq) const {
;     ...
;             const float rs = rs8[ai * 4 + m];
;             const int sq = seq_of_row(row); const bool isS = row >= NPROMPT; const int t = isS ? ((row - NPROMPT) & 7) : (row & (SEQ - 1));
;             if (!uni) { const float* sw = SHW + (size_t)sq * NZT + col0;
; #pragma unroll
;                 for (int bj = 0; bj < 2; ++bj) { sh[bj][0] = *(const f32x4*)(sw + bj * HALF); sh[bj][1] = *(const f32x4*)(sw + bj * HALF + 4); }
;                 asm volatile("" :: "v"(sh[0][0]), "v"(sh[0][1]), "v"(sh[1][0]), "v"(sh[1][1])); }
; #pragma unroll
;             for (int bj = 0; bj < 2; ++bj) { const int c = col0 + bj * HALF;
;                 const f32x4 v0 = acc[ai][bj][m][0] * rs + sh[bj][0], v1 = acc[ai][bj][m][1] * rs + sh[bj][1];
;                 if (u.pn < 48) {
;     ...
;                 } else if (bj == 0 && wc == 0 && fq < 2) {
;                     float* d = DT + (size_t)row * 16 + 8 * fq; const float* bb = dtb + 8 * fq;
;                     *(f32x4*)d = (f32x4){softplusf_(v0[0] + bb[0]), softplusf_(v0[1] + bb[1]), softplusf_(v0[2] + bb[2]), softplusf_(v0[3] + bb[3])};
.LBB0_1048:
	s_waitcnt lgkmcnt(1)
	v_add_f32_e32 v50, v214, v215
	v_fmamk_f32 v50, v50, 0x3a800000, v193
	v_rsq_f32_e32 v56, v50
	v_cmp_gt_i32_e64 s[12:13], s81, v58
	v_cmp_lt_i32_e64 s[14:15], s91, v58
	v_ashrrev_i32_e32 v59, 31, v58
	s_mov_b64 s[16:17], -1
	v_pk_fma_f32 v[48:49], v[48:49], v[56:57], v[40:41] op_sel_hi:[1,0,1]
	v_pk_fma_f32 v[46:47], v[46:47], v[56:57], v[38:39] op_sel_hi:[1,0,1]
	v_pk_fma_f32 v[44:45], v[44:45], v[56:57], v[36:37] op_sel_hi:[1,0,1]
	s_and_b64 vcc, exec, s[10:11]
	v_pk_fma_f32 v[42:43], v[42:43], v[56:57], v[34:35] op_sel_hi:[1,0,1]
	s_cbranch_vccnz .LBB0_1084
	s_and_saveexec_b64 s[18:19], s[38:39]
	s_cbranch_execz .LBB0_1083
	s_nop 1
	v_mov_b32_e32 v50, v244
	v_add_f32_e32 v50, v46, v50
	v_cmp_nlt_f32_e32 vcc, s92, v50
	s_and_saveexec_b64 s[20:21], vcc
	s_cbranch_execz .LBB0_1054
	v_mul_f32_e32 v50, 0x3fb8aa3b, v50
	v_exp_f32_e32 v51, v50
	s_nop 0
	v_fma_f32 v50, v51, s93, 0.5
	v_fma_f32 v50, -v51, v50, 1.0
	v_mul_f32_e32 v50, v51, v50
	v_cmp_ngt_f32_e32 vcc, s94, v51
	s_and_saveexec_b64 s[58:59], vcc
	s_cbranch_execz .LBB0_1053
	v_add_f32_e32 v50, 1.0, v51
	v_cmp_gt_f32_e32 vcc, s95, v50
	s_nop 1
	v_cndmask_b32_e64 v51, 0, 32, vcc
	v_ldexp_f32 v50, v50, v51
	v_log_f32_e32 v50, v50
	s_nop 0
	v_mul_f32_e32 v51, 0x3f317217, v50
	v_fma_f32 v51, v50, s96, -v51
	v_fmac_f32_e32 v51, 0x3377d1cf, v50
	v_fmac_f32_e32 v51, 0x3f317217, v50
	v_cmp_lt_f32_e64 s[16:17], |v50|, s97
	s_nop 1
	v_cndmask_b32_e64 v50, v50, v51, s[16:17]
	v_cndmask_b32_e32 v51, 0, v194, vcc
	v_sub_f32_e32 v50, v50, v51

; __device__ __forceinline__ float softplusf_(float x) { const float e = __expf(x); const float sm = e * (1.f - e * (0.5f - e * 0.33333334f)); return x > 20.f ? x : (e < 0.01f ? sm : __logf(1.f + e)); }
;     __device__ __forceinline__ void operator()(AccT acc, const Unit& u, int wr, int wc, int fr, int fq) const {
;     ...
;                     *(f32x4*)d = (f32x4){softplusf_(v0[0] + bb[0]), softplusf_(v0[1] + bb[1]), softplusf_(v0[2] + bb[2]), softplusf_(v0[3] + bb[3])};
.LBB0_1054:
	s_or_b64 exec, exec, s[20:21]
	s_nop 1
	v_mov_b32_e32 v51, v245
	v_add_f32_e32 v51, v47, v51
	v_cmp_nlt_f32_e32 vcc, s92, v51
	s_and_saveexec_b64 s[20:21], vcc
	s_cbranch_execz .LBB0_1058
	v_mul_f32_e32 v51, 0x3fb8aa3b, v51
	v_exp_f32_e32 v52, v51
	s_nop 0
	v_fma_f32 v51, v52, s93, 0.5
	v_fma_f32 v51, -v52, v51, 1.0
	v_mul_f32_e32 v51, v52, v51
	v_cmp_ngt_f32_e32 vcc, s94, v52
	s_and_saveexec_b64 s[58:59], vcc
	s_cbranch_execz .LBB0_1057
	v_add_f32_e32 v51, 1.0, v52
	v_cmp_gt_f32_e32 vcc, s95, v51
	s_nop 1
	v_cndmask_b32_e64 v52, 0, 32, vcc
	v_ldexp_f32 v51, v51, v52
	v_log_f32_e32 v51, v51
	s_nop 0
	v_mul_f32_e32 v52, 0x3f317217, v51
	v_fma_f32 v52, v51, s96, -v52
	v_fmac_f32_e32 v52, 0x3377d1cf, v51
	v_fmac_f32_e32 v52, 0x3f317217, v51
	v_cmp_lt_f32_e64 s[16:17], |v51|, s97
	s_nop 1
	v_cndmask_b32_e64 v51, v51, v52, s[16:17]
	v_cndmask_b32_e32 v52, 0, v194, vcc
	v_sub_f32_e32 v51, v51, v52

; __device__ __forceinline__ float softplusf_(float x) { const float e = __expf(x); const float sm = e * (1.f - e * (0.5f - e * 0.33333334f)); return x > 20.f ? x : (e < 0.01f ? sm : __logf(1.f + e)); }
;     __device__ __forceinline__ void operator()(AccT acc, const Unit& u, int wr, int wc, int fr, int fq) const {
;     ...
;                     *(f32x4*)d = (f32x4){softplusf_(v0[0] + bb[0]), softplusf_(v0[1] + bb[1]), softplusf_(v0[2] + bb[2]), softplusf_(v0[3] + bb[3])};
.LBB0_1058:
	s_or_b64 exec, exec, s[20:21]
	s_nop 1
	v_mov_b32_e32 v52, v246
	v_add_f32_e32 v52, v48, v52
	v_cmp_nlt_f32_e32 vcc, s92, v52
	s_and_saveexec_b64 s[20:21], vcc
	s_cbranch_execz .LBB0_1062
	v_mul_f32_e32 v52, 0x3fb8aa3b, v52
	v_exp_f32_e32 v53, v52
	s_nop 0
	v_fma_f32 v52, v53, s93, 0.5
	v_fma_f32 v52, -v53, v52, 1.0
	v_mul_f32_e32 v52, v53, v52
	v_cmp_ngt_f32_e32 vcc, s94, v53
	s_and_saveexec_b64 s[58:59], vcc
	s_cbranch_execz .LBB0_1061
	v_add_f32_e32 v52, 1.0, v53
	v_cmp_gt_f32_e32 vcc, s95, v52
	s_nop 1
	v_cndmask_b32_e64 v53, 0, 32, vcc
	v_ldexp_f32 v52, v52, v53
	v_log_f32_e32 v52, v52
	s_nop 0
	v_mul_f32_e32 v53, 0x3f317217, v52
	v_fma_f32 v53, v52, s96, -v53
	v_fmac_f32_e32 v53, 0x3377d1cf, v52
	v_fmac_f32_e32 v53, 0x3f317217, v52
	v_cmp_lt_f32_e64 s[16:17], |v52|, s97
	s_nop 1
	v_cndmask_b32_e64 v52, v52, v53, s[16:17]
	v_cndmask_b32_e32 v53, 0, v194, vcc
	v_sub_f32_e32 v52, v52, v53

; __device__ __forceinline__ float softplusf_(float x) { const float e = __expf(x); const float sm = e * (1.f - e * (0.5f - e * 0.33333334f)); return x > 20.f ? x : (e < 0.01f ? sm : __logf(1.f + e)); }
;     __device__ __forceinline__ void operator()(AccT acc, const Unit& u, int wr, int wc, int fr, int fq) const {
;     ...
;                     *(f32x4*)d = (f32x4){softplusf_(v0[0] + bb[0]), softplusf_(v0[1] + bb[1]), softplusf_(v0[2] + bb[2]), softplusf_(v0[3] + bb[3])};
.LBB0_1062:
	s_or_b64 exec, exec, s[20:21]
	s_nop 1
	v_mov_b32_e32 v53, v247
	v_add_f32_e32 v53, v49, v53
	v_cmp_nlt_f32_e32 vcc, s92, v53
	s_and_saveexec_b64 s[20:21], vcc
	s_cbranch_execz .LBB0_1066
	v_mul_f32_e32 v53, 0x3fb8aa3b, v53
	v_exp_f32_e32 v55, v53
	s_nop 0
	v_fma_f32 v53, v55, s93, 0.5
	v_fma_f32 v53, -v55, v53, 1.0
	v_mul_f32_e32 v53, v55, v53
	v_cmp_ngt_f32_e32 vcc, s94, v55
	s_and_saveexec_b64 s[58:59], vcc
	s_cbranch_execz .LBB0_1065
	v_add_f32_e32 v53, 1.0, v55
	v_cmp_gt_f32_e32 vcc, s95, v53
	s_nop 1
	v_cndmask_b32_e64 v55, 0, 32, vcc
	v_ldexp_f32 v53, v53, v55
	v_log_f32_e32 v53, v53
	s_nop 0
	v_mul_f32_e32 v55, 0x3f317217, v53
	v_fma_f32 v55, v53, s96, -v55
	v_fmac_f32_e32 v55, 0x3377d1cf, v53
	v_fmac_f32_e32 v55, 0x3f317217, v53
	v_cmp_lt_f32_e64 s[16:17], |v53|, s97
	s_nop 1
	v_cndmask_b32_e64 v53, v53, v55, s[16:17]
	v_cndmask_b32_e32 v55, 0, v194, vcc
	v_sub_f32_e32 v53, v53, v55

; __device__ __forceinline__ float softplusf_(float x) { const float e = __expf(x); const float sm = e * (1.f - e * (0.5f - e * 0.33333334f)); return x > 20.f ? x : (e < 0.01f ? sm : __logf(1.f + e)); }
;     __device__ __forceinline__ void operator()(AccT acc, const Unit& u, int wr, int wc, int fr, int fq) const {
;     ...
;                     *(f32x4*)d = (f32x4){softplusf_(v0[0] + bb[0]), softplusf_(v0[1] + bb[1]), softplusf_(v0[2] + bb[2]), softplusf_(v0[3] + bb[3])};
;                     *(f32x4*)(d + 4) = (f32x4){softplusf_(v1[0] + bb[4]), softplusf_(v1[1] + bb[5]), softplusf_(v1[2] + bb[6]), softplusf_(v1[3] + bb[7])};
.LBB0_1066:
	s_or_b64 exec, exec, s[20:21]
	v_lshlrev_b64 v[60:61], 6, v[58:59]
	v_lshl_add_u64 v[60:61], v[162:163], 0, v[60:61]
	global_store_dwordx4 v[60:61], v[50:53], off
	s_nop 1
	v_mov_b32_e32 v50, v248
	v_add_f32_e32 v50, v42, v50
	v_cmp_nlt_f32_e32 vcc, s92, v50
	s_and_saveexec_b64 s[20:21], vcc
	s_cbranch_execz .LBB0_1070
	v_mul_f32_e32 v50, 0x3fb8aa3b, v50
	v_exp_f32_e32 v51, v50
	s_nop 0
	v_fma_f32 v50, v51, s93, 0.5
	v_fma_f32 v50, -v51, v50, 1.0
	v_mul_f32_e32 v50, v51, v50
	v_cmp_ngt_f32_e32 vcc, s94, v51
	s_and_saveexec_b64 s[58:59], vcc
	s_cbranch_execz .LBB0_1069
	v_add_f32_e32 v50, 1.0, v51
	v_cmp_gt_f32_e32 vcc, s95, v50
	s_nop 1
	v_cndmask_b32_e64 v51, 0, 32, vcc
	v_ldexp_f32 v50, v50, v51
	v_log_f32_e32 v50, v50
	s_nop 0
	v_mul_f32_e32 v51, 0x3f317217, v50
	v_fma_f32 v51, v50, s96, -v51
	v_fmac_f32_e32 v51, 0x3377d1cf, v50
	v_fmac_f32_e32 v51, 0x3f317217, v50
	v_cmp_lt_f32_e64 s[16:17], |v50|, s97
	s_nop 1
	v_cndmask_b32_e64 v50, v50, v51, s[16:17]
	v_cndmask_b32_e32 v51, 0, v194, vcc
	v_sub_f32_e32 v50, v50, v51

; __device__ __forceinline__ float softplusf_(float x) { const float e = __expf(x); const float sm = e * (1.f - e * (0.5f - e * 0.33333334f)); return x > 20.f ? x : (e < 0.01f ? sm : __logf(1.f + e)); }
;     __device__ __forceinline__ void operator()(AccT acc, const Unit& u, int wr, int wc, int fr, int fq) const {
;     ...
;                     *(f32x4*)(d + 4) = (f32x4){softplusf_(v1[0] + bb[4]), softplusf_(v1[1] + bb[5]), softplusf_(v1[2] + bb[6]), softplusf_(v1[3] + bb[7])};
.LBB0_1070:
	s_or_b64 exec, exec, s[20:21]
	s_nop 1
	v_mov_b32_e32 v51, v249
	v_add_f32_e32 v51, v43, v51
	v_cmp_nlt_f32_e32 vcc, s92, v51
	s_and_saveexec_b64 s[20:21], vcc
	s_cbranch_execz .LBB0_1074
	v_mul_f32_e32 v51, 0x3fb8aa3b, v51
	v_exp_f32_e32 v52, v51
	s_nop 0
	v_fma_f32 v51, v52, s93, 0.5
	v_fma_f32 v51, -v52, v51, 1.0
	v_mul_f32_e32 v51, v52, v51
	v_cmp_ngt_f32_e32 vcc, s94, v52
	s_and_saveexec_b64 s[58:59], vcc
	s_cbranch_execz .LBB0_1073
	v_add_f32_e32 v51, 1.0, v52
	v_cmp_gt_f32_e32 vcc, s95, v51
	s_nop 1
	v_cndmask_b32_e64 v52, 0, 32, vcc
	v_ldexp_f32 v51, v51, v52
	v_log_f32_e32 v51, v51
	s_nop 0
	v_mul_f32_e32 v52, 0x3f317217, v51
	v_fma_f32 v52, v51, s96, -v52
	v_fmac_f32_e32 v52, 0x3377d1cf, v51
	v_fmac_f32_e32 v52, 0x3f317217, v51
	v_cmp_lt_f32_e64 s[16:17], |v51|, s97
	s_nop 1
	v_cndmask_b32_e64 v51, v51, v52, s[16:17]
	v_cndmask_b32_e32 v52, 0, v194, vcc
	v_sub_f32_e32 v51, v51, v52

; __device__ __forceinline__ float softplusf_(float x) { const float e = __expf(x); const float sm = e * (1.f - e * (0.5f - e * 0.33333334f)); return x > 20.f ? x : (e < 0.01f ? sm : __logf(1.f + e)); }
;     __device__ __forceinline__ void operator()(AccT acc, const Unit& u, int wr, int wc, int fr, int fq) const {
;     ...
;                     *(f32x4*)(d + 4) = (f32x4){softplusf_(v1[0] + bb[4]), softplusf_(v1[1] + bb[5]), softplusf_(v1[2] + bb[6]), softplusf_(v1[3] + bb[7])};
.LBB0_1074:
	s_or_b64 exec, exec, s[20:21]
	s_nop 1
	v_mov_b32_e32 v52, v250
	v_add_f32_e32 v52, v44, v52
	v_cmp_nlt_f32_e32 vcc, s92, v52
	s_and_saveexec_b64 s[20:21], vcc
	s_cbranch_execz .LBB0_1078
	v_mul_f32_e32 v52, 0x3fb8aa3b, v52
	v_exp_f32_e32 v53, v52
	s_nop 0
	v_fma_f32 v52, v53, s93, 0.5
	v_fma_f32 v52, -v53, v52, 1.0
	v_mul_f32_e32 v52, v53, v52
	v_cmp_ngt_f32_e32 vcc, s94, v53
	s_and_saveexec_b64 s[58:59], vcc
	s_cbranch_execz .LBB0_1077
	v_add_f32_e32 v52, 1.0, v53
	v_cmp_gt_f32_e32 vcc, s95, v52
	s_nop 1
	v_cndmask_b32_e64 v53, 0, 32, vcc
	v_ldexp_f32 v52, v52, v53
	v_log_f32_e32 v52, v52
	s_nop 0
	v_mul_f32_e32 v53, 0x3f317217, v52
	v_fma_f32 v53, v52, s96, -v53
	v_fmac_f32_e32 v53, 0x3377d1cf, v52
	v_fmac_f32_e32 v53, 0x3f317217, v52
	v_cmp_lt_f32_e64 s[16:17], |v52|, s97
	s_nop 1
	v_cndmask_b32_e64 v52, v52, v53, s[16:17]
	v_cndmask_b32_e32 v53, 0, v194, vcc
	v_sub_f32_e32 v52, v52, v53

; __device__ __forceinline__ float softplusf_(float x) { const float e = __expf(x); const float sm = e * (1.f - e * (0.5f - e * 0.33333334f)); return x > 20.f ? x : (e < 0.01f ? sm : __logf(1.f + e)); }
;     __device__ __forceinline__ void operator()(AccT acc, const Unit& u, int wr, int wc, int fr, int fq) const {
;     ...
;                     *(f32x4*)(d + 4) = (f32x4){softplusf_(v1[0] + bb[4]), softplusf_(v1[1] + bb[5]), softplusf_(v1[2] + bb[6]), softplusf_(v1[3] + bb[7])};
.LBB0_1078:
	s_or_b64 exec, exec, s[20:21]
	s_nop 1
	v_mov_b32_e32 v53, v251
	v_add_f32_e32 v53, v45, v53
	v_cmp_nlt_f32_e32 vcc, s92, v53
	s_and_saveexec_b64 s[20:21], vcc
	s_cbranch_execz .LBB0_1082
	v_mul_f32_e32 v53, 0x3fb8aa3b, v53
	v_exp_f32_e32 v55, v53
	s_nop 0
	v_fma_f32 v53, v55, s93, 0.5
	v_fma_f32 v53, -v55, v53, 1.0
	v_mul_f32_e32 v53, v55, v53
	v_cmp_ngt_f32_e32 vcc, s94, v55
	s_and_saveexec_b64 s[58:59], vcc
	s_cbranch_execz .LBB0_1081
	v_add_f32_e32 v53, 1.0, v55
	v_cmp_gt_f32_e32 vcc, s95, v53
	s_nop 1
	v_cndmask_b32_e64 v55, 0, 32, vcc
	v_ldexp_f32 v53, v53, v55
	v_log_f32_e32 v53, v53
	s_nop 0
	v_mul_f32_e32 v55, 0x3f317217, v53
	v_fma_f32 v55, v53, s96, -v55
	v_fmac_f32_e32 v55, 0x3377d1cf, v53
	v_fmac_f32_e32 v55, 0x3f317217, v53
	v_cmp_lt_f32_e64 s[16:17], |v53|, s97
	s_nop 1
	v_cndmask_b32_e64 v53, v53, v55, s[16:17]
	v_cndmask_b32_e32 v55, 0, v194, vcc
	v_sub_f32_e32 v53, v53, v55

; __device__ __forceinline__ float softplusf_(float x) { const float e = __expf(x); const float sm = e * (1.f - e * (0.5f - e * 0.33333334f)); return x > 20.f ? x : (e < 0.01f ? sm : __logf(1.f + e)); }
;     __device__ __forceinline__ void operator()(AccT acc, const Unit& u, int wr, int wc, int fr, int fq) const {
;     ...
;             const float rs = rs8[ai * 4 + m];
;             const int sq = seq_of_row(row); const bool isS = row >= NPROMPT; const int t = isS ? ((row - NPROMPT) & 7) : (row & (SEQ - 1));
;             if (!uni) { const float* sw = SHW + (size_t)sq * NZT + col0;
; #pragma unroll
;                 for (int bj = 0; bj < 2; ++bj) { sh[bj][0] = *(const f32x4*)(sw + bj * HALF); sh[bj][1] = *(const f32x4*)(sw + bj * HALF + 4); }
;                 asm volatile("" :: "v"(sh[0][0]), "v"(sh[0][1]), "v"(sh[1][0]), "v"(sh[1][1])); }
; #pragma unroll
;             for (int bj = 0; bj < 2; ++bj) { const int c = col0 + bj * HALF;
;                 const f32x4 v0 = acc[ai][bj][m][0] * rs + sh[bj][0], v1 = acc[ai][bj][m][1] * rs + sh[bj][1];
;                 if (u.pn < 48) {
;     ...
;                 } else if (bj == 0 && wc == 0 && fq < 2) {
;                     float* d = DT + (size_t)row * 16 + 8 * fq; const float* bb = dtb + 8 * fq;
;                     *(f32x4*)d = (f32x4){softplusf_(v0[0] + bb[0]), softplusf_(v0[1] + bb[1]), softplusf_(v0[2] + bb[2]), softplusf_(v0[3] + bb[3])};
.LBB0_1112:
	s_waitcnt lgkmcnt(0)
	v_add_f32_e32 v26, v212, v213
	v_fmamk_f32 v26, v26, 0x3a800000, v193
	v_rsq_f32_e32 v32, v26
	v_cmp_gt_i32_e64 s[6:7], s81, v42
	v_cmp_lt_i32_e64 s[12:13], s91, v42
	v_ashrrev_i32_e32 v43, 31, v42
	s_mov_b64 s[14:15], -1
	v_pk_fma_f32 v[24:25], v[24:25], v[32:33], v[40:41] op_sel_hi:[1,0,1]
	v_pk_fma_f32 v[22:23], v[22:23], v[32:33], v[38:39] op_sel_hi:[1,0,1]
	v_pk_fma_f32 v[20:21], v[20:21], v[32:33], v[36:37] op_sel_hi:[1,0,1]
	s_and_b64 vcc, exec, s[10:11]
	v_pk_fma_f32 v[18:19], v[18:19], v[32:33], v[34:35] op_sel_hi:[1,0,1]
	s_cbranch_vccnz .LBB0_1148
	s_and_saveexec_b64 s[14:15], s[38:39]
	s_cbranch_execz .LBB0_1147
	s_nop 1
	v_mov_b32_e32 v26, v244
	v_add_f32_e32 v26, v22, v26
	v_cmp_nlt_f32_e32 vcc, s92, v26
	s_and_saveexec_b64 s[16:17], vcc
	s_cbranch_execz .LBB0_1118
	v_mul_f32_e32 v26, 0x3fb8aa3b, v26
	v_exp_f32_e32 v27, v26
	s_nop 0
	v_fma_f32 v26, v27, s93, 0.5
	v_fma_f32 v26, -v27, v26, 1.0
	v_mul_f32_e32 v26, v27, v26
	v_cmp_ngt_f32_e32 vcc, s94, v27
	s_and_saveexec_b64 s[18:19], vcc
	s_cbranch_execz .LBB0_1117
	v_add_f32_e32 v26, 1.0, v27
	v_cmp_gt_f32_e32 vcc, s95, v26
	s_nop 1
	v_cndmask_b32_e64 v27, 0, 32, vcc
	v_ldexp_f32 v26, v26, v27
	v_log_f32_e32 v26, v26
	s_nop 0
	v_mul_f32_e32 v27, 0x3f317217, v26
	v_fma_f32 v27, v26, s96, -v27
	v_fmac_f32_e32 v27, 0x3377d1cf, v26
	v_fmac_f32_e32 v27, 0x3f317217, v26
	v_cmp_lt_f32_e64 s[10:11], |v26|, s97
	s_nop 1
	v_cndmask_b32_e64 v26, v26, v27, s[10:11]
	v_cndmask_b32_e32 v27, 0, v194, vcc
	v_sub_f32_e32 v26, v26, v27

; __device__ __forceinline__ float softplusf_(float x) { const float e = __expf(x); const float sm = e * (1.f - e * (0.5f - e * 0.33333334f)); return x > 20.f ? x : (e < 0.01f ? sm : __logf(1.f + e)); }
;     __device__ __forceinline__ void operator()(AccT acc, const Unit& u, int wr, int wc, int fr, int fq) const {
;     ...
;                     *(f32x4*)d = (f32x4){softplusf_(v0[0] + bb[0]), softplusf_(v0[1] + bb[1]), softplusf_(v0[2] + bb[2]), softplusf_(v0[3] + bb[3])};
.LBB0_1118:
	s_or_b64 exec, exec, s[16:17]
	s_nop 1
	v_mov_b32_e32 v27, v245
	v_add_f32_e32 v27, v23, v27
	v_cmp_nlt_f32_e32 vcc, s92, v27
	s_and_saveexec_b64 s[16:17], vcc
	s_cbranch_execz .LBB0_1122
	v_mul_f32_e32 v27, 0x3fb8aa3b, v27
	v_exp_f32_e32 v28, v27
	s_nop 0
	v_fma_f32 v27, v28, s93, 0.5
	v_fma_f32 v27, -v28, v27, 1.0
	v_mul_f32_e32 v27, v28, v27
	v_cmp_ngt_f32_e32 vcc, s94, v28
	s_and_saveexec_b64 s[18:19], vcc
	s_cbranch_execz .LBB0_1121
	v_add_f32_e32 v27, 1.0, v28
	v_cmp_gt_f32_e32 vcc, s95, v27
	s_nop 1
	v_cndmask_b32_e64 v28, 0, 32, vcc
	v_ldexp_f32 v27, v27, v28
	v_log_f32_e32 v27, v27
	s_nop 0
	v_mul_f32_e32 v28, 0x3f317217, v27
	v_fma_f32 v28, v27, s96, -v28
	v_fmac_f32_e32 v28, 0x3377d1cf, v27
	v_fmac_f32_e32 v28, 0x3f317217, v27
	v_cmp_lt_f32_e64 s[10:11], |v27|, s97
	s_nop 1
	v_cndmask_b32_e64 v27, v27, v28, s[10:11]
	v_cndmask_b32_e32 v28, 0, v194, vcc
	v_sub_f32_e32 v27, v27, v28

; __device__ __forceinline__ float softplusf_(float x) { const float e = __expf(x); const float sm = e * (1.f - e * (0.5f - e * 0.33333334f)); return x > 20.f ? x : (e < 0.01f ? sm : __logf(1.f + e)); }
;     __device__ __forceinline__ void operator()(AccT acc, const Unit& u, int wr, int wc, int fr, int fq) const {
;     ...
;                     *(f32x4*)d = (f32x4){softplusf_(v0[0] + bb[0]), softplusf_(v0[1] + bb[1]), softplusf_(v0[2] + bb[2]), softplusf_(v0[3] + bb[3])};
.LBB0_1122:
	s_or_b64 exec, exec, s[16:17]
	s_nop 1
	v_mov_b32_e32 v28, v246
	v_add_f32_e32 v28, v24, v28
	v_cmp_nlt_f32_e32 vcc, s92, v28
	s_and_saveexec_b64 s[16:17], vcc
	s_cbranch_execz .LBB0_1126
	v_mul_f32_e32 v28, 0x3fb8aa3b, v28
	v_exp_f32_e32 v29, v28
	s_nop 0
	v_fma_f32 v28, v29, s93, 0.5
	v_fma_f32 v28, -v29, v28, 1.0
	v_mul_f32_e32 v28, v29, v28
	v_cmp_ngt_f32_e32 vcc, s94, v29
	s_and_saveexec_b64 s[18:19], vcc
	s_cbranch_execz .LBB0_1125
	v_add_f32_e32 v28, 1.0, v29
	v_cmp_gt_f32_e32 vcc, s95, v28
	s_nop 1
	v_cndmask_b32_e64 v29, 0, 32, vcc
	v_ldexp_f32 v28, v28, v29
	v_log_f32_e32 v28, v28
	s_nop 0
	v_mul_f32_e32 v29, 0x3f317217, v28
	v_fma_f32 v29, v28, s96, -v29
	v_fmac_f32_e32 v29, 0x3377d1cf, v28
	v_fmac_f32_e32 v29, 0x3f317217, v28
	v_cmp_lt_f32_e64 s[10:11], |v28|, s97
	s_nop 1
	v_cndmask_b32_e64 v28, v28, v29, s[10:11]
	v_cndmask_b32_e32 v29, 0, v194, vcc
	v_sub_f32_e32 v28, v28, v29

; __device__ __forceinline__ float softplusf_(float x) { const float e = __expf(x); const float sm = e * (1.f - e * (0.5f - e * 0.33333334f)); return x > 20.f ? x : (e < 0.01f ? sm : __logf(1.f + e)); }
;     __device__ __forceinline__ void operator()(AccT acc, const Unit& u, int wr, int wc, int fr, int fq) const {
;     ...
;                     *(f32x4*)d = (f32x4){softplusf_(v0[0] + bb[0]), softplusf_(v0[1] + bb[1]), softplusf_(v0[2] + bb[2]), softplusf_(v0[3] + bb[3])};
.LBB0_1126:
	s_or_b64 exec, exec, s[16:17]
	s_nop 1
	v_mov_b32_e32 v29, v247
	v_add_f32_e32 v29, v25, v29
	v_cmp_nlt_f32_e32 vcc, s92, v29
	s_and_saveexec_b64 s[16:17], vcc
	s_cbranch_execz .LBB0_1130
	v_mul_f32_e32 v29, 0x3fb8aa3b, v29
	v_exp_f32_e32 v31, v29
	s_nop 0
	v_fma_f32 v29, v31, s93, 0.5
	v_fma_f32 v29, -v31, v29, 1.0
	v_mul_f32_e32 v29, v31, v29
	v_cmp_ngt_f32_e32 vcc, s94, v31
	s_and_saveexec_b64 s[18:19], vcc
	s_cbranch_execz .LBB0_1129
	v_add_f32_e32 v29, 1.0, v31
	v_cmp_gt_f32_e32 vcc, s95, v29
	s_nop 1
	v_cndmask_b32_e64 v31, 0, 32, vcc
	v_ldexp_f32 v29, v29, v31
	v_log_f32_e32 v29, v29
	s_nop 0
	v_mul_f32_e32 v31, 0x3f317217, v29
	v_fma_f32 v31, v29, s96, -v31
	v_fmac_f32_e32 v31, 0x3377d1cf, v29
	v_fmac_f32_e32 v31, 0x3f317217, v29
	v_cmp_lt_f32_e64 s[10:11], |v29|, s97
	s_nop 1
	v_cndmask_b32_e64 v29, v29, v31, s[10:11]
	v_cndmask_b32_e32 v31, 0, v194, vcc
	v_sub_f32_e32 v29, v29, v31

; __device__ __forceinline__ float softplusf_(float x) { const float e = __expf(x); const float sm = e * (1.f - e * (0.5f - e * 0.33333334f)); return x > 20.f ? x : (e < 0.01f ? sm : __logf(1.f + e)); }
;     __device__ __forceinline__ void operator()(AccT acc, const Unit& u, int wr, int wc, int fr, int fq) const {
;     ...
;                     *(f32x4*)d = (f32x4){softplusf_(v0[0] + bb[0]), softplusf_(v0[1] + bb[1]), softplusf_(v0[2] + bb[2]), softplusf_(v0[3] + bb[3])};
;                     *(f32x4*)(d + 4) = (f32x4){softplusf_(v1[0] + bb[4]), softplusf_(v1[1] + bb[5]), softplusf_(v1[2] + bb[6]), softplusf_(v1[3] + bb[7])};
.LBB0_1130:
	s_or_b64 exec, exec, s[16:17]
	v_lshlrev_b64 v[34:35], 6, v[42:43]
	v_lshl_add_u64 v[34:35], v[162:163], 0, v[34:35]
	global_store_dwordx4 v[34:35], v[26:29], off
	s_nop 1
	v_mov_b32_e32 v26, v248
	v_add_f32_e32 v26, v18, v26
	v_cmp_nlt_f32_e32 vcc, s92, v26
	s_and_saveexec_b64 s[16:17], vcc
	s_cbranch_execz .LBB0_1134
	v_mul_f32_e32 v26, 0x3fb8aa3b, v26
	v_exp_f32_e32 v27, v26
	s_nop 0
	v_fma_f32 v26, v27, s93, 0.5
	v_fma_f32 v26, -v27, v26, 1.0
	v_mul_f32_e32 v26, v27, v26
	v_cmp_ngt_f32_e32 vcc, s94, v27
	s_and_saveexec_b64 s[18:19], vcc
	s_cbranch_execz .LBB0_1133
	v_add_f32_e32 v26, 1.0, v27
	v_cmp_gt_f32_e32 vcc, s95, v26
	s_nop 1
	v_cndmask_b32_e64 v27, 0, 32, vcc
	v_ldexp_f32 v26, v26, v27
	v_log_f32_e32 v26, v26
	s_nop 0
	v_mul_f32_e32 v27, 0x3f317217, v26
	v_fma_f32 v27, v26, s96, -v27
	v_fmac_f32_e32 v27, 0x3377d1cf, v26
	v_fmac_f32_e32 v27, 0x3f317217, v26
	v_cmp_lt_f32_e64 s[10:11], |v26|, s97
	s_nop 1
	v_cndmask_b32_e64 v26, v26, v27, s[10:11]
	v_cndmask_b32_e32 v27, 0, v194, vcc
	v_sub_f32_e32 v26, v26, v27

; __device__ __forceinline__ float softplusf_(float x) { const float e = __expf(x); const float sm = e * (1.f - e * (0.5f - e * 0.33333334f)); return x > 20.f ? x : (e < 0.01f ? sm : __logf(1.f + e)); }
;     __device__ __forceinline__ void operator()(AccT acc, const Unit& u, int wr, int wc, int fr, int fq) const {
;     ...
;                     *(f32x4*)(d + 4) = (f32x4){softplusf_(v1[0] + bb[4]), softplusf_(v1[1] + bb[5]), softplusf_(v1[2] + bb[6]), softplusf_(v1[3] + bb[7])};
.LBB0_1134:
	s_or_b64 exec, exec, s[16:17]
	s_nop 1
	v_mov_b32_e32 v27, v249
	v_add_f32_e32 v27, v19, v27
	v_cmp_nlt_f32_e32 vcc, s92, v27
	s_and_saveexec_b64 s[16:17], vcc
	s_cbranch_execz .LBB0_1138
	v_mul_f32_e32 v27, 0x3fb8aa3b, v27
	v_exp_f32_e32 v28, v27
	s_nop 0
	v_fma_f32 v27, v28, s93, 0.5
	v_fma_f32 v27, -v28, v27, 1.0
	v_mul_f32_e32 v27, v28, v27
	v_cmp_ngt_f32_e32 vcc, s94, v28
	s_and_saveexec_b64 s[18:19], vcc
	s_cbranch_execz .LBB0_1137
	v_add_f32_e32 v27, 1.0, v28
	v_cmp_gt_f32_e32 vcc, s95, v27
	s_nop 1
	v_cndmask_b32_e64 v28, 0, 32, vcc
	v_ldexp_f32 v27, v27, v28
	v_log_f32_e32 v27, v27
	s_nop 0
	v_mul_f32_e32 v28, 0x3f317217, v27
	v_fma_f32 v28, v27, s96, -v28
	v_fmac_f32_e32 v28, 0x3377d1cf, v27
	v_fmac_f32_e32 v28, 0x3f317217, v27
	v_cmp_lt_f32_e64 s[10:11], |v27|, s97
	s_nop 1
	v_cndmask_b32_e64 v27, v27, v28, s[10:11]
	v_cndmask_b32_e32 v28, 0, v194, vcc
	v_sub_f32_e32 v27, v27, v28

; __device__ __forceinline__ float softplusf_(float x) { const float e = __expf(x); const float sm = e * (1.f - e * (0.5f - e * 0.33333334f)); return x > 20.f ? x : (e < 0.01f ? sm : __logf(1.f + e)); }
;     __device__ __forceinline__ void operator()(AccT acc, const Unit& u, int wr, int wc, int fr, int fq) const {
;     ...
;                     *(f32x4*)(d + 4) = (f32x4){softplusf_(v1[0] + bb[4]), softplusf_(v1[1] + bb[5]), softplusf_(v1[2] + bb[6]), softplusf_(v1[3] + bb[7])};
.LBB0_1138:
	s_or_b64 exec, exec, s[16:17]
	s_nop 1
	v_mov_b32_e32 v28, v250
	v_add_f32_e32 v28, v20, v28
	v_cmp_nlt_f32_e32 vcc, s92, v28
	s_and_saveexec_b64 s[16:17], vcc
	s_cbranch_execz .LBB0_1142
	v_mul_f32_e32 v28, 0x3fb8aa3b, v28
	v_exp_f32_e32 v29, v28
	s_nop 0
	v_fma_f32 v28, v29, s93, 0.5
	v_fma_f32 v28, -v29, v28, 1.0
	v_mul_f32_e32 v28, v29, v28
	v_cmp_ngt_f32_e32 vcc, s94, v29
	s_and_saveexec_b64 s[18:19], vcc
	s_cbranch_execz .LBB0_1141
	v_add_f32_e32 v28, 1.0, v29
	v_cmp_gt_f32_e32 vcc, s95, v28
	s_nop 1
	v_cndmask_b32_e64 v29, 0, 32, vcc
	v_ldexp_f32 v28, v28, v29
	v_log_f32_e32 v28, v28
	s_nop 0
	v_mul_f32_e32 v29, 0x3f317217, v28
	v_fma_f32 v29, v28, s96, -v29
	v_fmac_f32_e32 v29, 0x3377d1cf, v28
	v_fmac_f32_e32 v29, 0x3f317217, v28
	v_cmp_lt_f32_e64 s[10:11], |v28|, s97
	s_nop 1
	v_cndmask_b32_e64 v28, v28, v29, s[10:11]
	v_cndmask_b32_e32 v29, 0, v194, vcc
	v_sub_f32_e32 v28, v28, v29

; __device__ __forceinline__ float softplusf_(float x) { const float e = __expf(x); const float sm = e * (1.f - e * (0.5f - e * 0.33333334f)); return x > 20.f ? x : (e < 0.01f ? sm : __logf(1.f + e)); }
;     __device__ __forceinline__ void operator()(AccT acc, const Unit& u, int wr, int wc, int fr, int fq) const {
;     ...
;                     *(f32x4*)(d + 4) = (f32x4){softplusf_(v1[0] + bb[4]), softplusf_(v1[1] + bb[5]), softplusf_(v1[2] + bb[6]), softplusf_(v1[3] + bb[7])};
.LBB0_1142:
	s_or_b64 exec, exec, s[16:17]
	s_nop 1
	v_mov_b32_e32 v29, v251
	v_add_f32_e32 v29, v21, v29
	v_cmp_nlt_f32_e32 vcc, s92, v29
	s_and_saveexec_b64 s[16:17], vcc
	s_cbranch_execz .LBB0_1146
	v_mul_f32_e32 v29, 0x3fb8aa3b, v29
	v_exp_f32_e32 v31, v29
	s_nop 0
	v_fma_f32 v29, v31, s93, 0.5
	v_fma_f32 v29, -v31, v29, 1.0
	v_mul_f32_e32 v29, v31, v29
	v_cmp_ngt_f32_e32 vcc, s94, v31
	s_and_saveexec_b64 s[18:19], vcc
	s_cbranch_execz .LBB0_1145
	v_add_f32_e32 v29, 1.0, v31
	v_cmp_gt_f32_e32 vcc, s95, v29
	s_nop 1
	v_cndmask_b32_e64 v31, 0, 32, vcc
	v_ldexp_f32 v29, v29, v31
	v_log_f32_e32 v29, v29
	s_nop 0
	v_mul_f32_e32 v31, 0x3f317217, v29
	v_fma_f32 v31, v29, s96, -v31
	v_fmac_f32_e32 v31, 0x3377d1cf, v29
	v_fmac_f32_e32 v31, 0x3f317217, v29
	v_cmp_lt_f32_e64 s[10:11], |v29|, s97
	s_nop 1
	v_cndmask_b32_e64 v29, v29, v31, s[10:11]
	v_cndmask_b32_e32 v31, 0, v194, vcc
	v_sub_f32_e32 v29, v29, v31

; __device__ __forceinline__ unsigned cvt_pk_bf16(float lo, float hi) { unsigned r; asm volatile("v_cvt_pk_bf16_f32 %0, %1, %2" : "=v"(r) : "v"(lo), "v"(hi)); return r; }
;     __device__ __forceinline__ void operator()(AccT acc, const Unit& u, int wr, int wc, int fr, int fq) const {
;     ...
;         const int side = (u.pn >= 6 && u.pn < 18) ? 1 : ((u.pn >= 22 && u.pn < 32) ? 2 : 0);
;         EPI_ROWS_BEGIN
;             const float rs = rs8[ai * 4 + m];
;             const int sq = seq_of_row(row); const bool isS = row >= NPROMPT; const int t = isS ? ((row - NPROMPT) & 7) : (row & (SEQ - 1));
;             if (!uni) { const float* sw = SHW + (size_t)sq * NZT + col0;
; #pragma unroll
;                 for (int bj = 0; bj < 2; ++bj) { sh[bj][0] = *(const f32x4*)(sw + bj * HALF); sh[bj][1] = *(const f32x4*)(sw + bj * HALF + 4); }
;                 asm volatile("" :: "v"(sh[0][0]), "v"(sh[0][1]), "v"(sh[1][0]), "v"(sh[1][1])); }
; #pragma unroll
;             for (int bj = 0; bj < 2; ++bj) { const int c = col0 + bj * HALF;
;                 const f32x4 v0 = acc[ai][bj][m][0] * rs + sh[bj][0], v1 = acc[ai][bj][m][1] * rs + sh[bj][1];
;                 if (u.pn < 48) {
;                     u32x4 w; w.x = cvt_pk_bf16(v0[0], v0[1]); w.y = cvt_pk_bf16(v0[2], v0[3]); w.z = cvt_pk_bf16(v1[0], v1[1]); w.w = cvt_pk_bf16(v1[2], v1[3]);
;                     *(u32x4*)ZP(Z, row, c) = w;
;                     if (side) {
;                         float* dst = nullptr;
;                         if (side == 1) {
;                             const int kv = c >= ZV ? 1 : 0, cc = c - (kv ? ZV : ZK), g = cc >> 9, ci = cc & 511; const int keep = g == 0 ? 128 : (g == 1 ? 512 : 2048);
;                             if (isS) dst = out + (g == 0 ? O_SKV1 : (g == 1 ? O_SKV2 : O_SKV3)) + ((size_t)(l * 32 + (sq - 16)) * 8 + t) * 1024 + kv * 512 + ci;
;                             else if (t >= SEQ - keep) dst = out + (g == 0 ? O_PKV1 : (g == 1 ? O_PKV2 : O_PKV3)) + ((size_t)(l * 16 + sq) * keep + (t - (SEQ - keep))) * 1024 + kv * 512 + ci;
;                         } else {
;                             const int tl = isS ? 8 : SEQ;
;                             if (t >= tl - 3) { const int i3 = t - (tl - 3);
;                                 if (c < ZXC) dst = out + (isS ? O_SCB + ((size_t)(l * 32 + (sq - 16)) * 3 + i3) * 1536 : O_PCB + ((size_t)(l * 16 + sq) * 3 + i3) * 1536) + (c - ZXBC);
.LBB0_2689:
	s_waitcnt lgkmcnt(7)
	v_add_f32_e32 v146, v146, v147
	v_fmamk_f32 v146, v146, 0x3a800000, v191
	s_add_i32 s8, s18, -6
	s_sub_i32 s9, s18, 22
	v_rsq_f32_e32 v178, v146
	s_cmp_lt_u32 s9, 10
	s_cselect_b32 s9, 2, 0
	s_cmp_gt_u32 s8, 11
	s_cselect_b32 s47, s9, 1
	s_cmp_lt_i32 s18, 48
	s_cselect_b64 s[54:55], -1, 0
	s_cmp_gt_i32 s18, 47
	v_cmp_gt_i32_e64 s[10:11], s79, v176
	v_cmp_lt_i32_e64 s[12:13], s89, v176
	v_ashrrev_i32_e32 v177, 31, v176
	s_mov_b64 s[8:9], -1
	v_pk_fma_f32 v[144:145], v[144:145], v[178:179], v[40:41] op_sel_hi:[1,0,1]
	v_pk_fma_f32 v[142:143], v[142:143], v[178:179], v[38:39] op_sel_hi:[1,0,1]
	v_pk_fma_f32 v[140:141], v[140:141], v[178:179], v[36:37] op_sel_hi:[1,0,1]
	v_pk_fma_f32 v[138:139], v[138:139], v[178:179], v[34:35] op_sel_hi:[1,0,1]
	s_cselect_b64 s[20:21], -1, 0
	s_and_b64 vcc, exec, s[54:55]
	s_cbranch_vccnz .LBB0_2725
	s_and_saveexec_b64 s[14:15], s[38:39]
	s_cbranch_execz .LBB0_2724
	global_load_dwordx4 v[244:247], v[166:167], off offset:64
	global_load_dwordx4 v[248:251], v[166:167], off offset:80
	s_waitcnt vmcnt(0)
	v_mov_b32_e32 v146, v244
	v_add_f32_e32 v146, v142, v146
	v_cmp_nlt_f32_e32 vcc, s90, v146
	s_and_saveexec_b64 s[16:17], vcc
	s_cbranch_execz .LBB0_2695
	v_mul_f32_e32 v146, 0x3fb8aa3b, v146
	v_exp_f32_e32 v147, v146
	s_nop 0
	v_fma_f32 v146, v147, s91, 0.5
	v_fma_f32 v146, -v147, v146, 1.0
	v_mul_f32_e32 v146, v147, v146
	v_cmp_ngt_f32_e32 vcc, s92, v147
	s_and_saveexec_b64 s[56:57], vcc
	s_cbranch_execz .LBB0_2694
	v_add_f32_e32 v146, 1.0, v147
	v_cmp_gt_f32_e32 vcc, s93, v146
	s_nop 1
	v_cndmask_b32_e64 v147, 0, 32, vcc
	v_ldexp_f32 v146, v146, v147
	v_log_f32_e32 v146, v146
	s_nop 0
	v_mul_f32_e32 v147, 0x3f317217, v146
	v_fma_f32 v147, v146, s94, -v147
	v_fmac_f32_e32 v147, 0x3377d1cf, v146
	v_fmac_f32_e32 v147, 0x3f317217, v146
	v_cmp_lt_f32_e64 s[8:9], |v146|, s95
	s_nop 1
	v_cndmask_b32_e64 v146, v146, v147, s[8:9]
	v_cndmask_b32_e32 v147, 0, v192, vcc
	v_sub_f32_e32 v146, v146, v147

; __device__ __forceinline__ float softplusf_(float x) { const float e = __expf(x); const float sm = e * (1.f - e * (0.5f - e * 0.33333334f)); return x > 20.f ? x : (e < 0.01f ? sm : __logf(1.f + e)); }
;     __device__ __forceinline__ void operator()(AccT acc, const Unit& u, int wr, int wc, int fr, int fq) const {
;     ...
;                     *(f32x4*)d = (f32x4){softplusf_(v0[0] + bb[0]), softplusf_(v0[1] + bb[1]), softplusf_(v0[2] + bb[2]), softplusf_(v0[3] + bb[3])};
.LBB0_2695:
	s_or_b64 exec, exec, s[16:17]
	s_nop 1
	v_mov_b32_e32 v147, v245
	v_add_f32_e32 v147, v143, v147
	v_cmp_nlt_f32_e32 vcc, s90, v147
	s_and_saveexec_b64 s[16:17], vcc
	s_cbranch_execz .LBB0_2699
	v_mul_f32_e32 v147, 0x3fb8aa3b, v147
	v_exp_f32_e32 v148, v147
	s_nop 0
	v_fma_f32 v147, v148, s91, 0.5
	v_fma_f32 v147, -v148, v147, 1.0
	v_mul_f32_e32 v147, v148, v147
	v_cmp_ngt_f32_e32 vcc, s92, v148
	s_and_saveexec_b64 s[56:57], vcc
	s_cbranch_execz .LBB0_2698
	v_add_f32_e32 v147, 1.0, v148
	v_cmp_gt_f32_e32 vcc, s93, v147
	s_nop 1
	v_cndmask_b32_e64 v148, 0, 32, vcc
	v_ldexp_f32 v147, v147, v148
	v_log_f32_e32 v147, v147
	s_nop 0
	v_mul_f32_e32 v148, 0x3f317217, v147
	v_fma_f32 v148, v147, s94, -v148
	v_fmac_f32_e32 v148, 0x3377d1cf, v147
	v_fmac_f32_e32 v148, 0x3f317217, v147
	v_cmp_lt_f32_e64 s[8:9], |v147|, s95
	s_nop 1
	v_cndmask_b32_e64 v147, v147, v148, s[8:9]
	v_cndmask_b32_e32 v148, 0, v192, vcc
	v_sub_f32_e32 v147, v147, v148

; __device__ __forceinline__ float softplusf_(float x) { const float e = __expf(x); const float sm = e * (1.f - e * (0.5f - e * 0.33333334f)); return x > 20.f ? x : (e < 0.01f ? sm : __logf(1.f + e)); }
;     __device__ __forceinline__ void operator()(AccT acc, const Unit& u, int wr, int wc, int fr, int fq) const {
;     ...
;                     *(f32x4*)d = (f32x4){softplusf_(v0[0] + bb[0]), softplusf_(v0[1] + bb[1]), softplusf_(v0[2] + bb[2]), softplusf_(v0[3] + bb[3])};
.LBB0_2699:
	s_or_b64 exec, exec, s[16:17]
	s_nop 1
	v_mov_b32_e32 v148, v246
	v_add_f32_e32 v148, v144, v148
	v_cmp_nlt_f32_e32 vcc, s90, v148
	s_and_saveexec_b64 s[16:17], vcc
	s_cbranch_execz .LBB0_2703
	v_mul_f32_e32 v148, 0x3fb8aa3b, v148
	v_exp_f32_e32 v149, v148
	s_nop 0
	v_fma_f32 v148, v149, s91, 0.5
	v_fma_f32 v148, -v149, v148, 1.0
	v_mul_f32_e32 v148, v149, v148
	v_cmp_ngt_f32_e32 vcc, s92, v149
	s_and_saveexec_b64 s[56:57], vcc
	s_cbranch_execz .LBB0_2702
	v_add_f32_e32 v148, 1.0, v149
	v_cmp_gt_f32_e32 vcc, s93, v148
	s_nop 1
	v_cndmask_b32_e64 v149, 0, 32, vcc
	v_ldexp_f32 v148, v148, v149
	v_log_f32_e32 v148, v148
	s_nop 0
	v_mul_f32_e32 v149, 0x3f317217, v148
	v_fma_f32 v149, v148, s94, -v149
	v_fmac_f32_e32 v149, 0x3377d1cf, v148
	v_fmac_f32_e32 v149, 0x3f317217, v148
	v_cmp_lt_f32_e64 s[8:9], |v148|, s95
	s_nop 1
	v_cndmask_b32_e64 v148, v148, v149, s[8:9]
	v_cndmask_b32_e32 v149, 0, v192, vcc
	v_sub_f32_e32 v148, v148, v149

; __device__ __forceinline__ float softplusf_(float x) { const float e = __expf(x); const float sm = e * (1.f - e * (0.5f - e * 0.33333334f)); return x > 20.f ? x : (e < 0.01f ? sm : __logf(1.f + e)); }
;     __device__ __forceinline__ void operator()(AccT acc, const Unit& u, int wr, int wc, int fr, int fq) const {
;     ...
;                     *(f32x4*)d = (f32x4){softplusf_(v0[0] + bb[0]), softplusf_(v0[1] + bb[1]), softplusf_(v0[2] + bb[2]), softplusf_(v0[3] + bb[3])};
.LBB0_2703:
	s_or_b64 exec, exec, s[16:17]
	s_nop 1
	v_mov_b32_e32 v149, v247
	v_add_f32_e32 v149, v145, v149
	v_cmp_nlt_f32_e32 vcc, s90, v149
	s_and_saveexec_b64 s[16:17], vcc
	s_cbranch_execz .LBB0_2707
	v_mul_f32_e32 v149, 0x3fb8aa3b, v149
	v_exp_f32_e32 v158, v149
	s_nop 0
	v_fma_f32 v149, v158, s91, 0.5
	v_fma_f32 v149, -v158, v149, 1.0
	v_mul_f32_e32 v149, v158, v149
	v_cmp_ngt_f32_e32 vcc, s92, v158
	s_and_saveexec_b64 s[56:57], vcc
	s_cbranch_execz .LBB0_2706
	v_add_f32_e32 v149, 1.0, v158
	v_cmp_gt_f32_e32 vcc, s93, v149
	s_nop 1
	v_cndmask_b32_e64 v158, 0, 32, vcc
	v_ldexp_f32 v149, v149, v158
	v_log_f32_e32 v149, v149
	s_nop 0
	v_mul_f32_e32 v158, 0x3f317217, v149
	v_fma_f32 v158, v149, s94, -v158
	v_fmac_f32_e32 v158, 0x3377d1cf, v149
	v_fmac_f32_e32 v158, 0x3f317217, v149
	v_cmp_lt_f32_e64 s[8:9], |v149|, s95
	s_nop 1
	v_cndmask_b32_e64 v149, v149, v158, s[8:9]
	v_cndmask_b32_e32 v158, 0, v192, vcc
	v_sub_f32_e32 v149, v149, v158

; __device__ __forceinline__ float softplusf_(float x) { const float e = __expf(x); const float sm = e * (1.f - e * (0.5f - e * 0.33333334f)); return x > 20.f ? x : (e < 0.01f ? sm : __logf(1.f + e)); }
;     __device__ __forceinline__ void operator()(AccT acc, const Unit& u, int wr, int wc, int fr, int fq) const {
;     ...
;                     *(f32x4*)d = (f32x4){softplusf_(v0[0] + bb[0]), softplusf_(v0[1] + bb[1]), softplusf_(v0[2] + bb[2]), softplusf_(v0[3] + bb[3])};
;                     *(f32x4*)(d + 4) = (f32x4){softplusf_(v1[0] + bb[4]), softplusf_(v1[1] + bb[5]), softplusf_(v1[2] + bb[6]), softplusf_(v1[3] + bb[7])};
.LBB0_2707:
	s_or_b64 exec, exec, s[16:17]
	v_lshlrev_b64 v[180:181], 6, v[176:177]
	v_lshl_add_u64 v[180:181], v[162:163], 0, v[180:181]
	global_store_dwordx4 v[180:181], v[146:149], off
	s_nop 1
	v_mov_b32_e32 v146, v248
	v_add_f32_e32 v146, v138, v146
	v_cmp_nlt_f32_e32 vcc, s90, v146
	s_and_saveexec_b64 s[16:17], vcc
	s_cbranch_execz .LBB0_2711
	v_mul_f32_e32 v146, 0x3fb8aa3b, v146
	v_exp_f32_e32 v147, v146
	s_nop 0
	v_fma_f32 v146, v147, s91, 0.5
	v_fma_f32 v146, -v147, v146, 1.0
	v_mul_f32_e32 v146, v147, v146
	v_cmp_ngt_f32_e32 vcc, s92, v147
	s_and_saveexec_b64 s[56:57], vcc
	s_cbranch_execz .LBB0_2710
	v_add_f32_e32 v146, 1.0, v147
	v_cmp_gt_f32_e32 vcc, s93, v146
	s_nop 1
	v_cndmask_b32_e64 v147, 0, 32, vcc
	v_ldexp_f32 v146, v146, v147
	v_log_f32_e32 v146, v146
	s_nop 0
	v_mul_f32_e32 v147, 0x3f317217, v146
	v_fma_f32 v147, v146, s94, -v147
	v_fmac_f32_e32 v147, 0x3377d1cf, v146
	v_fmac_f32_e32 v147, 0x3f317217, v146
	v_cmp_lt_f32_e64 s[8:9], |v146|, s95
	s_nop 1
	v_cndmask_b32_e64 v146, v146, v147, s[8:9]
	v_cndmask_b32_e32 v147, 0, v192, vcc
	v_sub_f32_e32 v146, v146, v147

; __device__ __forceinline__ float softplusf_(float x) { const float e = __expf(x); const float sm = e * (1.f - e * (0.5f - e * 0.33333334f)); return x > 20.f ? x : (e < 0.01f ? sm : __logf(1.f + e)); }
;     __device__ __forceinline__ void operator()(AccT acc, const Unit& u, int wr, int wc, int fr, int fq) const {
;     ...
;                     *(f32x4*)(d + 4) = (f32x4){softplusf_(v1[0] + bb[4]), softplusf_(v1[1] + bb[5]), softplusf_(v1[2] + bb[6]), softplusf_(v1[3] + bb[7])};
.LBB0_2711:
	s_or_b64 exec, exec, s[16:17]
	s_nop 1
	v_mov_b32_e32 v147, v249
	v_add_f32_e32 v147, v139, v147
	v_cmp_nlt_f32_e32 vcc, s90, v147
	s_and_saveexec_b64 s[16:17], vcc
	s_cbranch_execz .LBB0_2715
	v_mul_f32_e32 v147, 0x3fb8aa3b, v147
	v_exp_f32_e32 v148, v147
	s_nop 0
	v_fma_f32 v147, v148, s91, 0.5
	v_fma_f32 v147, -v148, v147, 1.0
	v_mul_f32_e32 v147, v148, v147
	v_cmp_ngt_f32_e32 vcc, s92, v148
	s_and_saveexec_b64 s[56:57], vcc
	s_cbranch_execz .LBB0_2714
	v_add_f32_e32 v147, 1.0, v148
	v_cmp_gt_f32_e32 vcc, s93, v147
	s_nop 1
	v_cndmask_b32_e64 v148, 0, 32, vcc
	v_ldexp_f32 v147, v147, v148
	v_log_f32_e32 v147, v147
	s_nop 0
	v_mul_f32_e32 v148, 0x3f317217, v147
	v_fma_f32 v148, v147, s94, -v148
	v_fmac_f32_e32 v148, 0x3377d1cf, v147
	v_fmac_f32_e32 v148, 0x3f317217, v147
	v_cmp_lt_f32_e64 s[8:9], |v147|, s95
	s_nop 1
	v_cndmask_b32_e64 v147, v147, v148, s[8:9]
	v_cndmask_b32_e32 v148, 0, v192, vcc
	v_sub_f32_e32 v147, v147, v148

; __device__ __forceinline__ float softplusf_(float x) { const float e = __expf(x); const float sm = e * (1.f - e * (0.5f - e * 0.33333334f)); return x > 20.f ? x : (e < 0.01f ? sm : __logf(1.f + e)); }
;     __device__ __forceinline__ void operator()(AccT acc, const Unit& u, int wr, int wc, int fr, int fq) const {
;     ...
;                     *(f32x4*)(d + 4) = (f32x4){softplusf_(v1[0] + bb[4]), softplusf_(v1[1] + bb[5]), softplusf_(v1[2] + bb[6]), softplusf_(v1[3] + bb[7])};
.LBB0_2715:
	s_or_b64 exec, exec, s[16:17]
	s_nop 1
	v_mov_b32_e32 v148, v250
	v_add_f32_e32 v148, v140, v148
	v_cmp_nlt_f32_e32 vcc, s90, v148
	s_and_saveexec_b64 s[16:17], vcc
	s_cbranch_execz .LBB0_2719
	v_mul_f32_e32 v148, 0x3fb8aa3b, v148
	v_exp_f32_e32 v149, v148
	s_nop 0
	v_fma_f32 v148, v149, s91, 0.5
	v_fma_f32 v148, -v149, v148, 1.0
	v_mul_f32_e32 v148, v149, v148
	v_cmp_ngt_f32_e32 vcc, s92, v149
	s_and_saveexec_b64 s[56:57], vcc
	s_cbranch_execz .LBB0_2718
	v_add_f32_e32 v148, 1.0, v149
	v_cmp_gt_f32_e32 vcc, s93, v148
	s_nop 1
	v_cndmask_b32_e64 v149, 0, 32, vcc
	v_ldexp_f32 v148, v148, v149
	v_log_f32_e32 v148, v148
	s_nop 0
	v_mul_f32_e32 v149, 0x3f317217, v148
	v_fma_f32 v149, v148, s94, -v149
	v_fmac_f32_e32 v149, 0x3377d1cf, v148
	v_fmac_f32_e32 v149, 0x3f317217, v148
	v_cmp_lt_f32_e64 s[8:9], |v148|, s95
	s_nop 1
	v_cndmask_b32_e64 v148, v148, v149, s[8:9]
	v_cndmask_b32_e32 v149, 0, v192, vcc
	v_sub_f32_e32 v148, v148, v149

; __device__ __forceinline__ float softplusf_(float x) { const float e = __expf(x); const float sm = e * (1.f - e * (0.5f - e * 0.33333334f)); return x > 20.f ? x : (e < 0.01f ? sm : __logf(1.f + e)); }
;     __device__ __forceinline__ void operator()(AccT acc, const Unit& u, int wr, int wc, int fr, int fq) const {
;     ...
;                     *(f32x4*)(d + 4) = (f32x4){softplusf_(v1[0] + bb[4]), softplusf_(v1[1] + bb[5]), softplusf_(v1[2] + bb[6]), softplusf_(v1[3] + bb[7])};
.LBB0_2719:
	s_or_b64 exec, exec, s[16:17]
	s_nop 1
	v_mov_b32_e32 v149, v251
	v_add_f32_e32 v149, v141, v149
	v_cmp_nlt_f32_e32 vcc, s90, v149
	s_and_saveexec_b64 s[16:17], vcc
	s_cbranch_execz .LBB0_2723
	v_mul_f32_e32 v149, 0x3fb8aa3b, v149
	v_exp_f32_e32 v158, v149
	s_nop 0
	v_fma_f32 v149, v158, s91, 0.5
	v_fma_f32 v149, -v158, v149, 1.0
	v_mul_f32_e32 v149, v158, v149
	v_cmp_ngt_f32_e32 vcc, s92, v158
	s_and_saveexec_b64 s[56:57], vcc
	s_cbranch_execz .LBB0_2722
	v_add_f32_e32 v149, 1.0, v158
	v_cmp_gt_f32_e32 vcc, s93, v149
	s_nop 1
	v_cndmask_b32_e64 v158, 0, 32, vcc
	v_ldexp_f32 v149, v149, v158
	v_log_f32_e32 v149, v149
	s_nop 0
	v_mul_f32_e32 v158, 0x3f317217, v149
	v_fma_f32 v158, v149, s94, -v158
	v_fmac_f32_e32 v158, 0x3377d1cf, v149
	v_fmac_f32_e32 v158, 0x3f317217, v149
	v_cmp_lt_f32_e64 s[8:9], |v149|, s95
	s_nop 1
	v_cndmask_b32_e64 v149, v149, v158, s[8:9]
	v_cndmask_b32_e32 v158, 0, v192, vcc
	v_sub_f32_e32 v149, v149, v158

; __device__ __forceinline__ float row_rs(const float* SSQ, int row, int fq) {
;     const f32x4 a = *(const f32x4*)(SSQ + (size_t)row * 16 + 4 * fq);
;     float t = (a.x + a.y) + (a.z + a.w);
;     t += __shfl_xor(t, 16); t += __shfl_xor(t, 32);
;     return __builtin_amdgcn_rsqf(t * (1.f / DM) + EPS);
; }
;     __device__ __forceinline__ void operator()(AccT acc, const Unit& u, int wr, int wc, int fr, int fq) const {
;     ...
;                 const f32x4 v0 = acc[ai][bj][m][0] * rs + sh[bj][0], v1 = acc[ai][bj][m][1] * rs + sh[bj][1];
;                 if (u.pn < 48) {
;                     u32x4 w; w.x = cvt_pk_bf16(v0[0], v0[1]); w.y = cvt_pk_bf16(v0[2], v0[3]); w.z = cvt_pk_bf16(v1[0], v1[1]); w.w = cvt_pk_bf16(v1[2], v1[3]);
;                     *(u32x4*)ZP(Z, row, c) = w;
;                     if (side) {
;                         float* dst = nullptr;
;                         if (side == 1) {
;                             const int kv = c >= ZV ? 1 : 0, cc = c - (kv ? ZV : ZK), g = cc >> 9, ci = cc & 511; const int keep = g == 0 ? 128 : (g == 1 ? 512 : 2048);
;                             if (isS) dst = out + (g == 0 ? O_SKV1 : (g == 1 ? O_SKV2 : O_SKV3)) + ((size_t)(l * 32 + (sq - 16)) * 8 + t) * 1024 + kv * 512 + ci;
;                             else if (t >= SEQ - keep) dst = out + (g == 0 ? O_PKV1 : (g == 1 ? O_PKV2 : O_PKV3)) + ((size_t)(l * 16 + sq) * keep + (t - (SEQ - keep))) * 1024 + kv * 512 + ci;
;                         } else {
;                             const int tl = isS ? 8 : SEQ;
;                             if (t >= tl - 3) { const int i3 = t - (tl - 3);
;                                 if (c < ZXC) dst = out + (isS ? O_SCB + ((size_t)(l * 32 + (sq - 16)) * 3 + i3) * 1536 : O_PCB + ((size_t)(l * 16 + sq) * 3 + i3) * 1536) + (c - ZXBC);
;                                 else dst = out + (isS ? O_SCC + ((size_t)(l * 32 + (sq - 16)) * 3 + i3) * 1024 : O_PCC + ((size_t)(l * 16 + sq) * 3 + i3) * 1024) + (c - ZXC); }
;                         }
;                         if (dst) { *(f32x4*)dst = v0; *(f32x4*)(dst + 4) = v1; }
;                     }
;                 } else if (bj == 0 && wc == 0 && fq < 2) {
;                     float* d = DT + (size_t)row * 16 + 8 * fq; const float* bb = dtb + 8 * fq;
.LBB0_2753:
	s_waitcnt lgkmcnt(6)
	v_add_f32_e32 v130, v222, v223
	v_fmamk_f32 v130, v130, 0x3a800000, v191
	v_rsq_f32_e32 v134, v130
	v_cndmask_b32_e64 v130, 0, 1, s[20:21]
	v_cmp_gt_i32_e64 s[12:13], s79, v136
	v_cmp_lt_i32_e64 s[14:15], s89, v136
	v_ashrrev_i32_e32 v137, 31, v136
	s_mov_b64 s[16:17], -1
	v_pk_fma_f32 v[128:129], v[128:129], v[134:135], v[40:41] op_sel_hi:[1,0,1]
	v_pk_fma_f32 v[126:127], v[126:127], v[134:135], v[38:39] op_sel_hi:[1,0,1]
	v_pk_fma_f32 v[124:125], v[124:125], v[134:135], v[36:37] op_sel_hi:[1,0,1]
	v_cmp_ne_u32_e64 s[10:11], 1, v130
	s_andn2_b64 vcc, exec, s[20:21]
	v_pk_fma_f32 v[122:123], v[122:123], v[134:135], v[34:35] op_sel_hi:[1,0,1]
	s_cbranch_vccnz .LBB0_2789
	s_and_saveexec_b64 s[20:21], s[38:39]
	s_cbranch_execz .LBB0_2788
	s_nop 1
	v_mov_b32_e32 v130, v244
	v_add_f32_e32 v130, v126, v130
	v_cmp_nlt_f32_e32 vcc, s90, v130
	s_and_saveexec_b64 s[54:55], vcc
	s_cbranch_execz .LBB0_2759
	v_mul_f32_e32 v130, 0x3fb8aa3b, v130
	v_exp_f32_e32 v131, v130
	s_nop 0
	v_fma_f32 v130, v131, s91, 0.5
	v_fma_f32 v130, -v131, v130, 1.0
	v_mul_f32_e32 v130, v131, v130
	v_cmp_ngt_f32_e32 vcc, s92, v131
	s_and_saveexec_b64 s[56:57], vcc
	s_cbranch_execz .LBB0_2758
	v_add_f32_e32 v130, 1.0, v131
	v_cmp_gt_f32_e32 vcc, s93, v130
	s_nop 1
	v_cndmask_b32_e64 v131, 0, 32, vcc
	v_ldexp_f32 v130, v130, v131
	v_log_f32_e32 v130, v130
	s_nop 0
	v_mul_f32_e32 v131, 0x3f317217, v130
	v_fma_f32 v131, v130, s94, -v131
	v_fmac_f32_e32 v131, 0x3377d1cf, v130
	v_fmac_f32_e32 v131, 0x3f317217, v130
	v_cmp_lt_f32_e64 s[16:17], |v130|, s95
	s_nop 1
	v_cndmask_b32_e64 v130, v130, v131, s[16:17]
	v_cndmask_b32_e32 v131, 0, v192, vcc
	v_sub_f32_e32 v130, v130, v131

; __device__ __forceinline__ float softplusf_(float x) { const float e = __expf(x); const float sm = e * (1.f - e * (0.5f - e * 0.33333334f)); return x > 20.f ? x : (e < 0.01f ? sm : __logf(1.f + e)); }
;     __device__ __forceinline__ void operator()(AccT acc, const Unit& u, int wr, int wc, int fr, int fq) const {
;     ...
;                     *(f32x4*)d = (f32x4){softplusf_(v0[0] + bb[0]), softplusf_(v0[1] + bb[1]), softplusf_(v0[2] + bb[2]), softplusf_(v0[3] + bb[3])};
.LBB0_2759:
	s_or_b64 exec, exec, s[54:55]
	s_nop 1
	v_mov_b32_e32 v131, v245
	v_add_f32_e32 v131, v127, v131
	v_cmp_nlt_f32_e32 vcc, s90, v131
	s_and_saveexec_b64 s[54:55], vcc
	s_cbranch_execz .LBB0_2763
	v_mul_f32_e32 v131, 0x3fb8aa3b, v131
	v_exp_f32_e32 v132, v131
	s_nop 0
	v_fma_f32 v131, v132, s91, 0.5
	v_fma_f32 v131, -v132, v131, 1.0
	v_mul_f32_e32 v131, v132, v131
	v_cmp_ngt_f32_e32 vcc, s92, v132
	s_and_saveexec_b64 s[56:57], vcc
	s_cbranch_execz .LBB0_2762
	v_add_f32_e32 v131, 1.0, v132
	v_cmp_gt_f32_e32 vcc, s93, v131
	s_nop 1
	v_cndmask_b32_e64 v132, 0, 32, vcc
	v_ldexp_f32 v131, v131, v132
	v_log_f32_e32 v131, v131
	s_nop 0
	v_mul_f32_e32 v132, 0x3f317217, v131
	v_fma_f32 v132, v131, s94, -v132
	v_fmac_f32_e32 v132, 0x3377d1cf, v131
	v_fmac_f32_e32 v132, 0x3f317217, v131
	v_cmp_lt_f32_e64 s[16:17], |v131|, s95
	s_nop 1
	v_cndmask_b32_e64 v131, v131, v132, s[16:17]
	v_cndmask_b32_e32 v132, 0, v192, vcc
	v_sub_f32_e32 v131, v131, v132

; __device__ __forceinline__ float softplusf_(float x) { const float e = __expf(x); const float sm = e * (1.f - e * (0.5f - e * 0.33333334f)); return x > 20.f ? x : (e < 0.01f ? sm : __logf(1.f + e)); }
;     __device__ __forceinline__ void operator()(AccT acc, const Unit& u, int wr, int wc, int fr, int fq) const {
;     ...
;                     *(f32x4*)d = (f32x4){softplusf_(v0[0] + bb[0]), softplusf_(v0[1] + bb[1]), softplusf_(v0[2] + bb[2]), softplusf_(v0[3] + bb[3])};
.LBB0_2763:
	s_or_b64 exec, exec, s[54:55]
	s_nop 1
	v_mov_b32_e32 v132, v246
	v_add_f32_e32 v132, v128, v132
	v_cmp_nlt_f32_e32 vcc, s90, v132
	s_and_saveexec_b64 s[54:55], vcc
	s_cbranch_execz .LBB0_2767
	v_mul_f32_e32 v132, 0x3fb8aa3b, v132
	v_exp_f32_e32 v133, v132
	s_nop 0
	v_fma_f32 v132, v133, s91, 0.5
	v_fma_f32 v132, -v133, v132, 1.0
	v_mul_f32_e32 v132, v133, v132
	v_cmp_ngt_f32_e32 vcc, s92, v133
	s_and_saveexec_b64 s[56:57], vcc
	s_cbranch_execz .LBB0_2766
	v_add_f32_e32 v132, 1.0, v133
	v_cmp_gt_f32_e32 vcc, s93, v132
	s_nop 1
	v_cndmask_b32_e64 v133, 0, 32, vcc
	v_ldexp_f32 v132, v132, v133
	v_log_f32_e32 v132, v132
	s_nop 0
	v_mul_f32_e32 v133, 0x3f317217, v132
	v_fma_f32 v133, v132, s94, -v133
	v_fmac_f32_e32 v133, 0x3377d1cf, v132
	v_fmac_f32_e32 v133, 0x3f317217, v132
	v_cmp_lt_f32_e64 s[16:17], |v132|, s95
	s_nop 1
	v_cndmask_b32_e64 v132, v132, v133, s[16:17]
	v_cndmask_b32_e32 v133, 0, v192, vcc
	v_sub_f32_e32 v132, v132, v133

; __device__ __forceinline__ float softplusf_(float x) { const float e = __expf(x); const float sm = e * (1.f - e * (0.5f - e * 0.33333334f)); return x > 20.f ? x : (e < 0.01f ? sm : __logf(1.f + e)); }
;     __device__ __forceinline__ void operator()(AccT acc, const Unit& u, int wr, int wc, int fr, int fq) const {
;     ...
;                     *(f32x4*)d = (f32x4){softplusf_(v0[0] + bb[0]), softplusf_(v0[1] + bb[1]), softplusf_(v0[2] + bb[2]), softplusf_(v0[3] + bb[3])};
.LBB0_2767:
	s_or_b64 exec, exec, s[54:55]
	s_nop 1
	v_mov_b32_e32 v133, v247
	v_add_f32_e32 v133, v129, v133
	v_cmp_nlt_f32_e32 vcc, s90, v133
	s_and_saveexec_b64 s[54:55], vcc
	s_cbranch_execz .LBB0_2771
	v_mul_f32_e32 v133, 0x3fb8aa3b, v133
	v_exp_f32_e32 v135, v133
	s_nop 0
	v_fma_f32 v133, v135, s91, 0.5
	v_fma_f32 v133, -v135, v133, 1.0
	v_mul_f32_e32 v133, v135, v133
	v_cmp_ngt_f32_e32 vcc, s92, v135
	s_and_saveexec_b64 s[56:57], vcc
	s_cbranch_execz .LBB0_2770
	v_add_f32_e32 v133, 1.0, v135
	v_cmp_gt_f32_e32 vcc, s93, v133
	s_nop 1
	v_cndmask_b32_e64 v135, 0, 32, vcc
	v_ldexp_f32 v133, v133, v135
	v_log_f32_e32 v133, v133
	s_nop 0
	v_mul_f32_e32 v135, 0x3f317217, v133
	v_fma_f32 v135, v133, s94, -v135
	v_fmac_f32_e32 v135, 0x3377d1cf, v133
	v_fmac_f32_e32 v135, 0x3f317217, v133
	v_cmp_lt_f32_e64 s[16:17], |v133|, s95
	s_nop 1
	v_cndmask_b32_e64 v133, v133, v135, s[16:17]
	v_cndmask_b32_e32 v135, 0, v192, vcc
	v_sub_f32_e32 v133, v133, v135

; __device__ __forceinline__ float softplusf_(float x) { const float e = __expf(x); const float sm = e * (1.f - e * (0.5f - e * 0.33333334f)); return x > 20.f ? x : (e < 0.01f ? sm : __logf(1.f + e)); }
;     __device__ __forceinline__ void operator()(AccT acc, const Unit& u, int wr, int wc, int fr, int fq) const {
;     ...
;                     *(f32x4*)d = (f32x4){softplusf_(v0[0] + bb[0]), softplusf_(v0[1] + bb[1]), softplusf_(v0[2] + bb[2]), softplusf_(v0[3] + bb[3])};
;                     *(f32x4*)(d + 4) = (f32x4){softplusf_(v1[0] + bb[4]), softplusf_(v1[1] + bb[5]), softplusf_(v1[2] + bb[6]), softplusf_(v1[3] + bb[7])};
.LBB0_2771:
	s_or_b64 exec, exec, s[54:55]
	v_lshlrev_b64 v[140:141], 6, v[136:137]
	v_lshl_add_u64 v[140:141], v[162:163], 0, v[140:141]
	global_store_dwordx4 v[140:141], v[130:133], off
	s_nop 1
	v_mov_b32_e32 v130, v248
	v_add_f32_e32 v130, v122, v130
	v_cmp_nlt_f32_e32 vcc, s90, v130
	s_and_saveexec_b64 s[54:55], vcc
	s_cbranch_execz .LBB0_2775
	v_mul_f32_e32 v130, 0x3fb8aa3b, v130
	v_exp_f32_e32 v131, v130
	s_nop 0
	v_fma_f32 v130, v131, s91, 0.5
	v_fma_f32 v130, -v131, v130, 1.0
	v_mul_f32_e32 v130, v131, v130
	v_cmp_ngt_f32_e32 vcc, s92, v131
	s_and_saveexec_b64 s[56:57], vcc
	s_cbranch_execz .LBB0_2774
	v_add_f32_e32 v130, 1.0, v131
	v_cmp_gt_f32_e32 vcc, s93, v130
	s_nop 1
	v_cndmask_b32_e64 v131, 0, 32, vcc
	v_ldexp_f32 v130, v130, v131
	v_log_f32_e32 v130, v130
	s_nop 0
	v_mul_f32_e32 v131, 0x3f317217, v130
	v_fma_f32 v131, v130, s94, -v131
	v_fmac_f32_e32 v131, 0x3377d1cf, v130
	v_fmac_f32_e32 v131, 0x3f317217, v130
	v_cmp_lt_f32_e64 s[16:17], |v130|, s95
	s_nop 1
	v_cndmask_b32_e64 v130, v130, v131, s[16:17]
	v_cndmask_b32_e32 v131, 0, v192, vcc
	v_sub_f32_e32 v130, v130, v131

; __device__ __forceinline__ float softplusf_(float x) { const float e = __expf(x); const float sm = e * (1.f - e * (0.5f - e * 0.33333334f)); return x > 20.f ? x : (e < 0.01f ? sm : __logf(1.f + e)); }
;     __device__ __forceinline__ void operator()(AccT acc, const Unit& u, int wr, int wc, int fr, int fq) const {
;     ...
;                     *(f32x4*)(d + 4) = (f32x4){softplusf_(v1[0] + bb[4]), softplusf_(v1[1] + bb[5]), softplusf_(v1[2] + bb[6]), softplusf_(v1[3] + bb[7])};
.LBB0_2775:
	s_or_b64 exec, exec, s[54:55]
	s_nop 1
	v_mov_b32_e32 v131, v249
	v_add_f32_e32 v131, v123, v131
	v_cmp_nlt_f32_e32 vcc, s90, v131
	s_and_saveexec_b64 s[54:55], vcc
	s_cbranch_execz .LBB0_2779
	v_mul_f32_e32 v131, 0x3fb8aa3b, v131
	v_exp_f32_e32 v132, v131
	s_nop 0
	v_fma_f32 v131, v132, s91, 0.5
	v_fma_f32 v131, -v132, v131, 1.0
	v_mul_f32_e32 v131, v132, v131
	v_cmp_ngt_f32_e32 vcc, s92, v132
	s_and_saveexec_b64 s[56:57], vcc
	s_cbranch_execz .LBB0_2778
	v_add_f32_e32 v131, 1.0, v132
	v_cmp_gt_f32_e32 vcc, s93, v131
	s_nop 1
	v_cndmask_b32_e64 v132, 0, 32, vcc
	v_ldexp_f32 v131, v131, v132
	v_log_f32_e32 v131, v131
	s_nop 0
	v_mul_f32_e32 v132, 0x3f317217, v131
	v_fma_f32 v132, v131, s94, -v132
	v_fmac_f32_e32 v132, 0x3377d1cf, v131
	v_fmac_f32_e32 v132, 0x3f317217, v131
	v_cmp_lt_f32_e64 s[16:17], |v131|, s95
	s_nop 1
	v_cndmask_b32_e64 v131, v131, v132, s[16:17]
	v_cndmask_b32_e32 v132, 0, v192, vcc
	v_sub_f32_e32 v131, v131, v132

; __device__ __forceinline__ float softplusf_(float x) { const float e = __expf(x); const float sm = e * (1.f - e * (0.5f - e * 0.33333334f)); return x > 20.f ? x : (e < 0.01f ? sm : __logf(1.f + e)); }
;     __device__ __forceinline__ void operator()(AccT acc, const Unit& u, int wr, int wc, int fr, int fq) const {
;     ...
;                     *(f32x4*)(d + 4) = (f32x4){softplusf_(v1[0] + bb[4]), softplusf_(v1[1] + bb[5]), softplusf_(v1[2] + bb[6]), softplusf_(v1[3] + bb[7])};
.LBB0_2779:
	s_or_b64 exec, exec, s[54:55]
	s_nop 1
	v_mov_b32_e32 v132, v250
	v_add_f32_e32 v132, v124, v132
	v_cmp_nlt_f32_e32 vcc, s90, v132
	s_and_saveexec_b64 s[54:55], vcc
	s_cbranch_execz .LBB0_2783
	v_mul_f32_e32 v132, 0x3fb8aa3b, v132
	v_exp_f32_e32 v133, v132
	s_nop 0
	v_fma_f32 v132, v133, s91, 0.5
	v_fma_f32 v132, -v133, v132, 1.0
	v_mul_f32_e32 v132, v133, v132
	v_cmp_ngt_f32_e32 vcc, s92, v133
	s_and_saveexec_b64 s[56:57], vcc
	s_cbranch_execz .LBB0_2782
	v_add_f32_e32 v132, 1.0, v133
	v_cmp_gt_f32_e32 vcc, s93, v132
	s_nop 1
	v_cndmask_b32_e64 v133, 0, 32, vcc
	v_ldexp_f32 v132, v132, v133
	v_log_f32_e32 v132, v132
	s_nop 0
	v_mul_f32_e32 v133, 0x3f317217, v132
	v_fma_f32 v133, v132, s94, -v133
	v_fmac_f32_e32 v133, 0x3377d1cf, v132
	v_fmac_f32_e32 v133, 0x3f317217, v132
	v_cmp_lt_f32_e64 s[16:17], |v132|, s95
	s_nop 1
	v_cndmask_b32_e64 v132, v132, v133, s[16:17]
	v_cndmask_b32_e32 v133, 0, v192, vcc
	v_sub_f32_e32 v132, v132, v133

; __device__ __forceinline__ float softplusf_(float x) { const float e = __expf(x); const float sm = e * (1.f - e * (0.5f - e * 0.33333334f)); return x > 20.f ? x : (e < 0.01f ? sm : __logf(1.f + e)); }
;     __device__ __forceinline__ void operator()(AccT acc, const Unit& u, int wr, int wc, int fr, int fq) const {
;     ...
;                     *(f32x4*)(d + 4) = (f32x4){softplusf_(v1[0] + bb[4]), softplusf_(v1[1] + bb[5]), softplusf_(v1[2] + bb[6]), softplusf_(v1[3] + bb[7])};
.LBB0_2783:
	s_or_b64 exec, exec, s[54:55]
	s_nop 1
	v_mov_b32_e32 v133, v251
	v_add_f32_e32 v133, v125, v133
	v_cmp_nlt_f32_e32 vcc, s90, v133
	s_and_saveexec_b64 s[54:55], vcc
	s_cbranch_execz .LBB0_2787
	v_mul_f32_e32 v133, 0x3fb8aa3b, v133
	v_exp_f32_e32 v135, v133
	s_nop 0
	v_fma_f32 v133, v135, s91, 0.5
	v_fma_f32 v133, -v135, v133, 1.0
	v_mul_f32_e32 v133, v135, v133
	v_cmp_ngt_f32_e32 vcc, s92, v135
	s_and_saveexec_b64 s[56:57], vcc
	s_cbranch_execz .LBB0_2786
	v_add_f32_e32 v133, 1.0, v135
	v_cmp_gt_f32_e32 vcc, s93, v133
	s_nop 1
	v_cndmask_b32_e64 v135, 0, 32, vcc
	v_ldexp_f32 v133, v133, v135
	v_log_f32_e32 v133, v133
	s_nop 0
	v_mul_f32_e32 v135, 0x3f317217, v133
	v_fma_f32 v135, v133, s94, -v135
	v_fmac_f32_e32 v135, 0x3377d1cf, v133
	v_fmac_f32_e32 v135, 0x3f317217, v133
	v_cmp_lt_f32_e64 s[16:17], |v133|, s95
	s_nop 1
	v_cndmask_b32_e64 v133, v133, v135, s[16:17]
	v_cndmask_b32_e32 v135, 0, v192, vcc
	v_sub_f32_e32 v133, v133, v135

; __device__ __forceinline__ float row_rs(const float* SSQ, int row, int fq) {
;     const f32x4 a = *(const f32x4*)(SSQ + (size_t)row * 16 + 4 * fq);
;     float t = (a.x + a.y) + (a.z + a.w);
;     t += __shfl_xor(t, 16); t += __shfl_xor(t, 32);
;     return __builtin_amdgcn_rsqf(t * (1.f / DM) + EPS);
; }
;     __device__ __forceinline__ void operator()(AccT acc, const Unit& u, int wr, int wc, int fr, int fq) const {
;     ...
;                 const f32x4 v0 = acc[ai][bj][m][0] * rs + sh[bj][0], v1 = acc[ai][bj][m][1] * rs + sh[bj][1];
;                 if (u.pn < 48) {
;                     u32x4 w; w.x = cvt_pk_bf16(v0[0], v0[1]); w.y = cvt_pk_bf16(v0[2], v0[3]); w.z = cvt_pk_bf16(v1[0], v1[1]); w.w = cvt_pk_bf16(v1[2], v1[3]);
;                     *(u32x4*)ZP(Z, row, c) = w;
;                     if (side) {
;                         float* dst = nullptr;
;                         if (side == 1) {
;                             const int kv = c >= ZV ? 1 : 0, cc = c - (kv ? ZV : ZK), g = cc >> 9, ci = cc & 511; const int keep = g == 0 ? 128 : (g == 1 ? 512 : 2048);
;                             if (isS) dst = out + (g == 0 ? O_SKV1 : (g == 1 ? O_SKV2 : O_SKV3)) + ((size_t)(l * 32 + (sq - 16)) * 8 + t) * 1024 + kv * 512 + ci;
;                             else if (t >= SEQ - keep) dst = out + (g == 0 ? O_PKV1 : (g == 1 ? O_PKV2 : O_PKV3)) + ((size_t)(l * 16 + sq) * keep + (t - (SEQ - keep))) * 1024 + kv * 512 + ci;
;                         } else {
;                             const int tl = isS ? 8 : SEQ;
;                             if (t >= tl - 3) { const int i3 = t - (tl - 3);
;                                 if (c < ZXC) dst = out + (isS ? O_SCB + ((size_t)(l * 32 + (sq - 16)) * 3 + i3) * 1536 : O_PCB + ((size_t)(l * 16 + sq) * 3 + i3) * 1536) + (c - ZXBC);
;                                 else dst = out + (isS ? O_SCC + ((size_t)(l * 32 + (sq - 16)) * 3 + i3) * 1024 : O_PCC + ((size_t)(l * 16 + sq) * 3 + i3) * 1024) + (c - ZXC); }
;                         }
;                         if (dst) { *(f32x4*)dst = v0; *(f32x4*)(dst + 4) = v1; }
;                     }
;                 } else if (bj == 0 && wc == 0 && fq < 2) {
;                     float* d = DT + (size_t)row * 16 + 8 * fq; const float* bb = dtb + 8 * fq;
.LBB0_2817:
	s_waitcnt lgkmcnt(5)
	v_add_f32_e32 v114, v220, v221
	v_fmamk_f32 v114, v114, 0x3a800000, v191
	v_rsq_f32_e32 v118, v114
	v_cmp_gt_i32_e64 s[12:13], s79, v120
	v_cmp_lt_i32_e64 s[14:15], s89, v120
	v_ashrrev_i32_e32 v121, 31, v120
	s_mov_b64 s[16:17], -1
	v_pk_fma_f32 v[112:113], v[112:113], v[118:119], v[40:41] op_sel_hi:[1,0,1]
	v_pk_fma_f32 v[110:111], v[110:111], v[118:119], v[38:39] op_sel_hi:[1,0,1]
	v_pk_fma_f32 v[108:109], v[108:109], v[118:119], v[36:37] op_sel_hi:[1,0,1]
	s_and_b64 vcc, exec, s[10:11]
	v_pk_fma_f32 v[106:107], v[106:107], v[118:119], v[34:35] op_sel_hi:[1,0,1]
	s_cbranch_vccnz .LBB0_2853
	s_and_saveexec_b64 s[18:19], s[38:39]
	s_cbranch_execz .LBB0_2852
	s_nop 1
	v_mov_b32_e32 v114, v244
	v_add_f32_e32 v114, v110, v114
	v_cmp_nlt_f32_e32 vcc, s90, v114
	s_and_saveexec_b64 s[20:21], vcc
	s_cbranch_execz .LBB0_2823
	v_mul_f32_e32 v114, 0x3fb8aa3b, v114
	v_exp_f32_e32 v115, v114
	s_nop 0
	v_fma_f32 v114, v115, s91, 0.5
	v_fma_f32 v114, -v115, v114, 1.0
	v_mul_f32_e32 v114, v115, v114
	v_cmp_ngt_f32_e32 vcc, s92, v115
	s_and_saveexec_b64 s[56:57], vcc
	s_cbranch_execz .LBB0_2822
	v_add_f32_e32 v114, 1.0, v115
	v_cmp_gt_f32_e32 vcc, s93, v114
	s_nop 1
	v_cndmask_b32_e64 v115, 0, 32, vcc
	v_ldexp_f32 v114, v114, v115
	v_log_f32_e32 v114, v114
	s_nop 0
	v_mul_f32_e32 v115, 0x3f317217, v114
	v_fma_f32 v115, v114, s94, -v115
	v_fmac_f32_e32 v115, 0x3377d1cf, v114
	v_fmac_f32_e32 v115, 0x3f317217, v114
	v_cmp_lt_f32_e64 s[16:17], |v114|, s95
	s_nop 1
	v_cndmask_b32_e64 v114, v114, v115, s[16:17]
	v_cndmask_b32_e32 v115, 0, v192, vcc
	v_sub_f32_e32 v114, v114, v115

; __device__ __forceinline__ float softplusf_(float x) { const float e = __expf(x); const float sm = e * (1.f - e * (0.5f - e * 0.33333334f)); return x > 20.f ? x : (e < 0.01f ? sm : __logf(1.f + e)); }
;     __device__ __forceinline__ void operator()(AccT acc, const Unit& u, int wr, int wc, int fr, int fq) const {
;     ...
;                     *(f32x4*)d = (f32x4){softplusf_(v0[0] + bb[0]), softplusf_(v0[1] + bb[1]), softplusf_(v0[2] + bb[2]), softplusf_(v0[3] + bb[3])};
.LBB0_2823:
	s_or_b64 exec, exec, s[20:21]
	s_nop 1
	v_mov_b32_e32 v115, v245
	v_add_f32_e32 v115, v111, v115
	v_cmp_nlt_f32_e32 vcc, s90, v115
	s_and_saveexec_b64 s[20:21], vcc
	s_cbranch_execz .LBB0_2827
	v_mul_f32_e32 v115, 0x3fb8aa3b, v115
	v_exp_f32_e32 v116, v115
	s_nop 0
	v_fma_f32 v115, v116, s91, 0.5
	v_fma_f32 v115, -v116, v115, 1.0
	v_mul_f32_e32 v115, v116, v115
	v_cmp_ngt_f32_e32 vcc, s92, v116
	s_and_saveexec_b64 s[56:57], vcc
	s_cbranch_execz .LBB0_2826
	v_add_f32_e32 v115, 1.0, v116
	v_cmp_gt_f32_e32 vcc, s93, v115
	s_nop 1
	v_cndmask_b32_e64 v116, 0, 32, vcc
	v_ldexp_f32 v115, v115, v116
	v_log_f32_e32 v115, v115
	s_nop 0
	v_mul_f32_e32 v116, 0x3f317217, v115
	v_fma_f32 v116, v115, s94, -v116
	v_fmac_f32_e32 v116, 0x3377d1cf, v115
	v_fmac_f32_e32 v116, 0x3f317217, v115
	v_cmp_lt_f32_e64 s[16:17], |v115|, s95
	s_nop 1
	v_cndmask_b32_e64 v115, v115, v116, s[16:17]
	v_cndmask_b32_e32 v116, 0, v192, vcc
	v_sub_f32_e32 v115, v115, v116

; __device__ __forceinline__ float softplusf_(float x) { const float e = __expf(x); const float sm = e * (1.f - e * (0.5f - e * 0.33333334f)); return x > 20.f ? x : (e < 0.01f ? sm : __logf(1.f + e)); }
;     __device__ __forceinline__ void operator()(AccT acc, const Unit& u, int wr, int wc, int fr, int fq) const {
;     ...
;                     *(f32x4*)d = (f32x4){softplusf_(v0[0] + bb[0]), softplusf_(v0[1] + bb[1]), softplusf_(v0[2] + bb[2]), softplusf_(v0[3] + bb[3])};
.LBB0_2827:
	s_or_b64 exec, exec, s[20:21]
	s_nop 1
	v_mov_b32_e32 v116, v246
	v_add_f32_e32 v116, v112, v116
	v_cmp_nlt_f32_e32 vcc, s90, v116
	s_and_saveexec_b64 s[20:21], vcc
	s_cbranch_execz .LBB0_2831
	v_mul_f32_e32 v116, 0x3fb8aa3b, v116
	v_exp_f32_e32 v117, v116
	s_nop 0
	v_fma_f32 v116, v117, s91, 0.5
	v_fma_f32 v116, -v117, v116, 1.0
	v_mul_f32_e32 v116, v117, v116
	v_cmp_ngt_f32_e32 vcc, s92, v117
	s_and_saveexec_b64 s[56:57], vcc
	s_cbranch_execz .LBB0_2830
	v_add_f32_e32 v116, 1.0, v117
	v_cmp_gt_f32_e32 vcc, s93, v116
	s_nop 1
	v_cndmask_b32_e64 v117, 0, 32, vcc
	v_ldexp_f32 v116, v116, v117
	v_log_f32_e32 v116, v116
	s_nop 0
	v_mul_f32_e32 v117, 0x3f317217, v116
	v_fma_f32 v117, v116, s94, -v117
	v_fmac_f32_e32 v117, 0x3377d1cf, v116
	v_fmac_f32_e32 v117, 0x3f317217, v116
	v_cmp_lt_f32_e64 s[16:17], |v116|, s95
	s_nop 1
	v_cndmask_b32_e64 v116, v116, v117, s[16:17]
	v_cndmask_b32_e32 v117, 0, v192, vcc
	v_sub_f32_e32 v116, v116, v117

; __device__ __forceinline__ float softplusf_(float x) { const float e = __expf(x); const float sm = e * (1.f - e * (0.5f - e * 0.33333334f)); return x > 20.f ? x : (e < 0.01f ? sm : __logf(1.f + e)); }
;     __device__ __forceinline__ void operator()(AccT acc, const Unit& u, int wr, int wc, int fr, int fq) const {
;     ...
;                     *(f32x4*)d = (f32x4){softplusf_(v0[0] + bb[0]), softplusf_(v0[1] + bb[1]), softplusf_(v0[2] + bb[2]), softplusf_(v0[3] + bb[3])};
.LBB0_2831:
	s_or_b64 exec, exec, s[20:21]
	s_nop 1
	v_mov_b32_e32 v117, v247
	v_add_f32_e32 v117, v113, v117
	v_cmp_nlt_f32_e32 vcc, s90, v117
	s_and_saveexec_b64 s[20:21], vcc
	s_cbranch_execz .LBB0_2835
	v_mul_f32_e32 v117, 0x3fb8aa3b, v117
	v_exp_f32_e32 v119, v117
	s_nop 0
	v_fma_f32 v117, v119, s91, 0.5
	v_fma_f32 v117, -v119, v117, 1.0
	v_mul_f32_e32 v117, v119, v117
	v_cmp_ngt_f32_e32 vcc, s92, v119
	s_and_saveexec_b64 s[56:57], vcc
	s_cbranch_execz .LBB0_2834
	v_add_f32_e32 v117, 1.0, v119
	v_cmp_gt_f32_e32 vcc, s93, v117
	s_nop 1
	v_cndmask_b32_e64 v119, 0, 32, vcc
	v_ldexp_f32 v117, v117, v119
	v_log_f32_e32 v117, v117
	s_nop 0
	v_mul_f32_e32 v119, 0x3f317217, v117
	v_fma_f32 v119, v117, s94, -v119
	v_fmac_f32_e32 v119, 0x3377d1cf, v117
	v_fmac_f32_e32 v119, 0x3f317217, v117
	v_cmp_lt_f32_e64 s[16:17], |v117|, s95
	s_nop 1
	v_cndmask_b32_e64 v117, v117, v119, s[16:17]
	v_cndmask_b32_e32 v119, 0, v192, vcc
	v_sub_f32_e32 v117, v117, v119

; __device__ __forceinline__ float softplusf_(float x) { const float e = __expf(x); const float sm = e * (1.f - e * (0.5f - e * 0.33333334f)); return x > 20.f ? x : (e < 0.01f ? sm : __logf(1.f + e)); }
;     __device__ __forceinline__ void operator()(AccT acc, const Unit& u, int wr, int wc, int fr, int fq) const {
;     ...
;                     *(f32x4*)d = (f32x4){softplusf_(v0[0] + bb[0]), softplusf_(v0[1] + bb[1]), softplusf_(v0[2] + bb[2]), softplusf_(v0[3] + bb[3])};
;                     *(f32x4*)(d + 4) = (f32x4){softplusf_(v1[0] + bb[4]), softplusf_(v1[1] + bb[5]), softplusf_(v1[2] + bb[6]), softplusf_(v1[3] + bb[7])};
.LBB0_2835:
	s_or_b64 exec, exec, s[20:21]
	v_lshlrev_b64 v[122:123], 6, v[120:121]
	v_lshl_add_u64 v[122:123], v[162:163], 0, v[122:123]
	global_store_dwordx4 v[122:123], v[114:117], off
	s_nop 1
	v_mov_b32_e32 v114, v248
	v_add_f32_e32 v114, v106, v114
	v_cmp_nlt_f32_e32 vcc, s90, v114
	s_and_saveexec_b64 s[20:21], vcc
	s_cbranch_execz .LBB0_2839
	v_mul_f32_e32 v114, 0x3fb8aa3b, v114
	v_exp_f32_e32 v115, v114
	s_nop 0
	v_fma_f32 v114, v115, s91, 0.5
	v_fma_f32 v114, -v115, v114, 1.0
	v_mul_f32_e32 v114, v115, v114
	v_cmp_ngt_f32_e32 vcc, s92, v115
	s_and_saveexec_b64 s[56:57], vcc
	s_cbranch_execz .LBB0_2838
	v_add_f32_e32 v114, 1.0, v115
	v_cmp_gt_f32_e32 vcc, s93, v114
	s_nop 1
	v_cndmask_b32_e64 v115, 0, 32, vcc
	v_ldexp_f32 v114, v114, v115
	v_log_f32_e32 v114, v114
	s_nop 0
	v_mul_f32_e32 v115, 0x3f317217, v114
	v_fma_f32 v115, v114, s94, -v115
	v_fmac_f32_e32 v115, 0x3377d1cf, v114
	v_fmac_f32_e32 v115, 0x3f317217, v114
	v_cmp_lt_f32_e64 s[16:17], |v114|, s95
	s_nop 1
	v_cndmask_b32_e64 v114, v114, v115, s[16:17]
	v_cndmask_b32_e32 v115, 0, v192, vcc
	v_sub_f32_e32 v114, v114, v115

; __device__ __forceinline__ float softplusf_(float x) { const float e = __expf(x); const float sm = e * (1.f - e * (0.5f - e * 0.33333334f)); return x > 20.f ? x : (e < 0.01f ? sm : __logf(1.f + e)); }
;     __device__ __forceinline__ void operator()(AccT acc, const Unit& u, int wr, int wc, int fr, int fq) const {
;     ...
;                     *(f32x4*)(d + 4) = (f32x4){softplusf_(v1[0] + bb[4]), softplusf_(v1[1] + bb[5]), softplusf_(v1[2] + bb[6]), softplusf_(v1[3] + bb[7])};
.LBB0_2839:
	s_or_b64 exec, exec, s[20:21]
	s_nop 1
	v_mov_b32_e32 v115, v249
	v_add_f32_e32 v115, v107, v115
	v_cmp_nlt_f32_e32 vcc, s90, v115
	s_and_saveexec_b64 s[20:21], vcc
	s_cbranch_execz .LBB0_2843
	v_mul_f32_e32 v115, 0x3fb8aa3b, v115
	v_exp_f32_e32 v116, v115
	s_nop 0
	v_fma_f32 v115, v116, s91, 0.5
	v_fma_f32 v115, -v116, v115, 1.0
	v_mul_f32_e32 v115, v116, v115
	v_cmp_ngt_f32_e32 vcc, s92, v116
	s_and_saveexec_b64 s[56:57], vcc
	s_cbranch_execz .LBB0_2842
	v_add_f32_e32 v115, 1.0, v116
	v_cmp_gt_f32_e32 vcc, s93, v115
	s_nop 1
	v_cndmask_b32_e64 v116, 0, 32, vcc
	v_ldexp_f32 v115, v115, v116
	v_log_f32_e32 v115, v115
	s_nop 0
	v_mul_f32_e32 v116, 0x3f317217, v115
	v_fma_f32 v116, v115, s94, -v116
	v_fmac_f32_e32 v116, 0x3377d1cf, v115
	v_fmac_f32_e32 v116, 0x3f317217, v115
	v_cmp_lt_f32_e64 s[16:17], |v115|, s95
	s_nop 1
	v_cndmask_b32_e64 v115, v115, v116, s[16:17]
	v_cndmask_b32_e32 v116, 0, v192, vcc
	v_sub_f32_e32 v115, v115, v116

; __device__ __forceinline__ float softplusf_(float x) { const float e = __expf(x); const float sm = e * (1.f - e * (0.5f - e * 0.33333334f)); return x > 20.f ? x : (e < 0.01f ? sm : __logf(1.f + e)); }
;     __device__ __forceinline__ void operator()(AccT acc, const Unit& u, int wr, int wc, int fr, int fq) const {
;     ...
;                     *(f32x4*)(d + 4) = (f32x4){softplusf_(v1[0] + bb[4]), softplusf_(v1[1] + bb[5]), softplusf_(v1[2] + bb[6]), softplusf_(v1[3] + bb[7])};
.LBB0_2843:
	s_or_b64 exec, exec, s[20:21]
	s_nop 1
	v_mov_b32_e32 v116, v250
	v_add_f32_e32 v116, v108, v116
	v_cmp_nlt_f32_e32 vcc, s90, v116
	s_and_saveexec_b64 s[20:21], vcc
	s_cbranch_execz .LBB0_2847
	v_mul_f32_e32 v116, 0x3fb8aa3b, v116
	v_exp_f32_e32 v117, v116
	s_nop 0
	v_fma_f32 v116, v117, s91, 0.5
	v_fma_f32 v116, -v117, v116, 1.0
	v_mul_f32_e32 v116, v117, v116
	v_cmp_ngt_f32_e32 vcc, s92, v117
	s_and_saveexec_b64 s[56:57], vcc
	s_cbranch_execz .LBB0_2846
	v_add_f32_e32 v116, 1.0, v117
	v_cmp_gt_f32_e32 vcc, s93, v116
	s_nop 1
	v_cndmask_b32_e64 v117, 0, 32, vcc
	v_ldexp_f32 v116, v116, v117
	v_log_f32_e32 v116, v116
	s_nop 0
	v_mul_f32_e32 v117, 0x3f317217, v116
	v_fma_f32 v117, v116, s94, -v117
	v_fmac_f32_e32 v117, 0x3377d1cf, v116
	v_fmac_f32_e32 v117, 0x3f317217, v116
	v_cmp_lt_f32_e64 s[16:17], |v116|, s95
	s_nop 1
	v_cndmask_b32_e64 v116, v116, v117, s[16:17]
	v_cndmask_b32_e32 v117, 0, v192, vcc
	v_sub_f32_e32 v116, v116, v117

; __device__ __forceinline__ float softplusf_(float x) { const float e = __expf(x); const float sm = e * (1.f - e * (0.5f - e * 0.33333334f)); return x > 20.f ? x : (e < 0.01f ? sm : __logf(1.f + e)); }
;     __device__ __forceinline__ void operator()(AccT acc, const Unit& u, int wr, int wc, int fr, int fq) const {
;     ...
;                     *(f32x4*)(d + 4) = (f32x4){softplusf_(v1[0] + bb[4]), softplusf_(v1[1] + bb[5]), softplusf_(v1[2] + bb[6]), softplusf_(v1[3] + bb[7])};
.LBB0_2847:
	s_or_b64 exec, exec, s[20:21]
	s_nop 1
	v_mov_b32_e32 v117, v251
	v_add_f32_e32 v117, v109, v117
	v_cmp_nlt_f32_e32 vcc, s90, v117
	s_and_saveexec_b64 s[20:21], vcc
	s_cbranch_execz .LBB0_2851
	v_mul_f32_e32 v117, 0x3fb8aa3b, v117
	v_exp_f32_e32 v119, v117
	s_nop 0
	v_fma_f32 v117, v119, s91, 0.5
	v_fma_f32 v117, -v119, v117, 1.0
	v_mul_f32_e32 v117, v119, v117
	v_cmp_ngt_f32_e32 vcc, s92, v119
	s_and_saveexec_b64 s[56:57], vcc
	s_cbranch_execz .LBB0_2850
	v_add_f32_e32 v117, 1.0, v119
	v_cmp_gt_f32_e32 vcc, s93, v117
	s_nop 1
	v_cndmask_b32_e64 v119, 0, 32, vcc
	v_ldexp_f32 v117, v117, v119
	v_log_f32_e32 v117, v117
	s_nop 0
	v_mul_f32_e32 v119, 0x3f317217, v117
	v_fma_f32 v119, v117, s94, -v119
	v_fmac_f32_e32 v119, 0x3377d1cf, v117
	v_fmac_f32_e32 v119, 0x3f317217, v117
	v_cmp_lt_f32_e64 s[16:17], |v117|, s95
	s_nop 1
	v_cndmask_b32_e64 v117, v117, v119, s[16:17]
	v_cndmask_b32_e32 v119, 0, v192, vcc
	v_sub_f32_e32 v117, v117, v119

; __device__ __forceinline__ float row_rs(const float* SSQ, int row, int fq) {
;     const f32x4 a = *(const f32x4*)(SSQ + (size_t)row * 16 + 4 * fq);
;     float t = (a.x + a.y) + (a.z + a.w);
;     t += __shfl_xor(t, 16); t += __shfl_xor(t, 32);
;     return __builtin_amdgcn_rsqf(t * (1.f / DM) + EPS);
; }
;     __device__ __forceinline__ void operator()(AccT acc, const Unit& u, int wr, int wc, int fr, int fq) const {
;     ...
;                 const f32x4 v0 = acc[ai][bj][m][0] * rs + sh[bj][0], v1 = acc[ai][bj][m][1] * rs + sh[bj][1];
;                 if (u.pn < 48) {
;                     u32x4 w; w.x = cvt_pk_bf16(v0[0], v0[1]); w.y = cvt_pk_bf16(v0[2], v0[3]); w.z = cvt_pk_bf16(v1[0], v1[1]); w.w = cvt_pk_bf16(v1[2], v1[3]);
;                     *(u32x4*)ZP(Z, row, c) = w;
;                     if (side) {
;                         float* dst = nullptr;
;                         if (side == 1) {
;                             const int kv = c >= ZV ? 1 : 0, cc = c - (kv ? ZV : ZK), g = cc >> 9, ci = cc & 511; const int keep = g == 0 ? 128 : (g == 1 ? 512 : 2048);
;                             if (isS) dst = out + (g == 0 ? O_SKV1 : (g == 1 ? O_SKV2 : O_SKV3)) + ((size_t)(l * 32 + (sq - 16)) * 8 + t) * 1024 + kv * 512 + ci;
;                             else if (t >= SEQ - keep) dst = out + (g == 0 ? O_PKV1 : (g == 1 ? O_PKV2 : O_PKV3)) + ((size_t)(l * 16 + sq) * keep + (t - (SEQ - keep))) * 1024 + kv * 512 + ci;
;                         } else {
;                             const int tl = isS ? 8 : SEQ;
;                             if (t >= tl - 3) { const int i3 = t - (tl - 3);
;                                 if (c < ZXC) dst = out + (isS ? O_SCB + ((size_t)(l * 32 + (sq - 16)) * 3 + i3) * 1536 : O_PCB + ((size_t)(l * 16 + sq) * 3 + i3) * 1536) + (c - ZXBC);
;                                 else dst = out + (isS ? O_SCC + ((size_t)(l * 32 + (sq - 16)) * 3 + i3) * 1024 : O_PCC + ((size_t)(l * 16 + sq) * 3 + i3) * 1024) + (c - ZXC); }
;                         }
;                         if (dst) { *(f32x4*)dst = v0; *(f32x4*)(dst + 4) = v1; }
;                     }
;                 } else if (bj == 0 && wc == 0 && fq < 2) {
;                     float* d = DT + (size_t)row * 16 + 8 * fq; const float* bb = dtb + 8 * fq;
.LBB0_2881:
	s_waitcnt lgkmcnt(4)
	v_add_f32_e32 v98, v218, v219
	v_fmamk_f32 v98, v98, 0x3a800000, v191
	v_rsq_f32_e32 v102, v98
	v_cmp_gt_i32_e64 s[12:13], s79, v104
	v_cmp_lt_i32_e64 s[14:15], s89, v104
	v_ashrrev_i32_e32 v105, 31, v104
	s_mov_b64 s[16:17], -1
	v_pk_fma_f32 v[96:97], v[96:97], v[102:103], v[40:41] op_sel_hi:[1,0,1]
	v_pk_fma_f32 v[94:95], v[94:95], v[102:103], v[38:39] op_sel_hi:[1,0,1]
	v_pk_fma_f32 v[92:93], v[92:93], v[102:103], v[36:37] op_sel_hi:[1,0,1]
	s_and_b64 vcc, exec, s[10:11]
	v_pk_fma_f32 v[90:91], v[90:91], v[102:103], v[34:35] op_sel_hi:[1,0,1]
	s_cbranch_vccnz .LBB0_2917
	s_and_saveexec_b64 s[18:19], s[38:39]
	s_cbranch_execz .LBB0_2916
	s_nop 1
	v_mov_b32_e32 v98, v244
	v_add_f32_e32 v98, v94, v98
	v_cmp_nlt_f32_e32 vcc, s90, v98
	s_and_saveexec_b64 s[20:21], vcc
	s_cbranch_execz .LBB0_2887
	v_mul_f32_e32 v98, 0x3fb8aa3b, v98
	v_exp_f32_e32 v99, v98
	s_nop 0
	v_fma_f32 v98, v99, s91, 0.5
	v_fma_f32 v98, -v99, v98, 1.0
	v_mul_f32_e32 v98, v99, v98
	v_cmp_ngt_f32_e32 vcc, s92, v99
	s_and_saveexec_b64 s[56:57], vcc
	s_cbranch_execz .LBB0_2886
	v_add_f32_e32 v98, 1.0, v99
	v_cmp_gt_f32_e32 vcc, s93, v98
	s_nop 1
	v_cndmask_b32_e64 v99, 0, 32, vcc
	v_ldexp_f32 v98, v98, v99
	v_log_f32_e32 v98, v98
	s_nop 0
	v_mul_f32_e32 v99, 0x3f317217, v98
	v_fma_f32 v99, v98, s94, -v99
	v_fmac_f32_e32 v99, 0x3377d1cf, v98
	v_fmac_f32_e32 v99, 0x3f317217, v98
	v_cmp_lt_f32_e64 s[16:17], |v98|, s95
	s_nop 1
	v_cndmask_b32_e64 v98, v98, v99, s[16:17]
	v_cndmask_b32_e32 v99, 0, v192, vcc
	v_sub_f32_e32 v98, v98, v99

; __device__ __forceinline__ float softplusf_(float x) { const float e = __expf(x); const float sm = e * (1.f - e * (0.5f - e * 0.33333334f)); return x > 20.f ? x : (e < 0.01f ? sm : __logf(1.f + e)); }
;     __device__ __forceinline__ void operator()(AccT acc, const Unit& u, int wr, int wc, int fr, int fq) const {
;     ...
;                     *(f32x4*)d = (f32x4){softplusf_(v0[0] + bb[0]), softplusf_(v0[1] + bb[1]), softplusf_(v0[2] + bb[2]), softplusf_(v0[3] + bb[3])};
.LBB0_2887:
	s_or_b64 exec, exec, s[20:21]
	s_nop 1
	v_mov_b32_e32 v99, v245
	v_add_f32_e32 v99, v95, v99
	v_cmp_nlt_f32_e32 vcc, s90, v99
	s_and_saveexec_b64 s[20:21], vcc
	s_cbranch_execz .LBB0_2891
	v_mul_f32_e32 v99, 0x3fb8aa3b, v99
	v_exp_f32_e32 v100, v99
	s_nop 0
	v_fma_f32 v99, v100, s91, 0.5
	v_fma_f32 v99, -v100, v99, 1.0
	v_mul_f32_e32 v99, v100, v99
	v_cmp_ngt_f32_e32 vcc, s92, v100
	s_and_saveexec_b64 s[56:57], vcc
	s_cbranch_execz .LBB0_2890
	v_add_f32_e32 v99, 1.0, v100
	v_cmp_gt_f32_e32 vcc, s93, v99
	s_nop 1
	v_cndmask_b32_e64 v100, 0, 32, vcc
	v_ldexp_f32 v99, v99, v100
	v_log_f32_e32 v99, v99
	s_nop 0
	v_mul_f32_e32 v100, 0x3f317217, v99
	v_fma_f32 v100, v99, s94, -v100
	v_fmac_f32_e32 v100, 0x3377d1cf, v99
	v_fmac_f32_e32 v100, 0x3f317217, v99
	v_cmp_lt_f32_e64 s[16:17], |v99|, s95
	s_nop 1
	v_cndmask_b32_e64 v99, v99, v100, s[16:17]
	v_cndmask_b32_e32 v100, 0, v192, vcc
	v_sub_f32_e32 v99, v99, v100

; __device__ __forceinline__ float softplusf_(float x) { const float e = __expf(x); const float sm = e * (1.f - e * (0.5f - e * 0.33333334f)); return x > 20.f ? x : (e < 0.01f ? sm : __logf(1.f + e)); }
;     __device__ __forceinline__ void operator()(AccT acc, const Unit& u, int wr, int wc, int fr, int fq) const {
;     ...
;                     *(f32x4*)d = (f32x4){softplusf_(v0[0] + bb[0]), softplusf_(v0[1] + bb[1]), softplusf_(v0[2] + bb[2]), softplusf_(v0[3] + bb[3])};
.LBB0_2891:
	s_or_b64 exec, exec, s[20:21]
	s_nop 1
	v_mov_b32_e32 v100, v246
	v_add_f32_e32 v100, v96, v100
	v_cmp_nlt_f32_e32 vcc, s90, v100
	s_and_saveexec_b64 s[20:21], vcc
	s_cbranch_execz .LBB0_2895
	v_mul_f32_e32 v100, 0x3fb8aa3b, v100
	v_exp_f32_e32 v101, v100
	s_nop 0
	v_fma_f32 v100, v101, s91, 0.5
	v_fma_f32 v100, -v101, v100, 1.0
	v_mul_f32_e32 v100, v101, v100
	v_cmp_ngt_f32_e32 vcc, s92, v101
	s_and_saveexec_b64 s[56:57], vcc
	s_cbranch_execz .LBB0_2894
	v_add_f32_e32 v100, 1.0, v101
	v_cmp_gt_f32_e32 vcc, s93, v100
	s_nop 1
	v_cndmask_b32_e64 v101, 0, 32, vcc
	v_ldexp_f32 v100, v100, v101
	v_log_f32_e32 v100, v100
	s_nop 0
	v_mul_f32_e32 v101, 0x3f317217, v100
	v_fma_f32 v101, v100, s94, -v101
	v_fmac_f32_e32 v101, 0x3377d1cf, v100
	v_fmac_f32_e32 v101, 0x3f317217, v100
	v_cmp_lt_f32_e64 s[16:17], |v100|, s95
	s_nop 1
	v_cndmask_b32_e64 v100, v100, v101, s[16:17]
	v_cndmask_b32_e32 v101, 0, v192, vcc
	v_sub_f32_e32 v100, v100, v101

; __device__ __forceinline__ float softplusf_(float x) { const float e = __expf(x); const float sm = e * (1.f - e * (0.5f - e * 0.33333334f)); return x > 20.f ? x : (e < 0.01f ? sm : __logf(1.f + e)); }
;     __device__ __forceinline__ void operator()(AccT acc, const Unit& u, int wr, int wc, int fr, int fq) const {
;     ...
;                     *(f32x4*)d = (f32x4){softplusf_(v0[0] + bb[0]), softplusf_(v0[1] + bb[1]), softplusf_(v0[2] + bb[2]), softplusf_(v0[3] + bb[3])};
.LBB0_2895:
	s_or_b64 exec, exec, s[20:21]
	s_nop 1
	v_mov_b32_e32 v101, v247
	v_add_f32_e32 v101, v97, v101
	v_cmp_nlt_f32_e32 vcc, s90, v101
	s_and_saveexec_b64 s[20:21], vcc
	s_cbranch_execz .LBB0_2899
	v_mul_f32_e32 v101, 0x3fb8aa3b, v101
	v_exp_f32_e32 v103, v101
	s_nop 0
	v_fma_f32 v101, v103, s91, 0.5
	v_fma_f32 v101, -v103, v101, 1.0
	v_mul_f32_e32 v101, v103, v101
	v_cmp_ngt_f32_e32 vcc, s92, v103
	s_and_saveexec_b64 s[56:57], vcc
	s_cbranch_execz .LBB0_2898
	v_add_f32_e32 v101, 1.0, v103
	v_cmp_gt_f32_e32 vcc, s93, v101
	s_nop 1
	v_cndmask_b32_e64 v103, 0, 32, vcc
	v_ldexp_f32 v101, v101, v103
	v_log_f32_e32 v101, v101
	s_nop 0
	v_mul_f32_e32 v103, 0x3f317217, v101
	v_fma_f32 v103, v101, s94, -v103
	v_fmac_f32_e32 v103, 0x3377d1cf, v101
	v_fmac_f32_e32 v103, 0x3f317217, v101
	v_cmp_lt_f32_e64 s[16:17], |v101|, s95
	s_nop 1
	v_cndmask_b32_e64 v101, v101, v103, s[16:17]
	v_cndmask_b32_e32 v103, 0, v192, vcc
	v_sub_f32_e32 v101, v101, v103

; __device__ __forceinline__ float softplusf_(float x) { const float e = __expf(x); const float sm = e * (1.f - e * (0.5f - e * 0.33333334f)); return x > 20.f ? x : (e < 0.01f ? sm : __logf(1.f + e)); }
;     __device__ __forceinline__ void operator()(AccT acc, const Unit& u, int wr, int wc, int fr, int fq) const {
;     ...
;                     *(f32x4*)d = (f32x4){softplusf_(v0[0] + bb[0]), softplusf_(v0[1] + bb[1]), softplusf_(v0[2] + bb[2]), softplusf_(v0[3] + bb[3])};
;                     *(f32x4*)(d + 4) = (f32x4){softplusf_(v1[0] + bb[4]), softplusf_(v1[1] + bb[5]), softplusf_(v1[2] + bb[6]), softplusf_(v1[3] + bb[7])};
.LBB0_2899:
	s_or_b64 exec, exec, s[20:21]
	v_lshlrev_b64 v[106:107], 6, v[104:105]
	v_lshl_add_u64 v[106:107], v[162:163], 0, v[106:107]
	global_store_dwordx4 v[106:107], v[98:101], off
	s_nop 1
	v_mov_b32_e32 v98, v248
	v_add_f32_e32 v98, v90, v98
	v_cmp_nlt_f32_e32 vcc, s90, v98
	s_and_saveexec_b64 s[20:21], vcc
	s_cbranch_execz .LBB0_2903
	v_mul_f32_e32 v98, 0x3fb8aa3b, v98
	v_exp_f32_e32 v99, v98
	s_nop 0
	v_fma_f32 v98, v99, s91, 0.5
	v_fma_f32 v98, -v99, v98, 1.0
	v_mul_f32_e32 v98, v99, v98
	v_cmp_ngt_f32_e32 vcc, s92, v99
	s_and_saveexec_b64 s[56:57], vcc
	s_cbranch_execz .LBB0_2902
	v_add_f32_e32 v98, 1.0, v99
	v_cmp_gt_f32_e32 vcc, s93, v98
	s_nop 1
	v_cndmask_b32_e64 v99, 0, 32, vcc
	v_ldexp_f32 v98, v98, v99
	v_log_f32_e32 v98, v98
	s_nop 0
	v_mul_f32_e32 v99, 0x3f317217, v98
	v_fma_f32 v99, v98, s94, -v99
	v_fmac_f32_e32 v99, 0x3377d1cf, v98
	v_fmac_f32_e32 v99, 0x3f317217, v98
	v_cmp_lt_f32_e64 s[16:17], |v98|, s95
	s_nop 1
	v_cndmask_b32_e64 v98, v98, v99, s[16:17]
	v_cndmask_b32_e32 v99, 0, v192, vcc
	v_sub_f32_e32 v98, v98, v99

; __device__ __forceinline__ float softplusf_(float x) { const float e = __expf(x); const float sm = e * (1.f - e * (0.5f - e * 0.33333334f)); return x > 20.f ? x : (e < 0.01f ? sm : __logf(1.f + e)); }
;     __device__ __forceinline__ void operator()(AccT acc, const Unit& u, int wr, int wc, int fr, int fq) const {
;     ...
;                     *(f32x4*)(d + 4) = (f32x4){softplusf_(v1[0] + bb[4]), softplusf_(v1[1] + bb[5]), softplusf_(v1[2] + bb[6]), softplusf_(v1[3] + bb[7])};
.LBB0_2903:
	s_or_b64 exec, exec, s[20:21]
	s_nop 1
	v_mov_b32_e32 v99, v249
	v_add_f32_e32 v99, v91, v99
	v_cmp_nlt_f32_e32 vcc, s90, v99
	s_and_saveexec_b64 s[20:21], vcc
	s_cbranch_execz .LBB0_2907
	v_mul_f32_e32 v99, 0x3fb8aa3b, v99
	v_exp_f32_e32 v100, v99
	s_nop 0
	v_fma_f32 v99, v100, s91, 0.5
	v_fma_f32 v99, -v100, v99, 1.0
	v_mul_f32_e32 v99, v100, v99
	v_cmp_ngt_f32_e32 vcc, s92, v100
	s_and_saveexec_b64 s[56:57], vcc
	s_cbranch_execz .LBB0_2906
	v_add_f32_e32 v99, 1.0, v100
	v_cmp_gt_f32_e32 vcc, s93, v99
	s_nop 1
	v_cndmask_b32_e64 v100, 0, 32, vcc
	v_ldexp_f32 v99, v99, v100
	v_log_f32_e32 v99, v99
	s_nop 0
	v_mul_f32_e32 v100, 0x3f317217, v99
	v_fma_f32 v100, v99, s94, -v100
	v_fmac_f32_e32 v100, 0x3377d1cf, v99
	v_fmac_f32_e32 v100, 0x3f317217, v99
	v_cmp_lt_f32_e64 s[16:17], |v99|, s95
	s_nop 1
	v_cndmask_b32_e64 v99, v99, v100, s[16:17]
	v_cndmask_b32_e32 v100, 0, v192, vcc
	v_sub_f32_e32 v99, v99, v100

; __device__ __forceinline__ float softplusf_(float x) { const float e = __expf(x); const float sm = e * (1.f - e * (0.5f - e * 0.33333334f)); return x > 20.f ? x : (e < 0.01f ? sm : __logf(1.f + e)); }
;     __device__ __forceinline__ void operator()(AccT acc, const Unit& u, int wr, int wc, int fr, int fq) const {
;     ...
;                     *(f32x4*)(d + 4) = (f32x4){softplusf_(v1[0] + bb[4]), softplusf_(v1[1] + bb[5]), softplusf_(v1[2] + bb[6]), softplusf_(v1[3] + bb[7])};
.LBB0_2907:
	s_or_b64 exec, exec, s[20:21]
	s_nop 1
	v_mov_b32_e32 v100, v250
	v_add_f32_e32 v100, v92, v100
	v_cmp_nlt_f32_e32 vcc, s90, v100
	s_and_saveexec_b64 s[20:21], vcc
	s_cbranch_execz .LBB0_2911
	v_mul_f32_e32 v100, 0x3fb8aa3b, v100
	v_exp_f32_e32 v101, v100
	s_nop 0
	v_fma_f32 v100, v101, s91, 0.5
	v_fma_f32 v100, -v101, v100, 1.0
	v_mul_f32_e32 v100, v101, v100
	v_cmp_ngt_f32_e32 vcc, s92, v101
	s_and_saveexec_b64 s[56:57], vcc
	s_cbranch_execz .LBB0_2910
	v_add_f32_e32 v100, 1.0, v101
	v_cmp_gt_f32_e32 vcc, s93, v100
	s_nop 1
	v_cndmask_b32_e64 v101, 0, 32, vcc
	v_ldexp_f32 v100, v100, v101
	v_log_f32_e32 v100, v100
	s_nop 0
	v_mul_f32_e32 v101, 0x3f317217, v100
	v_fma_f32 v101, v100, s94, -v101
	v_fmac_f32_e32 v101, 0x3377d1cf, v100
	v_fmac_f32_e32 v101, 0x3f317217, v100
	v_cmp_lt_f32_e64 s[16:17], |v100|, s95
	s_nop 1
	v_cndmask_b32_e64 v100, v100, v101, s[16:17]
	v_cndmask_b32_e32 v101, 0, v192, vcc
	v_sub_f32_e32 v100, v100, v101

; __device__ __forceinline__ float softplusf_(float x) { const float e = __expf(x); const float sm = e * (1.f - e * (0.5f - e * 0.33333334f)); return x > 20.f ? x : (e < 0.01f ? sm : __logf(1.f + e)); }
;     __device__ __forceinline__ void operator()(AccT acc, const Unit& u, int wr, int wc, int fr, int fq) const {
;     ...
;                     *(f32x4*)(d + 4) = (f32x4){softplusf_(v1[0] + bb[4]), softplusf_(v1[1] + bb[5]), softplusf_(v1[2] + bb[6]), softplusf_(v1[3] + bb[7])};
.LBB0_2911:
	s_or_b64 exec, exec, s[20:21]
	s_nop 1
	v_mov_b32_e32 v101, v251
	v_add_f32_e32 v101, v93, v101
	v_cmp_nlt_f32_e32 vcc, s90, v101
	s_and_saveexec_b64 s[20:21], vcc
	s_cbranch_execz .LBB0_2915
	v_mul_f32_e32 v101, 0x3fb8aa3b, v101
	v_exp_f32_e32 v103, v101
	s_nop 0
	v_fma_f32 v101, v103, s91, 0.5
	v_fma_f32 v101, -v103, v101, 1.0
	v_mul_f32_e32 v101, v103, v101
	v_cmp_ngt_f32_e32 vcc, s92, v103
	s_and_saveexec_b64 s[56:57], vcc
	s_cbranch_execz .LBB0_2914
	v_add_f32_e32 v101, 1.0, v103
	v_cmp_gt_f32_e32 vcc, s93, v101
	s_nop 1
	v_cndmask_b32_e64 v103, 0, 32, vcc
	v_ldexp_f32 v101, v101, v103
	v_log_f32_e32 v101, v101
	s_nop 0
	v_mul_f32_e32 v103, 0x3f317217, v101
	v_fma_f32 v103, v101, s94, -v103
	v_fmac_f32_e32 v103, 0x3377d1cf, v101
	v_fmac_f32_e32 v103, 0x3f317217, v101
	v_cmp_lt_f32_e64 s[16:17], |v101|, s95
	s_nop 1
	v_cndmask_b32_e64 v101, v101, v103, s[16:17]
	v_cndmask_b32_e32 v103, 0, v192, vcc
	v_sub_f32_e32 v101, v101, v103

; __device__ __forceinline__ float row_rs(const float* SSQ, int row, int fq) {
;     const f32x4 a = *(const f32x4*)(SSQ + (size_t)row * 16 + 4 * fq);
;     float t = (a.x + a.y) + (a.z + a.w);
;     t += __shfl_xor(t, 16); t += __shfl_xor(t, 32);
;     return __builtin_amdgcn_rsqf(t * (1.f / DM) + EPS);
; }
;     __device__ __forceinline__ void operator()(AccT acc, const Unit& u, int wr, int wc, int fr, int fq) const {
;     ...
;                 const f32x4 v0 = acc[ai][bj][m][0] * rs + sh[bj][0], v1 = acc[ai][bj][m][1] * rs + sh[bj][1];
;                 if (u.pn < 48) {
;                     u32x4 w; w.x = cvt_pk_bf16(v0[0], v0[1]); w.y = cvt_pk_bf16(v0[2], v0[3]); w.z = cvt_pk_bf16(v1[0], v1[1]); w.w = cvt_pk_bf16(v1[2], v1[3]);
;                     *(u32x4*)ZP(Z, row, c) = w;
;                     if (side) {
;                         float* dst = nullptr;
;                         if (side == 1) {
;                             const int kv = c >= ZV ? 1 : 0, cc = c - (kv ? ZV : ZK), g = cc >> 9, ci = cc & 511; const int keep = g == 0 ? 128 : (g == 1 ? 512 : 2048);
;                             if (isS) dst = out + (g == 0 ? O_SKV1 : (g == 1 ? O_SKV2 : O_SKV3)) + ((size_t)(l * 32 + (sq - 16)) * 8 + t) * 1024 + kv * 512 + ci;
;                             else if (t >= SEQ - keep) dst = out + (g == 0 ? O_PKV1 : (g == 1 ? O_PKV2 : O_PKV3)) + ((size_t)(l * 16 + sq) * keep + (t - (SEQ - keep))) * 1024 + kv * 512 + ci;
;                         } else {
;                             const int tl = isS ? 8 : SEQ;
;                             if (t >= tl - 3) { const int i3 = t - (tl - 3);
;                                 if (c < ZXC) dst = out + (isS ? O_SCB + ((size_t)(l * 32 + (sq - 16)) * 3 + i3) * 1536 : O_PCB + ((size_t)(l * 16 + sq) * 3 + i3) * 1536) + (c - ZXBC);
;                                 else dst = out + (isS ? O_SCC + ((size_t)(l * 32 + (sq - 16)) * 3 + i3) * 1024 : O_PCC + ((size_t)(l * 16 + sq) * 3 + i3) * 1024) + (c - ZXC); }
;                         }
;                         if (dst) { *(f32x4*)dst = v0; *(f32x4*)(dst + 4) = v1; }
;                     }
;                 } else if (bj == 0 && wc == 0 && fq < 2) {
;                     float* d = DT + (size_t)row * 16 + 8 * fq; const float* bb = dtb + 8 * fq;
.LBB0_2945:
	s_waitcnt lgkmcnt(3)
	v_add_f32_e32 v82, v216, v217
	v_fmamk_f32 v82, v82, 0x3a800000, v191
	v_rsq_f32_e32 v88, v82
	v_cmp_gt_i32_e64 s[12:13], s79, v86
	v_cmp_lt_i32_e64 s[14:15], s89, v86
	v_ashrrev_i32_e32 v87, 31, v86
	s_mov_b64 s[16:17], -1
	v_pk_fma_f32 v[80:81], v[80:81], v[88:89], v[40:41] op_sel_hi:[1,0,1]
	v_pk_fma_f32 v[78:79], v[78:79], v[88:89], v[38:39] op_sel_hi:[1,0,1]
	v_pk_fma_f32 v[76:77], v[76:77], v[88:89], v[36:37] op_sel_hi:[1,0,1]
	s_and_b64 vcc, exec, s[10:11]
	v_pk_fma_f32 v[74:75], v[74:75], v[88:89], v[34:35] op_sel_hi:[1,0,1]
	s_cbranch_vccnz .LBB0_2981
	s_and_saveexec_b64 s[18:19], s[38:39]
	s_cbranch_execz .LBB0_2980
	global_load_dwordx4 v[244:247], v[166:167], off offset:64
	global_load_dwordx4 v[248:251], v[166:167], off offset:80
	s_waitcnt vmcnt(0)
	v_mov_b32_e32 v82, v244
	v_add_f32_e32 v82, v78, v82
	v_cmp_nlt_f32_e32 vcc, s90, v82
	s_and_saveexec_b64 s[20:21], vcc
	s_cbranch_execz .LBB0_2951
	v_mul_f32_e32 v82, 0x3fb8aa3b, v82
	v_exp_f32_e32 v83, v82
	s_nop 0
	v_fma_f32 v82, v83, s91, 0.5
	v_fma_f32 v82, -v83, v82, 1.0
	v_mul_f32_e32 v82, v83, v82
	v_cmp_ngt_f32_e32 vcc, s92, v83
	s_and_saveexec_b64 s[56:57], vcc
	s_cbranch_execz .LBB0_2950
	v_add_f32_e32 v82, 1.0, v83
	v_cmp_gt_f32_e32 vcc, s93, v82
	s_nop 1
	v_cndmask_b32_e64 v83, 0, 32, vcc
	v_ldexp_f32 v82, v82, v83
	v_log_f32_e32 v82, v82
	s_nop 0
	v_mul_f32_e32 v83, 0x3f317217, v82
	v_fma_f32 v83, v82, s94, -v83
	v_fmac_f32_e32 v83, 0x3377d1cf, v82
	v_fmac_f32_e32 v83, 0x3f317217, v82
	v_cmp_lt_f32_e64 s[16:17], |v82|, s95
	s_nop 1
	v_cndmask_b32_e64 v82, v82, v83, s[16:17]
	v_cndmask_b32_e32 v83, 0, v192, vcc
	v_sub_f32_e32 v82, v82, v83

; __device__ __forceinline__ float softplusf_(float x) { const float e = __expf(x); const float sm = e * (1.f - e * (0.5f - e * 0.33333334f)); return x > 20.f ? x : (e < 0.01f ? sm : __logf(1.f + e)); }
;     __device__ __forceinline__ void operator()(AccT acc, const Unit& u, int wr, int wc, int fr, int fq) const {
;     ...
;                     *(f32x4*)d = (f32x4){softplusf_(v0[0] + bb[0]), softplusf_(v0[1] + bb[1]), softplusf_(v0[2] + bb[2]), softplusf_(v0[3] + bb[3])};
.LBB0_2951:
	s_or_b64 exec, exec, s[20:21]
	s_nop 1
	v_mov_b32_e32 v83, v245
	v_add_f32_e32 v83, v79, v83
	v_cmp_nlt_f32_e32 vcc, s90, v83
	s_and_saveexec_b64 s[20:21], vcc
	s_cbranch_execz .LBB0_2955
	v_mul_f32_e32 v83, 0x3fb8aa3b, v83
	v_exp_f32_e32 v84, v83
	s_nop 0
	v_fma_f32 v83, v84, s91, 0.5
	v_fma_f32 v83, -v84, v83, 1.0
	v_mul_f32_e32 v83, v84, v83
	v_cmp_ngt_f32_e32 vcc, s92, v84
	s_and_saveexec_b64 s[56:57], vcc
	s_cbranch_execz .LBB0_2954
	v_add_f32_e32 v83, 1.0, v84
	v_cmp_gt_f32_e32 vcc, s93, v83
	s_nop 1
	v_cndmask_b32_e64 v84, 0, 32, vcc
	v_ldexp_f32 v83, v83, v84
	v_log_f32_e32 v83, v83
	s_nop 0
	v_mul_f32_e32 v84, 0x3f317217, v83
	v_fma_f32 v84, v83, s94, -v84
	v_fmac_f32_e32 v84, 0x3377d1cf, v83
	v_fmac_f32_e32 v84, 0x3f317217, v83
	v_cmp_lt_f32_e64 s[16:17], |v83|, s95
	s_nop 1
	v_cndmask_b32_e64 v83, v83, v84, s[16:17]
	v_cndmask_b32_e32 v84, 0, v192, vcc
	v_sub_f32_e32 v83, v83, v84

; __device__ __forceinline__ float softplusf_(float x) { const float e = __expf(x); const float sm = e * (1.f - e * (0.5f - e * 0.33333334f)); return x > 20.f ? x : (e < 0.01f ? sm : __logf(1.f + e)); }
;     __device__ __forceinline__ void operator()(AccT acc, const Unit& u, int wr, int wc, int fr, int fq) const {
;     ...
;                     *(f32x4*)d = (f32x4){softplusf_(v0[0] + bb[0]), softplusf_(v0[1] + bb[1]), softplusf_(v0[2] + bb[2]), softplusf_(v0[3] + bb[3])};
.LBB0_2955:
	s_or_b64 exec, exec, s[20:21]
	s_nop 1
	v_mov_b32_e32 v84, v246
	v_add_f32_e32 v84, v80, v84
	v_cmp_nlt_f32_e32 vcc, s90, v84
	s_and_saveexec_b64 s[20:21], vcc
	s_cbranch_execz .LBB0_2959
	v_mul_f32_e32 v84, 0x3fb8aa3b, v84
	v_exp_f32_e32 v85, v84
	s_nop 0
	v_fma_f32 v84, v85, s91, 0.5
	v_fma_f32 v84, -v85, v84, 1.0
	v_mul_f32_e32 v84, v85, v84
	v_cmp_ngt_f32_e32 vcc, s92, v85
	s_and_saveexec_b64 s[56:57], vcc
	s_cbranch_execz .LBB0_2958
	v_add_f32_e32 v84, 1.0, v85
	v_cmp_gt_f32_e32 vcc, s93, v84
	s_nop 1
	v_cndmask_b32_e64 v85, 0, 32, vcc
	v_ldexp_f32 v84, v84, v85
	v_log_f32_e32 v84, v84
	s_nop 0
	v_mul_f32_e32 v85, 0x3f317217, v84
	v_fma_f32 v85, v84, s94, -v85
	v_fmac_f32_e32 v85, 0x3377d1cf, v84
	v_fmac_f32_e32 v85, 0x3f317217, v84
	v_cmp_lt_f32_e64 s[16:17], |v84|, s95
	s_nop 1
	v_cndmask_b32_e64 v84, v84, v85, s[16:17]
	v_cndmask_b32_e32 v85, 0, v192, vcc
	v_sub_f32_e32 v84, v84, v85

; __device__ __forceinline__ float softplusf_(float x) { const float e = __expf(x); const float sm = e * (1.f - e * (0.5f - e * 0.33333334f)); return x > 20.f ? x : (e < 0.01f ? sm : __logf(1.f + e)); }
;     __device__ __forceinline__ void operator()(AccT acc, const Unit& u, int wr, int wc, int fr, int fq) const {
;     ...
;                     *(f32x4*)d = (f32x4){softplusf_(v0[0] + bb[0]), softplusf_(v0[1] + bb[1]), softplusf_(v0[2] + bb[2]), softplusf_(v0[3] + bb[3])};
.LBB0_2959:
	s_or_b64 exec, exec, s[20:21]
	s_nop 1
	v_mov_b32_e32 v85, v247
	v_add_f32_e32 v85, v81, v85
	v_cmp_nlt_f32_e32 vcc, s90, v85
	s_and_saveexec_b64 s[20:21], vcc
	s_cbranch_execz .LBB0_2963
	v_mul_f32_e32 v85, 0x3fb8aa3b, v85
	v_exp_f32_e32 v89, v85
	s_nop 0
	v_fma_f32 v85, v89, s91, 0.5
	v_fma_f32 v85, -v89, v85, 1.0
	v_mul_f32_e32 v85, v89, v85
	v_cmp_ngt_f32_e32 vcc, s92, v89
	s_and_saveexec_b64 s[56:57], vcc
	s_cbranch_execz .LBB0_2962
	v_add_f32_e32 v85, 1.0, v89
	v_cmp_gt_f32_e32 vcc, s93, v85
	s_nop 1
	v_cndmask_b32_e64 v89, 0, 32, vcc
	v_ldexp_f32 v85, v85, v89
	v_log_f32_e32 v85, v85
	s_nop 0
	v_mul_f32_e32 v89, 0x3f317217, v85
	v_fma_f32 v89, v85, s94, -v89
	v_fmac_f32_e32 v89, 0x3377d1cf, v85
	v_fmac_f32_e32 v89, 0x3f317217, v85
	v_cmp_lt_f32_e64 s[16:17], |v85|, s95
	s_nop 1
	v_cndmask_b32_e64 v85, v85, v89, s[16:17]
	v_cndmask_b32_e32 v89, 0, v192, vcc
	v_sub_f32_e32 v85, v85, v89

; __device__ __forceinline__ float softplusf_(float x) { const float e = __expf(x); const float sm = e * (1.f - e * (0.5f - e * 0.33333334f)); return x > 20.f ? x : (e < 0.01f ? sm : __logf(1.f + e)); }
;     __device__ __forceinline__ void operator()(AccT acc, const Unit& u, int wr, int wc, int fr, int fq) const {
;     ...
;                     *(f32x4*)d = (f32x4){softplusf_(v0[0] + bb[0]), softplusf_(v0[1] + bb[1]), softplusf_(v0[2] + bb[2]), softplusf_(v0[3] + bb[3])};
;                     *(f32x4*)(d + 4) = (f32x4){softplusf_(v1[0] + bb[4]), softplusf_(v1[1] + bb[5]), softplusf_(v1[2] + bb[6]), softplusf_(v1[3] + bb[7])};
.LBB0_2963:
	s_or_b64 exec, exec, s[20:21]
	v_lshlrev_b64 v[90:91], 6, v[86:87]
	v_lshl_add_u64 v[90:91], v[162:163], 0, v[90:91]
	global_store_dwordx4 v[90:91], v[82:85], off
	s_nop 1
	v_mov_b32_e32 v82, v248
	v_add_f32_e32 v82, v74, v82
	v_cmp_nlt_f32_e32 vcc, s90, v82
	s_and_saveexec_b64 s[20:21], vcc
	s_cbranch_execz .LBB0_2967
	v_mul_f32_e32 v82, 0x3fb8aa3b, v82
	v_exp_f32_e32 v83, v82
	s_nop 0
	v_fma_f32 v82, v83, s91, 0.5
	v_fma_f32 v82, -v83, v82, 1.0
	v_mul_f32_e32 v82, v83, v82
	v_cmp_ngt_f32_e32 vcc, s92, v83
	s_and_saveexec_b64 s[56:57], vcc
	s_cbranch_execz .LBB0_2966
	v_add_f32_e32 v82, 1.0, v83
	v_cmp_gt_f32_e32 vcc, s93, v82
	s_nop 1
	v_cndmask_b32_e64 v83, 0, 32, vcc
	v_ldexp_f32 v82, v82, v83
	v_log_f32_e32 v82, v82
	s_nop 0
	v_mul_f32_e32 v83, 0x3f317217, v82
	v_fma_f32 v83, v82, s94, -v83
	v_fmac_f32_e32 v83, 0x3377d1cf, v82
	v_fmac_f32_e32 v83, 0x3f317217, v82
	v_cmp_lt_f32_e64 s[16:17], |v82|, s95
	s_nop 1
	v_cndmask_b32_e64 v82, v82, v83, s[16:17]
	v_cndmask_b32_e32 v83, 0, v192, vcc
	v_sub_f32_e32 v82, v82, v83

; __device__ __forceinline__ float softplusf_(float x) { const float e = __expf(x); const float sm = e * (1.f - e * (0.5f - e * 0.33333334f)); return x > 20.f ? x : (e < 0.01f ? sm : __logf(1.f + e)); }
;     __device__ __forceinline__ void operator()(AccT acc, const Unit& u, int wr, int wc, int fr, int fq) const {
;     ...
;                     *(f32x4*)(d + 4) = (f32x4){softplusf_(v1[0] + bb[4]), softplusf_(v1[1] + bb[5]), softplusf_(v1[2] + bb[6]), softplusf_(v1[3] + bb[7])};
.LBB0_2967:
	s_or_b64 exec, exec, s[20:21]
	s_nop 1
	v_mov_b32_e32 v83, v249
	v_add_f32_e32 v83, v75, v83
	v_cmp_nlt_f32_e32 vcc, s90, v83
	s_and_saveexec_b64 s[20:21], vcc
	s_cbranch_execz .LBB0_2971
	v_mul_f32_e32 v83, 0x3fb8aa3b, v83
	v_exp_f32_e32 v84, v83
	s_nop 0
	v_fma_f32 v83, v84, s91, 0.5
	v_fma_f32 v83, -v84, v83, 1.0
	v_mul_f32_e32 v83, v84, v83
	v_cmp_ngt_f32_e32 vcc, s92, v84
	s_and_saveexec_b64 s[56:57], vcc
	s_cbranch_execz .LBB0_2970
	v_add_f32_e32 v83, 1.0, v84
	v_cmp_gt_f32_e32 vcc, s93, v83
	s_nop 1
	v_cndmask_b32_e64 v84, 0, 32, vcc
	v_ldexp_f32 v83, v83, v84
	v_log_f32_e32 v83, v83
	s_nop 0
	v_mul_f32_e32 v84, 0x3f317217, v83
	v_fma_f32 v84, v83, s94, -v84
	v_fmac_f32_e32 v84, 0x3377d1cf, v83
	v_fmac_f32_e32 v84, 0x3f317217, v83
	v_cmp_lt_f32_e64 s[16:17], |v83|, s95
	s_nop 1
	v_cndmask_b32_e64 v83, v83, v84, s[16:17]
	v_cndmask_b32_e32 v84, 0, v192, vcc
	v_sub_f32_e32 v83, v83, v84

; __device__ __forceinline__ float softplusf_(float x) { const float e = __expf(x); const float sm = e * (1.f - e * (0.5f - e * 0.33333334f)); return x > 20.f ? x : (e < 0.01f ? sm : __logf(1.f + e)); }
;     __device__ __forceinline__ void operator()(AccT acc, const Unit& u, int wr, int wc, int fr, int fq) const {
;     ...
;                     *(f32x4*)(d + 4) = (f32x4){softplusf_(v1[0] + bb[4]), softplusf_(v1[1] + bb[5]), softplusf_(v1[2] + bb[6]), softplusf_(v1[3] + bb[7])};
.LBB0_2971:
	s_or_b64 exec, exec, s[20:21]
	s_nop 1
	v_mov_b32_e32 v84, v250
	v_add_f32_e32 v84, v76, v84
	v_cmp_nlt_f32_e32 vcc, s90, v84
	s_and_saveexec_b64 s[20:21], vcc
	s_cbranch_execz .LBB0_2975
	v_mul_f32_e32 v84, 0x3fb8aa3b, v84
	v_exp_f32_e32 v85, v84
	s_nop 0
	v_fma_f32 v84, v85, s91, 0.5
	v_fma_f32 v84, -v85, v84, 1.0
	v_mul_f32_e32 v84, v85, v84
	v_cmp_ngt_f32_e32 vcc, s92, v85
	s_and_saveexec_b64 s[56:57], vcc
	s_cbranch_execz .LBB0_2974
	v_add_f32_e32 v84, 1.0, v85
	v_cmp_gt_f32_e32 vcc, s93, v84
	s_nop 1
	v_cndmask_b32_e64 v85, 0, 32, vcc
	v_ldexp_f32 v84, v84, v85
	v_log_f32_e32 v84, v84
	s_nop 0
	v_mul_f32_e32 v85, 0x3f317217, v84
	v_fma_f32 v85, v84, s94, -v85
	v_fmac_f32_e32 v85, 0x3377d1cf, v84
	v_fmac_f32_e32 v85, 0x3f317217, v84
	v_cmp_lt_f32_e64 s[16:17], |v84|, s95
	s_nop 1
	v_cndmask_b32_e64 v84, v84, v85, s[16:17]
	v_cndmask_b32_e32 v85, 0, v192, vcc
	v_sub_f32_e32 v84, v84, v85

; __device__ __forceinline__ float softplusf_(float x) { const float e = __expf(x); const float sm = e * (1.f - e * (0.5f - e * 0.33333334f)); return x > 20.f ? x : (e < 0.01f ? sm : __logf(1.f + e)); }
;     __device__ __forceinline__ void operator()(AccT acc, const Unit& u, int wr, int wc, int fr, int fq) const {
;     ...
;                     *(f32x4*)(d + 4) = (f32x4){softplusf_(v1[0] + bb[4]), softplusf_(v1[1] + bb[5]), softplusf_(v1[2] + bb[6]), softplusf_(v1[3] + bb[7])};
.LBB0_2975:
	s_or_b64 exec, exec, s[20:21]
	s_nop 1
	v_mov_b32_e32 v85, v251
	v_add_f32_e32 v85, v77, v85
	v_cmp_nlt_f32_e32 vcc, s90, v85
	s_and_saveexec_b64 s[20:21], vcc
	s_cbranch_execz .LBB0_2979
	v_mul_f32_e32 v85, 0x3fb8aa3b, v85
	v_exp_f32_e32 v89, v85
	s_nop 0
	v_fma_f32 v85, v89, s91, 0.5
	v_fma_f32 v85, -v89, v85, 1.0
	v_mul_f32_e32 v85, v89, v85
	v_cmp_ngt_f32_e32 vcc, s92, v89
	s_and_saveexec_b64 s[56:57], vcc
	s_cbranch_execz .LBB0_2978
	v_add_f32_e32 v85, 1.0, v89
	v_cmp_gt_f32_e32 vcc, s93, v85
	s_nop 1
	v_cndmask_b32_e64 v89, 0, 32, vcc
	v_ldexp_f32 v85, v85, v89
	v_log_f32_e32 v85, v85
	s_nop 0
	v_mul_f32_e32 v89, 0x3f317217, v85
	v_fma_f32 v89, v85, s94, -v89
	v_fmac_f32_e32 v89, 0x3377d1cf, v85
	v_fmac_f32_e32 v89, 0x3f317217, v85
	v_cmp_lt_f32_e64 s[16:17], |v85|, s95
	s_nop 1
	v_cndmask_b32_e64 v85, v85, v89, s[16:17]
	v_cndmask_b32_e32 v89, 0, v192, vcc
	v_sub_f32_e32 v85, v85, v89

; __device__ __forceinline__ float row_rs(const float* SSQ, int row, int fq) {
;     const f32x4 a = *(const f32x4*)(SSQ + (size_t)row * 16 + 4 * fq);
;     float t = (a.x + a.y) + (a.z + a.w);
;     t += __shfl_xor(t, 16); t += __shfl_xor(t, 32);
;     return __builtin_amdgcn_rsqf(t * (1.f / DM) + EPS);
; }
;     __device__ __forceinline__ void operator()(AccT acc, const Unit& u, int wr, int wc, int fr, int fq) const {
;     ...
;                 const f32x4 v0 = acc[ai][bj][m][0] * rs + sh[bj][0], v1 = acc[ai][bj][m][1] * rs + sh[bj][1];
;                 if (u.pn < 48) {
;                     u32x4 w; w.x = cvt_pk_bf16(v0[0], v0[1]); w.y = cvt_pk_bf16(v0[2], v0[3]); w.z = cvt_pk_bf16(v1[0], v1[1]); w.w = cvt_pk_bf16(v1[2], v1[3]);
;                     *(u32x4*)ZP(Z, row, c) = w;
;                     if (side) {
;                         float* dst = nullptr;
;                         if (side == 1) {
;                             const int kv = c >= ZV ? 1 : 0, cc = c - (kv ? ZV : ZK), g = cc >> 9, ci = cc & 511; const int keep = g == 0 ? 128 : (g == 1 ? 512 : 2048);
;                             if (isS) dst = out + (g == 0 ? O_SKV1 : (g == 1 ? O_SKV2 : O_SKV3)) + ((size_t)(l * 32 + (sq - 16)) * 8 + t) * 1024 + kv * 512 + ci;
;                             else if (t >= SEQ - keep) dst = out + (g == 0 ? O_PKV1 : (g == 1 ? O_PKV2 : O_PKV3)) + ((size_t)(l * 16 + sq) * keep + (t - (SEQ - keep))) * 1024 + kv * 512 + ci;
;                         } else {
;                             const int tl = isS ? 8 : SEQ;
;                             if (t >= tl - 3) { const int i3 = t - (tl - 3);
;                                 if (c < ZXC) dst = out + (isS ? O_SCB + ((size_t)(l * 32 + (sq - 16)) * 3 + i3) * 1536 : O_PCB + ((size_t)(l * 16 + sq) * 3 + i3) * 1536) + (c - ZXBC);
;                                 else dst = out + (isS ? O_SCC + ((size_t)(l * 32 + (sq - 16)) * 3 + i3) * 1024 : O_PCC + ((size_t)(l * 16 + sq) * 3 + i3) * 1024) + (c - ZXC); }
;                         }
;                         if (dst) { *(f32x4*)dst = v0; *(f32x4*)(dst + 4) = v1; }
;                     }
;                 } else if (bj == 0 && wc == 0 && fq < 2) {
;                     float* d = DT + (size_t)row * 16 + 8 * fq; const float* bb = dtb + 8 * fq;
.LBB0_3009:
	s_waitcnt lgkmcnt(2)
	v_add_f32_e32 v66, v214, v215
	v_fmamk_f32 v66, v66, 0x3a800000, v191
	v_rsq_f32_e32 v70, v66
	v_cmp_gt_i32_e64 s[12:13], s79, v72
	v_cmp_lt_i32_e64 s[14:15], s89, v72
	v_ashrrev_i32_e32 v73, 31, v72
	s_mov_b64 s[16:17], -1
	v_pk_fma_f32 v[64:65], v[64:65], v[70:71], v[40:41] op_sel_hi:[1,0,1]
	v_pk_fma_f32 v[62:63], v[62:63], v[70:71], v[38:39] op_sel_hi:[1,0,1]
	v_pk_fma_f32 v[60:61], v[60:61], v[70:71], v[36:37] op_sel_hi:[1,0,1]
	s_and_b64 vcc, exec, s[10:11]
	v_pk_fma_f32 v[58:59], v[58:59], v[70:71], v[34:35] op_sel_hi:[1,0,1]
	s_cbranch_vccnz .LBB0_3045
	s_and_saveexec_b64 s[18:19], s[38:39]
	s_cbranch_execz .LBB0_3044
	s_nop 1
	v_mov_b32_e32 v66, v244
	v_add_f32_e32 v66, v62, v66
	v_cmp_nlt_f32_e32 vcc, s90, v66
	s_and_saveexec_b64 s[20:21], vcc
	s_cbranch_execz .LBB0_3015
	v_mul_f32_e32 v66, 0x3fb8aa3b, v66
	v_exp_f32_e32 v67, v66
	s_nop 0
	v_fma_f32 v66, v67, s91, 0.5
	v_fma_f32 v66, -v67, v66, 1.0
	v_mul_f32_e32 v66, v67, v66
	v_cmp_ngt_f32_e32 vcc, s92, v67
	s_and_saveexec_b64 s[56:57], vcc
	s_cbranch_execz .LBB0_3014
	v_add_f32_e32 v66, 1.0, v67
	v_cmp_gt_f32_e32 vcc, s93, v66
	s_nop 1
	v_cndmask_b32_e64 v67, 0, 32, vcc
	v_ldexp_f32 v66, v66, v67
	v_log_f32_e32 v66, v66
	s_nop 0
	v_mul_f32_e32 v67, 0x3f317217, v66
	v_fma_f32 v67, v66, s94, -v67
	v_fmac_f32_e32 v67, 0x3377d1cf, v66
	v_fmac_f32_e32 v67, 0x3f317217, v66
	v_cmp_lt_f32_e64 s[16:17], |v66|, s95
	s_nop 1
	v_cndmask_b32_e64 v66, v66, v67, s[16:17]
	v_cndmask_b32_e32 v67, 0, v192, vcc
	v_sub_f32_e32 v66, v66, v67

; __device__ __forceinline__ float softplusf_(float x) { const float e = __expf(x); const float sm = e * (1.f - e * (0.5f - e * 0.33333334f)); return x > 20.f ? x : (e < 0.01f ? sm : __logf(1.f + e)); }
;     __device__ __forceinline__ void operator()(AccT acc, const Unit& u, int wr, int wc, int fr, int fq) const {
;     ...
;                     *(f32x4*)d = (f32x4){softplusf_(v0[0] + bb[0]), softplusf_(v0[1] + bb[1]), softplusf_(v0[2] + bb[2]), softplusf_(v0[3] + bb[3])};
.LBB0_3015:
	s_or_b64 exec, exec, s[20:21]
	s_nop 1
	v_mov_b32_e32 v67, v245
	v_add_f32_e32 v67, v63, v67
	v_cmp_nlt_f32_e32 vcc, s90, v67
	s_and_saveexec_b64 s[20:21], vcc
	s_cbranch_execz .LBB0_3019
	v_mul_f32_e32 v67, 0x3fb8aa3b, v67
	v_exp_f32_e32 v68, v67
	s_nop 0
	v_fma_f32 v67, v68, s91, 0.5
	v_fma_f32 v67, -v68, v67, 1.0
	v_mul_f32_e32 v67, v68, v67
	v_cmp_ngt_f32_e32 vcc, s92, v68
	s_and_saveexec_b64 s[56:57], vcc
	s_cbranch_execz .LBB0_3018
	v_add_f32_e32 v67, 1.0, v68
	v_cmp_gt_f32_e32 vcc, s93, v67
	s_nop 1
	v_cndmask_b32_e64 v68, 0, 32, vcc
	v_ldexp_f32 v67, v67, v68
	v_log_f32_e32 v67, v67
	s_nop 0
	v_mul_f32_e32 v68, 0x3f317217, v67
	v_fma_f32 v68, v67, s94, -v68
	v_fmac_f32_e32 v68, 0x3377d1cf, v67
	v_fmac_f32_e32 v68, 0x3f317217, v67
	v_cmp_lt_f32_e64 s[16:17], |v67|, s95
	s_nop 1
	v_cndmask_b32_e64 v67, v67, v68, s[16:17]
	v_cndmask_b32_e32 v68, 0, v192, vcc
	v_sub_f32_e32 v67, v67, v68

; __device__ __forceinline__ float softplusf_(float x) { const float e = __expf(x); const float sm = e * (1.f - e * (0.5f - e * 0.33333334f)); return x > 20.f ? x : (e < 0.01f ? sm : __logf(1.f + e)); }
;     __device__ __forceinline__ void operator()(AccT acc, const Unit& u, int wr, int wc, int fr, int fq) const {
;     ...
;                     *(f32x4*)d = (f32x4){softplusf_(v0[0] + bb[0]), softplusf_(v0[1] + bb[1]), softplusf_(v0[2] + bb[2]), softplusf_(v0[3] + bb[3])};
.LBB0_3019:
	s_or_b64 exec, exec, s[20:21]
	s_nop 1
	v_mov_b32_e32 v68, v246
	v_add_f32_e32 v68, v64, v68
	v_cmp_nlt_f32_e32 vcc, s90, v68
	s_and_saveexec_b64 s[20:21], vcc
	s_cbranch_execz .LBB0_3023
	v_mul_f32_e32 v68, 0x3fb8aa3b, v68
	v_exp_f32_e32 v69, v68
	s_nop 0
	v_fma_f32 v68, v69, s91, 0.5
	v_fma_f32 v68, -v69, v68, 1.0
	v_mul_f32_e32 v68, v69, v68
	v_cmp_ngt_f32_e32 vcc, s92, v69
	s_and_saveexec_b64 s[56:57], vcc
	s_cbranch_execz .LBB0_3022
	v_add_f32_e32 v68, 1.0, v69
	v_cmp_gt_f32_e32 vcc, s93, v68
	s_nop 1
	v_cndmask_b32_e64 v69, 0, 32, vcc
	v_ldexp_f32 v68, v68, v69
	v_log_f32_e32 v68, v68
	s_nop 0
	v_mul_f32_e32 v69, 0x3f317217, v68
	v_fma_f32 v69, v68, s94, -v69
	v_fmac_f32_e32 v69, 0x3377d1cf, v68
	v_fmac_f32_e32 v69, 0x3f317217, v68
	v_cmp_lt_f32_e64 s[16:17], |v68|, s95
	s_nop 1
	v_cndmask_b32_e64 v68, v68, v69, s[16:17]
	v_cndmask_b32_e32 v69, 0, v192, vcc
	v_sub_f32_e32 v68, v68, v69

; __device__ __forceinline__ float softplusf_(float x) { const float e = __expf(x); const float sm = e * (1.f - e * (0.5f - e * 0.33333334f)); return x > 20.f ? x : (e < 0.01f ? sm : __logf(1.f + e)); }
;     __device__ __forceinline__ void operator()(AccT acc, const Unit& u, int wr, int wc, int fr, int fq) const {
;     ...
;                     *(f32x4*)d = (f32x4){softplusf_(v0[0] + bb[0]), softplusf_(v0[1] + bb[1]), softplusf_(v0[2] + bb[2]), softplusf_(v0[3] + bb[3])};
.LBB0_3023:
	s_or_b64 exec, exec, s[20:21]
	s_nop 1
	v_mov_b32_e32 v69, v247
	v_add_f32_e32 v69, v65, v69
	v_cmp_nlt_f32_e32 vcc, s90, v69
	s_and_saveexec_b64 s[20:21], vcc
	s_cbranch_execz .LBB0_3027
	v_mul_f32_e32 v69, 0x3fb8aa3b, v69
	v_exp_f32_e32 v71, v69
	s_nop 0
	v_fma_f32 v69, v71, s91, 0.5
	v_fma_f32 v69, -v71, v69, 1.0
	v_mul_f32_e32 v69, v71, v69
	v_cmp_ngt_f32_e32 vcc, s92, v71
	s_and_saveexec_b64 s[56:57], vcc
	s_cbranch_execz .LBB0_3026
	v_add_f32_e32 v69, 1.0, v71
	v_cmp_gt_f32_e32 vcc, s93, v69
	s_nop 1
	v_cndmask_b32_e64 v71, 0, 32, vcc
	v_ldexp_f32 v69, v69, v71
	v_log_f32_e32 v69, v69
	s_nop 0
	v_mul_f32_e32 v71, 0x3f317217, v69
	v_fma_f32 v71, v69, s94, -v71
	v_fmac_f32_e32 v71, 0x3377d1cf, v69
	v_fmac_f32_e32 v71, 0x3f317217, v69
	v_cmp_lt_f32_e64 s[16:17], |v69|, s95
	s_nop 1
	v_cndmask_b32_e64 v69, v69, v71, s[16:17]
	v_cndmask_b32_e32 v71, 0, v192, vcc
	v_sub_f32_e32 v69, v69, v71

; __device__ __forceinline__ float softplusf_(float x) { const float e = __expf(x); const float sm = e * (1.f - e * (0.5f - e * 0.33333334f)); return x > 20.f ? x : (e < 0.01f ? sm : __logf(1.f + e)); }
;     __device__ __forceinline__ void operator()(AccT acc, const Unit& u, int wr, int wc, int fr, int fq) const {
;     ...
;                     *(f32x4*)d = (f32x4){softplusf_(v0[0] + bb[0]), softplusf_(v0[1] + bb[1]), softplusf_(v0[2] + bb[2]), softplusf_(v0[3] + bb[3])};
;                     *(f32x4*)(d + 4) = (f32x4){softplusf_(v1[0] + bb[4]), softplusf_(v1[1] + bb[5]), softplusf_(v1[2] + bb[6]), softplusf_(v1[3] + bb[7])};
.LBB0_3027:
	s_or_b64 exec, exec, s[20:21]
	v_lshlrev_b64 v[74:75], 6, v[72:73]
	v_lshl_add_u64 v[74:75], v[162:163], 0, v[74:75]
	global_store_dwordx4 v[74:75], v[66:69], off
	s_nop 1
	v_mov_b32_e32 v66, v248
	v_add_f32_e32 v66, v58, v66
	v_cmp_nlt_f32_e32 vcc, s90, v66
	s_and_saveexec_b64 s[20:21], vcc
	s_cbranch_execz .LBB0_3031
	v_mul_f32_e32 v66, 0x3fb8aa3b, v66
	v_exp_f32_e32 v67, v66
	s_nop 0
	v_fma_f32 v66, v67, s91, 0.5
	v_fma_f32 v66, -v67, v66, 1.0
	v_mul_f32_e32 v66, v67, v66
	v_cmp_ngt_f32_e32 vcc, s92, v67
	s_and_saveexec_b64 s[56:57], vcc
	s_cbranch_execz .LBB0_3030
	v_add_f32_e32 v66, 1.0, v67
	v_cmp_gt_f32_e32 vcc, s93, v66
	s_nop 1
	v_cndmask_b32_e64 v67, 0, 32, vcc
	v_ldexp_f32 v66, v66, v67
	v_log_f32_e32 v66, v66
	s_nop 0
	v_mul_f32_e32 v67, 0x3f317217, v66
	v_fma_f32 v67, v66, s94, -v67
	v_fmac_f32_e32 v67, 0x3377d1cf, v66
	v_fmac_f32_e32 v67, 0x3f317217, v66
	v_cmp_lt_f32_e64 s[16:17], |v66|, s95
	s_nop 1
	v_cndmask_b32_e64 v66, v66, v67, s[16:17]
	v_cndmask_b32_e32 v67, 0, v192, vcc
	v_sub_f32_e32 v66, v66, v67

; __device__ __forceinline__ float softplusf_(float x) { const float e = __expf(x); const float sm = e * (1.f - e * (0.5f - e * 0.33333334f)); return x > 20.f ? x : (e < 0.01f ? sm : __logf(1.f + e)); }
;     __device__ __forceinline__ void operator()(AccT acc, const Unit& u, int wr, int wc, int fr, int fq) const {
;     ...
;                     *(f32x4*)(d + 4) = (f32x4){softplusf_(v1[0] + bb[4]), softplusf_(v1[1] + bb[5]), softplusf_(v1[2] + bb[6]), softplusf_(v1[3] + bb[7])};
.LBB0_3031:
	s_or_b64 exec, exec, s[20:21]
	s_nop 1
	v_mov_b32_e32 v67, v249
	v_add_f32_e32 v67, v59, v67
	v_cmp_nlt_f32_e32 vcc, s90, v67
	s_and_saveexec_b64 s[20:21], vcc
	s_cbranch_execz .LBB0_3035
	v_mul_f32_e32 v67, 0x3fb8aa3b, v67
	v_exp_f32_e32 v68, v67
	s_nop 0
	v_fma_f32 v67, v68, s91, 0.5
	v_fma_f32 v67, -v68, v67, 1.0
	v_mul_f32_e32 v67, v68, v67
	v_cmp_ngt_f32_e32 vcc, s92, v68
	s_and_saveexec_b64 s[56:57], vcc
	s_cbranch_execz .LBB0_3034
	v_add_f32_e32 v67, 1.0, v68
	v_cmp_gt_f32_e32 vcc, s93, v67
	s_nop 1
	v_cndmask_b32_e64 v68, 0, 32, vcc
	v_ldexp_f32 v67, v67, v68
	v_log_f32_e32 v67, v67
	s_nop 0
	v_mul_f32_e32 v68, 0x3f317217, v67
	v_fma_f32 v68, v67, s94, -v68
	v_fmac_f32_e32 v68, 0x3377d1cf, v67
	v_fmac_f32_e32 v68, 0x3f317217, v67
	v_cmp_lt_f32_e64 s[16:17], |v67|, s95
	s_nop 1
	v_cndmask_b32_e64 v67, v67, v68, s[16:17]
	v_cndmask_b32_e32 v68, 0, v192, vcc
	v_sub_f32_e32 v67, v67, v68

; __device__ __forceinline__ float softplusf_(float x) { const float e = __expf(x); const float sm = e * (1.f - e * (0.5f - e * 0.33333334f)); return x > 20.f ? x : (e < 0.01f ? sm : __logf(1.f + e)); }
;     __device__ __forceinline__ void operator()(AccT acc, const Unit& u, int wr, int wc, int fr, int fq) const {
;     ...
;                     *(f32x4*)(d + 4) = (f32x4){softplusf_(v1[0] + bb[4]), softplusf_(v1[1] + bb[5]), softplusf_(v1[2] + bb[6]), softplusf_(v1[3] + bb[7])};
.LBB0_3035:
	s_or_b64 exec, exec, s[20:21]
	s_nop 1
	v_mov_b32_e32 v68, v250
	v_add_f32_e32 v68, v60, v68
	v_cmp_nlt_f32_e32 vcc, s90, v68
	s_and_saveexec_b64 s[20:21], vcc
	s_cbranch_execz .LBB0_3039
	v_mul_f32_e32 v68, 0x3fb8aa3b, v68
	v_exp_f32_e32 v69, v68
	s_nop 0
	v_fma_f32 v68, v69, s91, 0.5
	v_fma_f32 v68, -v69, v68, 1.0
	v_mul_f32_e32 v68, v69, v68
	v_cmp_ngt_f32_e32 vcc, s92, v69
	s_and_saveexec_b64 s[56:57], vcc
	s_cbranch_execz .LBB0_3038
	v_add_f32_e32 v68, 1.0, v69
	v_cmp_gt_f32_e32 vcc, s93, v68
	s_nop 1
	v_cndmask_b32_e64 v69, 0, 32, vcc
	v_ldexp_f32 v68, v68, v69
	v_log_f32_e32 v68, v68
	s_nop 0
	v_mul_f32_e32 v69, 0x3f317217, v68
	v_fma_f32 v69, v68, s94, -v69
	v_fmac_f32_e32 v69, 0x3377d1cf, v68
	v_fmac_f32_e32 v69, 0x3f317217, v68
	v_cmp_lt_f32_e64 s[16:17], |v68|, s95
	s_nop 1
	v_cndmask_b32_e64 v68, v68, v69, s[16:17]
	v_cndmask_b32_e32 v69, 0, v192, vcc
	v_sub_f32_e32 v68, v68, v69

; __device__ __forceinline__ float softplusf_(float x) { const float e = __expf(x); const float sm = e * (1.f - e * (0.5f - e * 0.33333334f)); return x > 20.f ? x : (e < 0.01f ? sm : __logf(1.f + e)); }
;     __device__ __forceinline__ void operator()(AccT acc, const Unit& u, int wr, int wc, int fr, int fq) const {
;     ...
;                     *(f32x4*)(d + 4) = (f32x4){softplusf_(v1[0] + bb[4]), softplusf_(v1[1] + bb[5]), softplusf_(v1[2] + bb[6]), softplusf_(v1[3] + bb[7])};
.LBB0_3039:
	s_or_b64 exec, exec, s[20:21]
	s_nop 1
	v_mov_b32_e32 v69, v251
	v_add_f32_e32 v69, v61, v69
	v_cmp_nlt_f32_e32 vcc, s90, v69
	s_and_saveexec_b64 s[20:21], vcc
	s_cbranch_execz .LBB0_3043
	v_mul_f32_e32 v69, 0x3fb8aa3b, v69
	v_exp_f32_e32 v71, v69
	s_nop 0
	v_fma_f32 v69, v71, s91, 0.5
	v_fma_f32 v69, -v71, v69, 1.0
	v_mul_f32_e32 v69, v71, v69
	v_cmp_ngt_f32_e32 vcc, s92, v71
	s_and_saveexec_b64 s[56:57], vcc
	s_cbranch_execz .LBB0_3042
	v_add_f32_e32 v69, 1.0, v71
	v_cmp_gt_f32_e32 vcc, s93, v69
	s_nop 1
	v_cndmask_b32_e64 v71, 0, 32, vcc
	v_ldexp_f32 v69, v69, v71
	v_log_f32_e32 v69, v69
	s_nop 0
	v_mul_f32_e32 v71, 0x3f317217, v69
	v_fma_f32 v71, v69, s94, -v71
	v_fmac_f32_e32 v71, 0x3377d1cf, v69
	v_fmac_f32_e32 v71, 0x3f317217, v69
	v_cmp_lt_f32_e64 s[16:17], |v69|, s95
	s_nop 1
	v_cndmask_b32_e64 v69, v69, v71, s[16:17]
	v_cndmask_b32_e32 v71, 0, v192, vcc
	v_sub_f32_e32 v69, v69, v71

; __device__ __forceinline__ float row_rs(const float* SSQ, int row, int fq) {
;     const f32x4 a = *(const f32x4*)(SSQ + (size_t)row * 16 + 4 * fq);
;     float t = (a.x + a.y) + (a.z + a.w);
;     t += __shfl_xor(t, 16); t += __shfl_xor(t, 32);
;     return __builtin_amdgcn_rsqf(t * (1.f / DM) + EPS);
; }
;     __device__ __forceinline__ void operator()(AccT acc, const Unit& u, int wr, int wc, int fr, int fq) const {
;     ...
;                 const f32x4 v0 = acc[ai][bj][m][0] * rs + sh[bj][0], v1 = acc[ai][bj][m][1] * rs + sh[bj][1];
;                 if (u.pn < 48) {
;                     u32x4 w; w.x = cvt_pk_bf16(v0[0], v0[1]); w.y = cvt_pk_bf16(v0[2], v0[3]); w.z = cvt_pk_bf16(v1[0], v1[1]); w.w = cvt_pk_bf16(v1[2], v1[3]);
;                     *(u32x4*)ZP(Z, row, c) = w;
;                     if (side) {
;                         float* dst = nullptr;
;                         if (side == 1) {
;                             const int kv = c >= ZV ? 1 : 0, cc = c - (kv ? ZV : ZK), g = cc >> 9, ci = cc & 511; const int keep = g == 0 ? 128 : (g == 1 ? 512 : 2048);
;                             if (isS) dst = out + (g == 0 ? O_SKV1 : (g == 1 ? O_SKV2 : O_SKV3)) + ((size_t)(l * 32 + (sq - 16)) * 8 + t) * 1024 + kv * 512 + ci;
;                             else if (t >= SEQ - keep) dst = out + (g == 0 ? O_PKV1 : (g == 1 ? O_PKV2 : O_PKV3)) + ((size_t)(l * 16 + sq) * keep + (t - (SEQ - keep))) * 1024 + kv * 512 + ci;
;                         } else {
;                             const int tl = isS ? 8 : SEQ;
;                             if (t >= tl - 3) { const int i3 = t - (tl - 3);
;                                 if (c < ZXC) dst = out + (isS ? O_SCB + ((size_t)(l * 32 + (sq - 16)) * 3 + i3) * 1536 : O_PCB + ((size_t)(l * 16 + sq) * 3 + i3) * 1536) + (c - ZXBC);
;                                 else dst = out + (isS ? O_SCC + ((size_t)(l * 32 + (sq - 16)) * 3 + i3) * 1024 : O_PCC + ((size_t)(l * 16 + sq) * 3 + i3) * 1024) + (c - ZXC); }
;                         }
;                         if (dst) { *(f32x4*)dst = v0; *(f32x4*)(dst + 4) = v1; }
;                     }
;                 } else if (bj == 0 && wc == 0 && fq < 2) {
;                     float* d = DT + (size_t)row * 16 + 8 * fq; const float* bb = dtb + 8 * fq;
.LBB0_3073:
	s_waitcnt lgkmcnt(1)
	v_add_f32_e32 v50, v212, v213
	v_fmamk_f32 v50, v50, 0x3a800000, v191
	v_rsq_f32_e32 v54, v50
	v_cmp_gt_i32_e64 s[12:13], s79, v56
	v_cmp_lt_i32_e64 s[14:15], s89, v56
	v_ashrrev_i32_e32 v57, 31, v56
	s_mov_b64 s[16:17], -1
	v_pk_fma_f32 v[48:49], v[48:49], v[54:55], v[40:41] op_sel_hi:[1,0,1]
	v_pk_fma_f32 v[46:47], v[46:47], v[54:55], v[38:39] op_sel_hi:[1,0,1]
	v_pk_fma_f32 v[44:45], v[44:45], v[54:55], v[36:37] op_sel_hi:[1,0,1]
	s_and_b64 vcc, exec, s[10:11]
	v_pk_fma_f32 v[42:43], v[42:43], v[54:55], v[34:35] op_sel_hi:[1,0,1]
	s_cbranch_vccnz .LBB0_3109
	s_and_saveexec_b64 s[18:19], s[38:39]
	s_cbranch_execz .LBB0_3108
	s_nop 1
	v_mov_b32_e32 v50, v244
	v_add_f32_e32 v50, v46, v50
	v_cmp_nlt_f32_e32 vcc, s90, v50
	s_and_saveexec_b64 s[20:21], vcc
	s_cbranch_execz .LBB0_3079
	v_mul_f32_e32 v50, 0x3fb8aa3b, v50
	v_exp_f32_e32 v51, v50
	s_nop 0
	v_fma_f32 v50, v51, s91, 0.5
	v_fma_f32 v50, -v51, v50, 1.0
	v_mul_f32_e32 v50, v51, v50
	v_cmp_ngt_f32_e32 vcc, s92, v51
	s_and_saveexec_b64 s[56:57], vcc
	s_cbranch_execz .LBB0_3078
	v_add_f32_e32 v50, 1.0, v51
	v_cmp_gt_f32_e32 vcc, s93, v50
	s_nop 1
	v_cndmask_b32_e64 v51, 0, 32, vcc
	v_ldexp_f32 v50, v50, v51
	v_log_f32_e32 v50, v50
	s_nop 0
	v_mul_f32_e32 v51, 0x3f317217, v50
	v_fma_f32 v51, v50, s94, -v51
	v_fmac_f32_e32 v51, 0x3377d1cf, v50
	v_fmac_f32_e32 v51, 0x3f317217, v50
	v_cmp_lt_f32_e64 s[16:17], |v50|, s95
	s_nop 1
	v_cndmask_b32_e64 v50, v50, v51, s[16:17]
	v_cndmask_b32_e32 v51, 0, v192, vcc
	v_sub_f32_e32 v50, v50, v51

; __device__ __forceinline__ float softplusf_(float x) { const float e = __expf(x); const float sm = e * (1.f - e * (0.5f - e * 0.33333334f)); return x > 20.f ? x : (e < 0.01f ? sm : __logf(1.f + e)); }
;     __device__ __forceinline__ void operator()(AccT acc, const Unit& u, int wr, int wc, int fr, int fq) const {
;     ...
;                     *(f32x4*)d = (f32x4){softplusf_(v0[0] + bb[0]), softplusf_(v0[1] + bb[1]), softplusf_(v0[2] + bb[2]), softplusf_(v0[3] + bb[3])};
.LBB0_3079:
	s_or_b64 exec, exec, s[20:21]
	s_nop 1
	v_mov_b32_e32 v51, v245
	v_add_f32_e32 v51, v47, v51
	v_cmp_nlt_f32_e32 vcc, s90, v51
	s_and_saveexec_b64 s[20:21], vcc
	s_cbranch_execz .LBB0_3083
	v_mul_f32_e32 v51, 0x3fb8aa3b, v51
	v_exp_f32_e32 v52, v51
	s_nop 0
	v_fma_f32 v51, v52, s91, 0.5
	v_fma_f32 v51, -v52, v51, 1.0
	v_mul_f32_e32 v51, v52, v51
	v_cmp_ngt_f32_e32 vcc, s92, v52
	s_and_saveexec_b64 s[56:57], vcc
	s_cbranch_execz .LBB0_3082
	v_add_f32_e32 v51, 1.0, v52
	v_cmp_gt_f32_e32 vcc, s93, v51
	s_nop 1
	v_cndmask_b32_e64 v52, 0, 32, vcc
	v_ldexp_f32 v51, v51, v52
	v_log_f32_e32 v51, v51
	s_nop 0
	v_mul_f32_e32 v52, 0x3f317217, v51
	v_fma_f32 v52, v51, s94, -v52
	v_fmac_f32_e32 v52, 0x3377d1cf, v51
	v_fmac_f32_e32 v52, 0x3f317217, v51
	v_cmp_lt_f32_e64 s[16:17], |v51|, s95
	s_nop 1
	v_cndmask_b32_e64 v51, v51, v52, s[16:17]
	v_cndmask_b32_e32 v52, 0, v192, vcc
	v_sub_f32_e32 v51, v51, v52

; __device__ __forceinline__ float softplusf_(float x) { const float e = __expf(x); const float sm = e * (1.f - e * (0.5f - e * 0.33333334f)); return x > 20.f ? x : (e < 0.01f ? sm : __logf(1.f + e)); }
;     __device__ __forceinline__ void operator()(AccT acc, const Unit& u, int wr, int wc, int fr, int fq) const {
;     ...
;                     *(f32x4*)d = (f32x4){softplusf_(v0[0] + bb[0]), softplusf_(v0[1] + bb[1]), softplusf_(v0[2] + bb[2]), softplusf_(v0[3] + bb[3])};
.LBB0_3083:
	s_or_b64 exec, exec, s[20:21]
	s_nop 1
	v_mov_b32_e32 v52, v246
	v_add_f32_e32 v52, v48, v52
	v_cmp_nlt_f32_e32 vcc, s90, v52
	s_and_saveexec_b64 s[20:21], vcc
	s_cbranch_execz .LBB0_3087
	v_mul_f32_e32 v52, 0x3fb8aa3b, v52
	v_exp_f32_e32 v53, v52
	s_nop 0
	v_fma_f32 v52, v53, s91, 0.5
	v_fma_f32 v52, -v53, v52, 1.0
	v_mul_f32_e32 v52, v53, v52
	v_cmp_ngt_f32_e32 vcc, s92, v53
	s_and_saveexec_b64 s[56:57], vcc
	s_cbranch_execz .LBB0_3086
	v_add_f32_e32 v52, 1.0, v53
	v_cmp_gt_f32_e32 vcc, s93, v52
	s_nop 1
	v_cndmask_b32_e64 v53, 0, 32, vcc
	v_ldexp_f32 v52, v52, v53
	v_log_f32_e32 v52, v52
	s_nop 0
	v_mul_f32_e32 v53, 0x3f317217, v52
	v_fma_f32 v53, v52, s94, -v53
	v_fmac_f32_e32 v53, 0x3377d1cf, v52
	v_fmac_f32_e32 v53, 0x3f317217, v52
	v_cmp_lt_f32_e64 s[16:17], |v52|, s95
	s_nop 1
	v_cndmask_b32_e64 v52, v52, v53, s[16:17]
	v_cndmask_b32_e32 v53, 0, v192, vcc
	v_sub_f32_e32 v52, v52, v53

; __device__ __forceinline__ float softplusf_(float x) { const float e = __expf(x); const float sm = e * (1.f - e * (0.5f - e * 0.33333334f)); return x > 20.f ? x : (e < 0.01f ? sm : __logf(1.f + e)); }
;     __device__ __forceinline__ void operator()(AccT acc, const Unit& u, int wr, int wc, int fr, int fq) const {
;     ...
;                     *(f32x4*)d = (f32x4){softplusf_(v0[0] + bb[0]), softplusf_(v0[1] + bb[1]), softplusf_(v0[2] + bb[2]), softplusf_(v0[3] + bb[3])};
.LBB0_3087:
	s_or_b64 exec, exec, s[20:21]
	s_nop 1
	v_mov_b32_e32 v53, v247
	v_add_f32_e32 v53, v49, v53
	v_cmp_nlt_f32_e32 vcc, s90, v53
	s_and_saveexec_b64 s[20:21], vcc
	s_cbranch_execz .LBB0_3091
	v_mul_f32_e32 v53, 0x3fb8aa3b, v53
	v_exp_f32_e32 v55, v53
	s_nop 0
	v_fma_f32 v53, v55, s91, 0.5
	v_fma_f32 v53, -v55, v53, 1.0
	v_mul_f32_e32 v53, v55, v53
	v_cmp_ngt_f32_e32 vcc, s92, v55
	s_and_saveexec_b64 s[56:57], vcc
	s_cbranch_execz .LBB0_3090
	v_add_f32_e32 v53, 1.0, v55
	v_cmp_gt_f32_e32 vcc, s93, v53
	s_nop 1
	v_cndmask_b32_e64 v55, 0, 32, vcc
	v_ldexp_f32 v53, v53, v55
	v_log_f32_e32 v53, v53
	s_nop 0
	v_mul_f32_e32 v55, 0x3f317217, v53
	v_fma_f32 v55, v53, s94, -v55
	v_fmac_f32_e32 v55, 0x3377d1cf, v53
	v_fmac_f32_e32 v55, 0x3f317217, v53
	v_cmp_lt_f32_e64 s[16:17], |v53|, s95
	s_nop 1
	v_cndmask_b32_e64 v53, v53, v55, s[16:17]
	v_cndmask_b32_e32 v55, 0, v192, vcc
	v_sub_f32_e32 v53, v53, v55

; __device__ __forceinline__ float softplusf_(float x) { const float e = __expf(x); const float sm = e * (1.f - e * (0.5f - e * 0.33333334f)); return x > 20.f ? x : (e < 0.01f ? sm : __logf(1.f + e)); }
;     __device__ __forceinline__ void operator()(AccT acc, const Unit& u, int wr, int wc, int fr, int fq) const {
;     ...
;                     *(f32x4*)d = (f32x4){softplusf_(v0[0] + bb[0]), softplusf_(v0[1] + bb[1]), softplusf_(v0[2] + bb[2]), softplusf_(v0[3] + bb[3])};
;                     *(f32x4*)(d + 4) = (f32x4){softplusf_(v1[0] + bb[4]), softplusf_(v1[1] + bb[5]), softplusf_(v1[2] + bb[6]), softplusf_(v1[3] + bb[7])};
.LBB0_3091:
	s_or_b64 exec, exec, s[20:21]
	v_lshlrev_b64 v[58:59], 6, v[56:57]
	v_lshl_add_u64 v[58:59], v[162:163], 0, v[58:59]
	global_store_dwordx4 v[58:59], v[50:53], off
	s_nop 1
	v_mov_b32_e32 v50, v248
	v_add_f32_e32 v50, v42, v50
	v_cmp_nlt_f32_e32 vcc, s90, v50
	s_and_saveexec_b64 s[20:21], vcc
	s_cbranch_execz .LBB0_3095
	v_mul_f32_e32 v50, 0x3fb8aa3b, v50
	v_exp_f32_e32 v51, v50
	s_nop 0
	v_fma_f32 v50, v51, s91, 0.5
	v_fma_f32 v50, -v51, v50, 1.0
	v_mul_f32_e32 v50, v51, v50
	v_cmp_ngt_f32_e32 vcc, s92, v51
	s_and_saveexec_b64 s[56:57], vcc
	s_cbranch_execz .LBB0_3094
	v_add_f32_e32 v50, 1.0, v51
	v_cmp_gt_f32_e32 vcc, s93, v50
	s_nop 1
	v_cndmask_b32_e64 v51, 0, 32, vcc
	v_ldexp_f32 v50, v50, v51
	v_log_f32_e32 v50, v50
	s_nop 0
	v_mul_f32_e32 v51, 0x3f317217, v50
	v_fma_f32 v51, v50, s94, -v51
	v_fmac_f32_e32 v51, 0x3377d1cf, v50
	v_fmac_f32_e32 v51, 0x3f317217, v50
	v_cmp_lt_f32_e64 s[16:17], |v50|, s95
	s_nop 1
	v_cndmask_b32_e64 v50, v50, v51, s[16:17]
	v_cndmask_b32_e32 v51, 0, v192, vcc
	v_sub_f32_e32 v50, v50, v51

; __device__ __forceinline__ float softplusf_(float x) { const float e = __expf(x); const float sm = e * (1.f - e * (0.5f - e * 0.33333334f)); return x > 20.f ? x : (e < 0.01f ? sm : __logf(1.f + e)); }
;     __device__ __forceinline__ void operator()(AccT acc, const Unit& u, int wr, int wc, int fr, int fq) const {
;     ...
;                     *(f32x4*)(d + 4) = (f32x4){softplusf_(v1[0] + bb[4]), softplusf_(v1[1] + bb[5]), softplusf_(v1[2] + bb[6]), softplusf_(v1[3] + bb[7])};
.LBB0_3095:
	s_or_b64 exec, exec, s[20:21]
	s_nop 1
	v_mov_b32_e32 v51, v249
	v_add_f32_e32 v51, v43, v51
	v_cmp_nlt_f32_e32 vcc, s90, v51
	s_and_saveexec_b64 s[20:21], vcc
	s_cbranch_execz .LBB0_3099
	v_mul_f32_e32 v51, 0x3fb8aa3b, v51
	v_exp_f32_e32 v52, v51
	s_nop 0
	v_fma_f32 v51, v52, s91, 0.5
	v_fma_f32 v51, -v52, v51, 1.0
	v_mul_f32_e32 v51, v52, v51
	v_cmp_ngt_f32_e32 vcc, s92, v52
	s_and_saveexec_b64 s[56:57], vcc
	s_cbranch_execz .LBB0_3098
	v_add_f32_e32 v51, 1.0, v52
	v_cmp_gt_f32_e32 vcc, s93, v51
	s_nop 1
	v_cndmask_b32_e64 v52, 0, 32, vcc
	v_ldexp_f32 v51, v51, v52
	v_log_f32_e32 v51, v51
	s_nop 0
	v_mul_f32_e32 v52, 0x3f317217, v51
	v_fma_f32 v52, v51, s94, -v52
	v_fmac_f32_e32 v52, 0x3377d1cf, v51
	v_fmac_f32_e32 v52, 0x3f317217, v51
	v_cmp_lt_f32_e64 s[16:17], |v51|, s95
	s_nop 1
	v_cndmask_b32_e64 v51, v51, v52, s[16:17]
	v_cndmask_b32_e32 v52, 0, v192, vcc
	v_sub_f32_e32 v51, v51, v52

; __device__ __forceinline__ float softplusf_(float x) { const float e = __expf(x); const float sm = e * (1.f - e * (0.5f - e * 0.33333334f)); return x > 20.f ? x : (e < 0.01f ? sm : __logf(1.f + e)); }
;     __device__ __forceinline__ void operator()(AccT acc, const Unit& u, int wr, int wc, int fr, int fq) const {
;     ...
;                     *(f32x4*)(d + 4) = (f32x4){softplusf_(v1[0] + bb[4]), softplusf_(v1[1] + bb[5]), softplusf_(v1[2] + bb[6]), softplusf_(v1[3] + bb[7])};
.LBB0_3099:
	s_or_b64 exec, exec, s[20:21]
	s_nop 1
	v_mov_b32_e32 v52, v250
	v_add_f32_e32 v52, v44, v52
	v_cmp_nlt_f32_e32 vcc, s90, v52
	s_and_saveexec_b64 s[20:21], vcc
	s_cbranch_execz .LBB0_3103
	v_mul_f32_e32 v52, 0x3fb8aa3b, v52
	v_exp_f32_e32 v53, v52
	s_nop 0
	v_fma_f32 v52, v53, s91, 0.5
	v_fma_f32 v52, -v53, v52, 1.0
	v_mul_f32_e32 v52, v53, v52
	v_cmp_ngt_f32_e32 vcc, s92, v53
	s_and_saveexec_b64 s[56:57], vcc
	s_cbranch_execz .LBB0_3102
	v_add_f32_e32 v52, 1.0, v53
	v_cmp_gt_f32_e32 vcc, s93, v52
	s_nop 1
	v_cndmask_b32_e64 v53, 0, 32, vcc
	v_ldexp_f32 v52, v52, v53
	v_log_f32_e32 v52, v52
	s_nop 0
	v_mul_f32_e32 v53, 0x3f317217, v52
	v_fma_f32 v53, v52, s94, -v53
	v_fmac_f32_e32 v53, 0x3377d1cf, v52
	v_fmac_f32_e32 v53, 0x3f317217, v52
	v_cmp_lt_f32_e64 s[16:17], |v52|, s95
	s_nop 1
	v_cndmask_b32_e64 v52, v52, v53, s[16:17]
	v_cndmask_b32_e32 v53, 0, v192, vcc
	v_sub_f32_e32 v52, v52, v53

; __device__ __forceinline__ float softplusf_(float x) { const float e = __expf(x); const float sm = e * (1.f - e * (0.5f - e * 0.33333334f)); return x > 20.f ? x : (e < 0.01f ? sm : __logf(1.f + e)); }
;     __device__ __forceinline__ void operator()(AccT acc, const Unit& u, int wr, int wc, int fr, int fq) const {
;     ...
;                     *(f32x4*)(d + 4) = (f32x4){softplusf_(v1[0] + bb[4]), softplusf_(v1[1] + bb[5]), softplusf_(v1[2] + bb[6]), softplusf_(v1[3] + bb[7])};
.LBB0_3103:
	s_or_b64 exec, exec, s[20:21]
	s_nop 1
	v_mov_b32_e32 v53, v251
	v_add_f32_e32 v53, v45, v53
	v_cmp_nlt_f32_e32 vcc, s90, v53
	s_and_saveexec_b64 s[20:21], vcc
	s_cbranch_execz .LBB0_3107
	v_mul_f32_e32 v53, 0x3fb8aa3b, v53
	v_exp_f32_e32 v55, v53
	s_nop 0
	v_fma_f32 v53, v55, s91, 0.5
	v_fma_f32 v53, -v55, v53, 1.0
	v_mul_f32_e32 v53, v55, v53
	v_cmp_ngt_f32_e32 vcc, s92, v55
	s_and_saveexec_b64 s[56:57], vcc
	s_cbranch_execz .LBB0_3106
	v_add_f32_e32 v53, 1.0, v55
	v_cmp_gt_f32_e32 vcc, s93, v53
	s_nop 1
	v_cndmask_b32_e64 v55, 0, 32, vcc
	v_ldexp_f32 v53, v53, v55
	v_log_f32_e32 v53, v53
	s_nop 0
	v_mul_f32_e32 v55, 0x3f317217, v53
	v_fma_f32 v55, v53, s94, -v55
	v_fmac_f32_e32 v55, 0x3377d1cf, v53
	v_fmac_f32_e32 v55, 0x3f317217, v53
	v_cmp_lt_f32_e64 s[16:17], |v53|, s95
	s_nop 1
	v_cndmask_b32_e64 v53, v53, v55, s[16:17]
	v_cndmask_b32_e32 v55, 0, v192, vcc
	v_sub_f32_e32 v53, v53, v55

; __device__ __forceinline__ float softplusf_(float x) { const float e = __expf(x); const float sm = e * (1.f - e * (0.5f - e * 0.33333334f)); return x > 20.f ? x : (e < 0.01f ? sm : __logf(1.f + e)); }
;     __device__ __forceinline__ void operator()(AccT acc, const Unit& u, int wr, int wc, int fr, int fq) const {
;     ...
;             const float rs = rs8[ai * 4 + m];
;             const int sq = seq_of_row(row); const bool isS = row >= NPROMPT; const int t = isS ? ((row - NPROMPT) & 7) : (row & (SEQ - 1));
;             if (!uni) { const float* sw = SHW + (size_t)sq * NZT + col0;
; #pragma unroll
;                 for (int bj = 0; bj < 2; ++bj) { sh[bj][0] = *(const f32x4*)(sw + bj * HALF); sh[bj][1] = *(const f32x4*)(sw + bj * HALF + 4); }
;                 asm volatile("" :: "v"(sh[0][0]), "v"(sh[0][1]), "v"(sh[1][0]), "v"(sh[1][1])); }
; #pragma unroll
;             for (int bj = 0; bj < 2; ++bj) { const int c = col0 + bj * HALF;
;                 const f32x4 v0 = acc[ai][bj][m][0] * rs + sh[bj][0], v1 = acc[ai][bj][m][1] * rs + sh[bj][1];
;     ...
;                 } else if (bj == 0 && wc == 0 && fq < 2) {
;                     float* d = DT + (size_t)row * 16 + 8 * fq; const float* bb = dtb + 8 * fq;
;                     *(f32x4*)d = (f32x4){softplusf_(v0[0] + bb[0]), softplusf_(v0[1] + bb[1]), softplusf_(v0[2] + bb[2]), softplusf_(v0[3] + bb[3])};
.LBB0_3137:
	s_waitcnt lgkmcnt(0)
	v_add_f32_e32 v26, v210, v211
	v_fmamk_f32 v26, v26, 0x3a800000, v191
	v_rsq_f32_e32 v30, v26
	v_cmp_gt_i32_e64 s[6:7], s79, v32
	v_cmp_lt_i32_e64 s[12:13], s89, v32
	v_ashrrev_i32_e32 v33, 31, v32
	s_mov_b64 s[14:15], -1
	v_pk_fma_f32 v[24:25], v[24:25], v[30:31], v[40:41] op_sel_hi:[1,0,1]
	v_pk_fma_f32 v[22:23], v[22:23], v[30:31], v[38:39] op_sel_hi:[1,0,1]
	v_pk_fma_f32 v[20:21], v[20:21], v[30:31], v[36:37] op_sel_hi:[1,0,1]
	s_and_b64 vcc, exec, s[10:11]
	v_pk_fma_f32 v[18:19], v[18:19], v[30:31], v[34:35] op_sel_hi:[1,0,1]
	s_cbranch_vccnz .LBB0_3173
	s_and_saveexec_b64 s[14:15], s[38:39]
	s_cbranch_execz .LBB0_3172
	s_nop 1
	v_mov_b32_e32 v26, v244
	v_add_f32_e32 v26, v22, v26
	v_cmp_nlt_f32_e32 vcc, s90, v26
	s_and_saveexec_b64 s[16:17], vcc
	s_cbranch_execz .LBB0_3143
	v_mul_f32_e32 v26, 0x3fb8aa3b, v26
	v_exp_f32_e32 v27, v26
	s_nop 0
	v_fma_f32 v26, v27, s91, 0.5
	v_fma_f32 v26, -v27, v26, 1.0
	v_mul_f32_e32 v26, v27, v26
	v_cmp_ngt_f32_e32 vcc, s92, v27
	s_and_saveexec_b64 s[18:19], vcc
	s_cbranch_execz .LBB0_3142
	v_add_f32_e32 v26, 1.0, v27
	v_cmp_gt_f32_e32 vcc, s93, v26
	s_nop 1
	v_cndmask_b32_e64 v27, 0, 32, vcc
	v_ldexp_f32 v26, v26, v27
	v_log_f32_e32 v26, v26
	s_nop 0
	v_mul_f32_e32 v27, 0x3f317217, v26
	v_fma_f32 v27, v26, s94, -v27
	v_fmac_f32_e32 v27, 0x3377d1cf, v26
	v_fmac_f32_e32 v27, 0x3f317217, v26
	v_cmp_lt_f32_e64 s[10:11], |v26|, s95
	s_nop 1
	v_cndmask_b32_e64 v26, v26, v27, s[10:11]
	v_cndmask_b32_e32 v27, 0, v192, vcc
	v_sub_f32_e32 v26, v26, v27

; __device__ __forceinline__ float softplusf_(float x) { const float e = __expf(x); const float sm = e * (1.f - e * (0.5f - e * 0.33333334f)); return x > 20.f ? x : (e < 0.01f ? sm : __logf(1.f + e)); }
;     __device__ __forceinline__ void operator()(AccT acc, const Unit& u, int wr, int wc, int fr, int fq) const {
;     ...
;                 } else if (bj == 0 && wc == 0 && fq < 2) {
;                     float* d = DT + (size_t)row * 16 + 8 * fq; const float* bb = dtb + 8 * fq;
;                     *(f32x4*)d = (f32x4){softplusf_(v0[0] + bb[0]), softplusf_(v0[1] + bb[1]), softplusf_(v0[2] + bb[2]), softplusf_(v0[3] + bb[3])};
.LBB0_3143:
	s_or_b64 exec, exec, s[16:17]
	s_nop 1
	v_mov_b32_e32 v27, v245
	v_add_f32_e32 v27, v23, v27
	v_cmp_nlt_f32_e32 vcc, s90, v27
	s_and_saveexec_b64 s[16:17], vcc
	s_cbranch_execz .LBB0_3147
	v_mul_f32_e32 v27, 0x3fb8aa3b, v27
	v_exp_f32_e32 v28, v27
	s_nop 0
	v_fma_f32 v27, v28, s91, 0.5
	v_fma_f32 v27, -v28, v27, 1.0
	v_mul_f32_e32 v27, v28, v27
	v_cmp_ngt_f32_e32 vcc, s92, v28
	s_and_saveexec_b64 s[18:19], vcc
	s_cbranch_execz .LBB0_3146
	v_add_f32_e32 v27, 1.0, v28
	v_cmp_gt_f32_e32 vcc, s93, v27
	s_nop 1
	v_cndmask_b32_e64 v28, 0, 32, vcc
	v_ldexp_f32 v27, v27, v28
	v_log_f32_e32 v27, v27
	s_nop 0
	v_mul_f32_e32 v28, 0x3f317217, v27
	v_fma_f32 v28, v27, s94, -v28
	v_fmac_f32_e32 v28, 0x3377d1cf, v27
	v_fmac_f32_e32 v28, 0x3f317217, v27
	v_cmp_lt_f32_e64 s[10:11], |v27|, s95
	s_nop 1
	v_cndmask_b32_e64 v27, v27, v28, s[10:11]
	v_cndmask_b32_e32 v28, 0, v192, vcc
	v_sub_f32_e32 v27, v27, v28

; __device__ __forceinline__ float softplusf_(float x) { const float e = __expf(x); const float sm = e * (1.f - e * (0.5f - e * 0.33333334f)); return x > 20.f ? x : (e < 0.01f ? sm : __logf(1.f + e)); }
;     __device__ __forceinline__ void operator()(AccT acc, const Unit& u, int wr, int wc, int fr, int fq) const {
;     ...
;                 } else if (bj == 0 && wc == 0 && fq < 2) {
;                     float* d = DT + (size_t)row * 16 + 8 * fq; const float* bb = dtb + 8 * fq;
;                     *(f32x4*)d = (f32x4){softplusf_(v0[0] + bb[0]), softplusf_(v0[1] + bb[1]), softplusf_(v0[2] + bb[2]), softplusf_(v0[3] + bb[3])};
.LBB0_3147:
	s_or_b64 exec, exec, s[16:17]
	s_nop 1
	v_mov_b32_e32 v28, v246
	v_add_f32_e32 v28, v24, v28
	v_cmp_nlt_f32_e32 vcc, s90, v28
	s_and_saveexec_b64 s[16:17], vcc
	s_cbranch_execz .LBB0_3151
	v_mul_f32_e32 v28, 0x3fb8aa3b, v28
	v_exp_f32_e32 v29, v28
	s_nop 0
	v_fma_f32 v28, v29, s91, 0.5
	v_fma_f32 v28, -v29, v28, 1.0
	v_mul_f32_e32 v28, v29, v28
	v_cmp_ngt_f32_e32 vcc, s92, v29
	s_and_saveexec_b64 s[18:19], vcc
	s_cbranch_execz .LBB0_3150
	v_add_f32_e32 v28, 1.0, v29
	v_cmp_gt_f32_e32 vcc, s93, v28
	s_nop 1
	v_cndmask_b32_e64 v29, 0, 32, vcc
	v_ldexp_f32 v28, v28, v29
	v_log_f32_e32 v28, v28
	s_nop 0
	v_mul_f32_e32 v29, 0x3f317217, v28
	v_fma_f32 v29, v28, s94, -v29
	v_fmac_f32_e32 v29, 0x3377d1cf, v28
	v_fmac_f32_e32 v29, 0x3f317217, v28
	v_cmp_lt_f32_e64 s[10:11], |v28|, s95
	s_nop 1
	v_cndmask_b32_e64 v28, v28, v29, s[10:11]
	v_cndmask_b32_e32 v29, 0, v192, vcc
	v_sub_f32_e32 v28, v28, v29

; __device__ __forceinline__ float softplusf_(float x) { const float e = __expf(x); const float sm = e * (1.f - e * (0.5f - e * 0.33333334f)); return x > 20.f ? x : (e < 0.01f ? sm : __logf(1.f + e)); }
;     __device__ __forceinline__ void operator()(AccT acc, const Unit& u, int wr, int wc, int fr, int fq) const {
;     ...
;                 } else if (bj == 0 && wc == 0 && fq < 2) {
;                     float* d = DT + (size_t)row * 16 + 8 * fq; const float* bb = dtb + 8 * fq;
;                     *(f32x4*)d = (f32x4){softplusf_(v0[0] + bb[0]), softplusf_(v0[1] + bb[1]), softplusf_(v0[2] + bb[2]), softplusf_(v0[3] + bb[3])};
.LBB0_3151:
	s_or_b64 exec, exec, s[16:17]
	s_nop 1
	v_mov_b32_e32 v29, v247
	v_add_f32_e32 v29, v25, v29
	v_cmp_nlt_f32_e32 vcc, s90, v29
	s_and_saveexec_b64 s[16:17], vcc
	s_cbranch_execz .LBB0_3155
	v_mul_f32_e32 v29, 0x3fb8aa3b, v29
	v_exp_f32_e32 v31, v29
	s_nop 0
	v_fma_f32 v29, v31, s91, 0.5
	v_fma_f32 v29, -v31, v29, 1.0
	v_mul_f32_e32 v29, v31, v29
	v_cmp_ngt_f32_e32 vcc, s92, v31
	s_and_saveexec_b64 s[18:19], vcc
	s_cbranch_execz .LBB0_3154
	v_add_f32_e32 v29, 1.0, v31
	v_cmp_gt_f32_e32 vcc, s93, v29
	s_nop 1
	v_cndmask_b32_e64 v31, 0, 32, vcc
	v_ldexp_f32 v29, v29, v31
	v_log_f32_e32 v29, v29
	s_nop 0
	v_mul_f32_e32 v31, 0x3f317217, v29
	v_fma_f32 v31, v29, s94, -v31
	v_fmac_f32_e32 v31, 0x3377d1cf, v29
	v_fmac_f32_e32 v31, 0x3f317217, v29
	v_cmp_lt_f32_e64 s[10:11], |v29|, s95
	s_nop 1
	v_cndmask_b32_e64 v29, v29, v31, s[10:11]
	v_cndmask_b32_e32 v31, 0, v192, vcc
	v_sub_f32_e32 v29, v29, v31

; __device__ __forceinline__ float softplusf_(float x) { const float e = __expf(x); const float sm = e * (1.f - e * (0.5f - e * 0.33333334f)); return x > 20.f ? x : (e < 0.01f ? sm : __logf(1.f + e)); }
;     __device__ __forceinline__ void operator()(AccT acc, const Unit& u, int wr, int wc, int fr, int fq) const {
;     ...
;                     *(f32x4*)d = (f32x4){softplusf_(v0[0] + bb[0]), softplusf_(v0[1] + bb[1]), softplusf_(v0[2] + bb[2]), softplusf_(v0[3] + bb[3])};
;                     *(f32x4*)(d + 4) = (f32x4){softplusf_(v1[0] + bb[4]), softplusf_(v1[1] + bb[5]), softplusf_(v1[2] + bb[6]), softplusf_(v1[3] + bb[7])};
.LBB0_3155:
	s_or_b64 exec, exec, s[16:17]
	v_lshlrev_b64 v[34:35], 6, v[32:33]
	v_lshl_add_u64 v[34:35], v[162:163], 0, v[34:35]
	global_store_dwordx4 v[34:35], v[26:29], off
	s_nop 1
	v_mov_b32_e32 v26, v248
	v_add_f32_e32 v26, v18, v26
	v_cmp_nlt_f32_e32 vcc, s90, v26
	s_and_saveexec_b64 s[16:17], vcc
	s_cbranch_execz .LBB0_3159
	v_mul_f32_e32 v26, 0x3fb8aa3b, v26
	v_exp_f32_e32 v27, v26
	s_nop 0
	v_fma_f32 v26, v27, s91, 0.5
	v_fma_f32 v26, -v27, v26, 1.0
	v_mul_f32_e32 v26, v27, v26
	v_cmp_ngt_f32_e32 vcc, s92, v27
	s_and_saveexec_b64 s[18:19], vcc
	s_cbranch_execz .LBB0_3158
	v_add_f32_e32 v26, 1.0, v27
	v_cmp_gt_f32_e32 vcc, s93, v26
	s_nop 1
	v_cndmask_b32_e64 v27, 0, 32, vcc
	v_ldexp_f32 v26, v26, v27
	v_log_f32_e32 v26, v26
	s_nop 0
	v_mul_f32_e32 v27, 0x3f317217, v26
	v_fma_f32 v27, v26, s94, -v27
	v_fmac_f32_e32 v27, 0x3377d1cf, v26
	v_fmac_f32_e32 v27, 0x3f317217, v26
	v_cmp_lt_f32_e64 s[10:11], |v26|, s95
	s_nop 1
	v_cndmask_b32_e64 v26, v26, v27, s[10:11]
	v_cndmask_b32_e32 v27, 0, v192, vcc
	v_sub_f32_e32 v26, v26, v27

; __device__ __forceinline__ float softplusf_(float x) { const float e = __expf(x); const float sm = e * (1.f - e * (0.5f - e * 0.33333334f)); return x > 20.f ? x : (e < 0.01f ? sm : __logf(1.f + e)); }
;     __device__ __forceinline__ void operator()(AccT acc, const Unit& u, int wr, int wc, int fr, int fq) const {
;     ...
;                     *(f32x4*)(d + 4) = (f32x4){softplusf_(v1[0] + bb[4]), softplusf_(v1[1] + bb[5]), softplusf_(v1[2] + bb[6]), softplusf_(v1[3] + bb[7])};
.LBB0_3159:
	s_or_b64 exec, exec, s[16:17]
	s_nop 1
	v_mov_b32_e32 v27, v249
	v_add_f32_e32 v27, v19, v27
	v_cmp_nlt_f32_e32 vcc, s90, v27
	s_and_saveexec_b64 s[16:17], vcc
	s_cbranch_execz .LBB0_3163
	v_mul_f32_e32 v27, 0x3fb8aa3b, v27
	v_exp_f32_e32 v28, v27
	s_nop 0
	v_fma_f32 v27, v28, s91, 0.5
	v_fma_f32 v27, -v28, v27, 1.0
	v_mul_f32_e32 v27, v28, v27
	v_cmp_ngt_f32_e32 vcc, s92, v28
	s_and_saveexec_b64 s[18:19], vcc
	s_cbranch_execz .LBB0_3162
	v_add_f32_e32 v27, 1.0, v28
	v_cmp_gt_f32_e32 vcc, s93, v27
	s_nop 1
	v_cndmask_b32_e64 v28, 0, 32, vcc
	v_ldexp_f32 v27, v27, v28
	v_log_f32_e32 v27, v27
	s_nop 0
	v_mul_f32_e32 v28, 0x3f317217, v27
	v_fma_f32 v28, v27, s94, -v28
	v_fmac_f32_e32 v28, 0x3377d1cf, v27
	v_fmac_f32_e32 v28, 0x3f317217, v27
	v_cmp_lt_f32_e64 s[10:11], |v27|, s95
	s_nop 1
	v_cndmask_b32_e64 v27, v27, v28, s[10:11]
	v_cndmask_b32_e32 v28, 0, v192, vcc
	v_sub_f32_e32 v27, v27, v28

; __device__ __forceinline__ float softplusf_(float x) { const float e = __expf(x); const float sm = e * (1.f - e * (0.5f - e * 0.33333334f)); return x > 20.f ? x : (e < 0.01f ? sm : __logf(1.f + e)); }
;     __device__ __forceinline__ void operator()(AccT acc, const Unit& u, int wr, int wc, int fr, int fq) const {
;     ...
;                     *(f32x4*)(d + 4) = (f32x4){softplusf_(v1[0] + bb[4]), softplusf_(v1[1] + bb[5]), softplusf_(v1[2] + bb[6]), softplusf_(v1[3] + bb[7])};
.LBB0_3163:
	s_or_b64 exec, exec, s[16:17]
	s_nop 1
	v_mov_b32_e32 v28, v250
	v_add_f32_e32 v28, v20, v28
	v_cmp_nlt_f32_e32 vcc, s90, v28
	s_and_saveexec_b64 s[16:17], vcc
	s_cbranch_execz .LBB0_3167
	v_mul_f32_e32 v28, 0x3fb8aa3b, v28
	v_exp_f32_e32 v29, v28
	s_nop 0
	v_fma_f32 v28, v29, s91, 0.5
	v_fma_f32 v28, -v29, v28, 1.0
	v_mul_f32_e32 v28, v29, v28
	v_cmp_ngt_f32_e32 vcc, s92, v29
	s_and_saveexec_b64 s[18:19], vcc
	s_cbranch_execz .LBB0_3166
	v_add_f32_e32 v28, 1.0, v29
	v_cmp_gt_f32_e32 vcc, s93, v28
	s_nop 1
	v_cndmask_b32_e64 v29, 0, 32, vcc
	v_ldexp_f32 v28, v28, v29
	v_log_f32_e32 v28, v28
	s_nop 0
	v_mul_f32_e32 v29, 0x3f317217, v28
	v_fma_f32 v29, v28, s94, -v29
	v_fmac_f32_e32 v29, 0x3377d1cf, v28
	v_fmac_f32_e32 v29, 0x3f317217, v28
	v_cmp_lt_f32_e64 s[10:11], |v28|, s95
	s_nop 1
	v_cndmask_b32_e64 v28, v28, v29, s[10:11]
	v_cndmask_b32_e32 v29, 0, v192, vcc
	v_sub_f32_e32 v28, v28, v29

; __device__ __forceinline__ float softplusf_(float x) { const float e = __expf(x); const float sm = e * (1.f - e * (0.5f - e * 0.33333334f)); return x > 20.f ? x : (e < 0.01f ? sm : __logf(1.f + e)); }
;     __device__ __forceinline__ void operator()(AccT acc, const Unit& u, int wr, int wc, int fr, int fq) const {
;     ...
;                     *(f32x4*)(d + 4) = (f32x4){softplusf_(v1[0] + bb[4]), softplusf_(v1[1] + bb[5]), softplusf_(v1[2] + bb[6]), softplusf_(v1[3] + bb[7])};
.LBB0_3167:
	s_or_b64 exec, exec, s[16:17]
	s_nop 1
	v_mov_b32_e32 v29, v251
	v_add_f32_e32 v29, v21, v29
	v_cmp_nlt_f32_e32 vcc, s90, v29
	s_and_saveexec_b64 s[16:17], vcc
	s_cbranch_execz .LBB0_3171
	v_mul_f32_e32 v29, 0x3fb8aa3b, v29
	v_exp_f32_e32 v31, v29
	s_nop 0
	v_fma_f32 v29, v31, s91, 0.5
	v_fma_f32 v29, -v31, v29, 1.0
	v_mul_f32_e32 v29, v31, v29
	v_cmp_ngt_f32_e32 vcc, s92, v31
	s_and_saveexec_b64 s[18:19], vcc
	s_cbranch_execz .LBB0_3170
	v_add_f32_e32 v29, 1.0, v31
	v_cmp_gt_f32_e32 vcc, s93, v29
	s_nop 1
	v_cndmask_b32_e64 v31, 0, 32, vcc
	v_ldexp_f32 v29, v29, v31
	v_log_f32_e32 v29, v29
	s_nop 0
	v_mul_f32_e32 v31, 0x3f317217, v29
	v_fma_f32 v31, v29, s94, -v31
	v_fmac_f32_e32 v31, 0x3377d1cf, v29
	v_fmac_f32_e32 v31, 0x3f317217, v29
	v_cmp_lt_f32_e64 s[10:11], |v29|, s95
	s_nop 1
	v_cndmask_b32_e64 v29, v29, v31, s[10:11]
	v_cndmask_b32_e32 v31, 0, v192, vcc
	v_sub_f32_e32 v29, v29, v31
